# v75 with the M0-write to LDS-DMA wait state restored at 12 sites (address computation placed between the M0 write and its load); otherwise identical
# speedup vs baseline: 1.0024x; 1.0024x over previous
; #define PG8_STAGE(bufoff, gbase, voff) do { _Pragma("unroll") for (int _i = 0; _i < 2; ++_i) \
;         __builtin_amdgcn_global_load_lds((const unsigned*)((const char*)(gbase) + (voff)[_i]), (LAS unsigned*)(lds + (bufoff) + ldsw + _i * 8192), 16, 0, 0); } while (0)
; #define PG8_LDA(dst, b, h) do { _Pragma("unroll") for (int m = 0; m < 4; ++m) _Pragma("unroll") for (int k = 0; k < 2; ++k) dst[m][k] = *(const LAS bf16x8*)(lds + PG8_SA(b, h) + aoff + m * 2048 + k * 1024); } while (0)
; #define PG8_LDB(dst, b, h) do { _Pragma("unroll") for (int n = 0; n < 2; ++n) _Pragma("unroll") for (int k = 0; k < 2; ++k) dst[n][k] = *(const LAS bf16x8*)(lds + PG8_SB(b, h) + boff + n * 2048 + k * 1024); } while (0)
; #define PG8_MMA(ai, bj, At, Bt) do { __builtin_amdgcn_s_setprio(1); _Pragma("unroll") for (int m = 0; m < 4; ++m) _Pragma("unroll") for (int n = 0; n < 2; ++n) _Pragma("unroll") for (int k = 0; k < 2; ++k) \
;         acc[ai][bj][m][n] = __builtin_amdgcn_mfma_f32_16x16x32_bf16(Bt[n][k], At[m][k], acc[ai][bj][m][n], 0, 0, 0); __builtin_amdgcn_s_setprio(0); } while (0)
; #define PG8_WAIT_V(n) asm volatile("s_waitcnt vmcnt(" #n ")" ::: "memory")
; #define PG8_WAIT_L(n) asm volatile("s_waitcnt lgkmcnt(" #n ")" ::: "memory")
; #define PG8_BAR __builtin_amdgcn_s_barrier()
; #define PG8_SCHED __builtin_amdgcn_sched_barrier(0)
; template <class Epi, bool ALIGN_EPI = PG8_ALIGN, bool SP2 = PG8_SP2>
; __device__ __forceinline__ void gemm_phase(LAS uchar* lds, const Gemm g, const StaticOrder& S, const Epi& E) {
;     ...
;             PG8_LDB(B0, 0, 0); PG8_LDB(B1, 0, 1); PG8_SCHED; PG8_LDA(At, 0, 0); PG8_STAGE(PG8_SA(1, 1), a1 + hstepA, voffA);
;             PG8_WAIT_V(8); PG8_WAIT_L(0); PG8_BAR; PG8_MMA(0, 0, At, B0); PG8_MMA(0, 1, At, B1); PG8_BAR; PG8_SCHED;
;             PG8_LDA(At, 0, 1); PG8_STAGE(PG8_SB(0, 0), b2, voffB); PG8_STAGE(PG8_SB(0, 1), b2 + hstepB, voffB); PG8_STAGE(PG8_SA(0, 0), a2, voffA);
;             PG8_WAIT_V(8); PG8_WAIT_L(0); PG8_BAR; PG8_MMA(1, 0, At, B0); PG8_MMA(1, 1, At, B1); PG8_BAR; PG8_SCHED;
.LBB0_345:
	s_add_u32 s18, s16, 0x100
	s_addc_u32 s19, s17, 0
	s_add_i32 s41, 0, 0x10000
	s_cmp_eq_u32 s40, 12
	s_cselect_b32 s21, s7, s19
	s_cselect_b32 s20, s6, s18
	v_add_u32_e32 v168, s41, v139
	s_cselect_b32 s5, s15, s39
	s_cselect_b32 s4, s14, s38
	s_add_i32 s42, 0, 0x14000
	ds_read_b128 v[164:167], v168
	ds_read_b128 v[172:175], v168 offset:1024
	ds_read_b128 v[176:179], v168 offset:2048
	ds_read_b128 v[184:187], v168 offset:3072
	v_add_u32_e32 v168, s42, v139
	ds_read_b128 v[188:191], v168
	ds_read_b128 v[192:195], v168 offset:1024
	ds_read_b128 v[196:199], v168 offset:2048
	ds_read_b128 v[200:203], v168 offset:3072
	v_lshl_add_u64 v[168:169], s[16:17], 0, v[160:161]
	s_add_i32 m0, s25, 0xc000
	ds_read_b128 v[204:207], v171
	ds_read_b128 v[208:211], v171 offset:1024
	ds_read_b128 v[212:215], v171 offset:2048
	ds_read_b128 v[216:219], v171 offset:3072
	ds_read_b128 v[220:223], v171 offset:4096
	ds_read_b128 v[224:227], v171 offset:5120
	ds_read_b128 v[228:231], v171 offset:6144
	ds_read_b128 v[232:235], v171 offset:7168
	global_load_lds_dwordx4 v[168:169], off
	s_add_i32 m0, s25, 0xe000
	v_lshl_add_u64 v[168:169], s[16:17], 0, v[162:163]
	global_load_lds_dwordx4 v[168:169], off
	s_waitcnt vmcnt(8)
	s_waitcnt lgkmcnt(0)
	s_setprio 1
	s_barrier
	v_mfma_f32_16x16x32_bf16 v[126:129], v[164:167], v[204:207], v[126:129]
	v_mfma_f32_16x16x32_bf16 v[122:125], v[176:179], v[204:207], v[122:125]
	v_mfma_f32_16x16x32_bf16 v[118:121], v[164:167], v[212:215], v[118:121]
	v_mfma_f32_16x16x32_bf16 v[110:113], v[176:179], v[212:215], v[110:113]
	v_mfma_f32_16x16x32_bf16 v[102:105], v[164:167], v[220:223], v[102:105]
	v_mfma_f32_16x16x32_bf16 v[94:97], v[176:179], v[220:223], v[94:97]
	v_mfma_f32_16x16x32_bf16 v[86:89], v[164:167], v[228:231], v[86:89]
	v_mfma_f32_16x16x32_bf16 v[78:81], v[176:179], v[228:231], v[78:81]
	v_mfma_f32_16x16x32_bf16 v[126:129], v[172:175], v[208:211], v[126:129]
	v_mfma_f32_16x16x32_bf16 v[122:125], v[184:187], v[208:211], v[122:125]
	v_mfma_f32_16x16x32_bf16 v[118:121], v[172:175], v[216:219], v[118:121]
	v_mfma_f32_16x16x32_bf16 v[110:113], v[184:187], v[216:219], v[110:113]
	v_mfma_f32_16x16x32_bf16 v[102:105], v[172:175], v[224:227], v[102:105]
	v_mfma_f32_16x16x32_bf16 v[94:97], v[184:187], v[224:227], v[94:97]
	v_mfma_f32_16x16x32_bf16 v[86:89], v[172:175], v[232:235], v[86:89]
	v_mfma_f32_16x16x32_bf16 v[78:81], v[184:187], v[232:235], v[78:81]
	v_mfma_f32_16x16x32_bf16 v[114:117], v[188:191], v[204:207], v[114:117]
	v_mfma_f32_16x16x32_bf16 v[106:109], v[196:199], v[204:207], v[106:109]
	v_mfma_f32_16x16x32_bf16 v[98:101], v[188:191], v[212:215], v[98:101]
	v_mfma_f32_16x16x32_bf16 v[90:93], v[196:199], v[212:215], v[90:93]
	v_mfma_f32_16x16x32_bf16 v[82:85], v[188:191], v[220:223], v[82:85]
	v_mfma_f32_16x16x32_bf16 v[74:77], v[196:199], v[220:223], v[74:77]
	v_mfma_f32_16x16x32_bf16 v[70:73], v[188:191], v[228:231], v[70:73]
	v_mfma_f32_16x16x32_bf16 v[66:69], v[196:199], v[228:231], v[66:69]
	v_mfma_f32_16x16x32_bf16 v[114:117], v[192:195], v[208:211], v[114:117]
	v_mfma_f32_16x16x32_bf16 v[106:109], v[200:203], v[208:211], v[106:109]
	v_mfma_f32_16x16x32_bf16 v[98:101], v[192:195], v[216:219], v[98:101]
	v_mfma_f32_16x16x32_bf16 v[90:93], v[200:203], v[216:219], v[90:93]
	v_mfma_f32_16x16x32_bf16 v[82:85], v[192:195], v[224:227], v[82:85]
	v_mfma_f32_16x16x32_bf16 v[74:77], v[200:203], v[224:227], v[74:77]
	v_mfma_f32_16x16x32_bf16 v[70:73], v[192:195], v[232:235], v[70:73]
	v_mfma_f32_16x16x32_bf16 v[66:69], v[200:203], v[232:235], v[66:69]
	s_barrier
	s_setprio 0
	s_add_i32 s16, s41, s23
	v_lshl_add_u64 v[168:169], s[4:5], 0, v[134:135]
	s_mov_b32 m0, s16
	ds_read_b128 v[204:207], v171 offset:16384
	ds_read_b128 v[208:211], v171 offset:17408
	ds_read_b128 v[212:215], v171 offset:18432
	ds_read_b128 v[216:219], v171 offset:19456
	ds_read_b128 v[220:223], v171 offset:20480
	ds_read_b128 v[224:227], v171 offset:21504
	ds_read_b128 v[228:231], v171 offset:22528
	ds_read_b128 v[232:235], v171 offset:23552
	global_load_lds_dwordx4 v[168:169], off
	s_add_i32 m0, s16, 0x2000
	s_add_u32 s16, s4, 0x44000
	v_lshl_add_u64 v[180:181], s[4:5], 0, v[130:131]
	s_addc_u32 s17, s5, 0
	s_add_i32 s41, s42, s23
	global_load_lds_dwordx4 v[180:181], off
	s_mov_b32 m0, s41
	v_lshl_add_u64 v[236:237], s[16:17], 0, v[134:135]
	global_load_lds_dwordx4 v[236:237], off
	s_add_i32 m0, s41, 0x2000
	v_lshl_add_u64 v[236:237], s[16:17], 0, v[130:131]
	global_load_lds_dwordx4 v[236:237], off
	s_mov_b32 m0, s25
	v_lshl_add_u64 v[236:237], s[20:21], 0, v[156:157]
	global_load_lds_dwordx4 v[236:237], off
	s_mov_b32 m0, s26
	v_lshl_add_u64 v[238:239], s[20:21], 0, v[132:133]
	global_load_lds_dwordx4 v[238:239], off
	s_waitcnt vmcnt(8)
	s_waitcnt lgkmcnt(0)
	s_setprio 1
	s_barrier
; #define PG8_STAGE(bufoff, gbase, voff) do { _Pragma("unroll") for (int _i = 0; _i < 2; ++_i) \
;         __builtin_amdgcn_global_load_lds((const unsigned*)((const char*)(gbase) + (voff)[_i]), (LAS unsigned*)(lds + (bufoff) + ldsw + _i * 8192), 16, 0, 0); } while (0)
; #define PG8_LDA(dst, b, h) do { _Pragma("unroll") for (int m = 0; m < 4; ++m) _Pragma("unroll") for (int k = 0; k < 2; ++k) dst[m][k] = *(const LAS bf16x8*)(lds + PG8_SA(b, h) + aoff + m * 2048 + k * 1024); } while (0)
; #define PG8_LDB(dst, b, h) do { _Pragma("unroll") for (int n = 0; n < 2; ++n) _Pragma("unroll") for (int k = 0; k < 2; ++k) dst[n][k] = *(const LAS bf16x8*)(lds + PG8_SB(b, h) + boff + n * 2048 + k * 1024); } while (0)
; #define PG8_MMA(ai, bj, At, Bt) do { __builtin_amdgcn_s_setprio(1); _Pragma("unroll") for (int m = 0; m < 4; ++m) _Pragma("unroll") for (int n = 0; n < 2; ++n) _Pragma("unroll") for (int k = 0; k < 2; ++k) \
;         acc[ai][bj][m][n] = __builtin_amdgcn_mfma_f32_16x16x32_bf16(Bt[n][k], At[m][k], acc[ai][bj][m][n], 0, 0, 0); __builtin_amdgcn_s_setprio(0); } while (0)
; #define PG8_WAIT_V(n) asm volatile("s_waitcnt vmcnt(" #n ")" ::: "memory")
; #define PG8_WAIT_L(n) asm volatile("s_waitcnt lgkmcnt(" #n ")" ::: "memory")
; #define PG8_BAR __builtin_amdgcn_s_barrier()
; #define PG8_SCHED __builtin_amdgcn_sched_barrier(0)
; template <class Epi, bool ALIGN_EPI = PG8_ALIGN, bool SP2 = PG8_SP2>
; __device__ __forceinline__ void gemm_phase(LAS uchar* lds, const Gemm g, const StaticOrder& S, const Epi& E) {
;     ...
;             PG8_WAIT_V(8); PG8_WAIT_L(0); PG8_BAR; PG8_MMA(1, 0, At, B0); PG8_MMA(1, 1, At, B1); PG8_BAR; PG8_SCHED;
;             PG8_LDB(B0, 1, 0); PG8_LDB(B1, 1, 1); PG8_SCHED; PG8_LDA(At, 1, 0); PG8_STAGE(PG8_SA(0, 1), a2 + hstepA, voffA);
;             PG8_WAIT_V(8); PG8_WAIT_L(0); PG8_BAR; PG8_MMA(0, 0, At, B0); PG8_MMA(0, 1, At, B1); PG8_BAR; PG8_SCHED;
	v_mfma_f32_16x16x32_bf16 v[62:65], v[164:167], v[204:207], v[62:65]
	v_mfma_f32_16x16x32_bf16 v[58:61], v[176:179], v[204:207], v[58:61]
	v_mfma_f32_16x16x32_bf16 v[54:57], v[164:167], v[212:215], v[54:57]
	v_mfma_f32_16x16x32_bf16 v[46:49], v[176:179], v[212:215], v[46:49]
	v_mfma_f32_16x16x32_bf16 v[38:41], v[164:167], v[220:223], v[38:41]
	v_mfma_f32_16x16x32_bf16 v[30:33], v[176:179], v[220:223], v[30:33]
	v_mfma_f32_16x16x32_bf16 v[22:25], v[164:167], v[228:231], v[22:25]
	v_mfma_f32_16x16x32_bf16 v[14:17], v[176:179], v[228:231], v[14:17]
	v_mfma_f32_16x16x32_bf16 v[62:65], v[172:175], v[208:211], v[62:65]
	v_mfma_f32_16x16x32_bf16 v[58:61], v[184:187], v[208:211], v[58:61]
	v_mfma_f32_16x16x32_bf16 v[54:57], v[172:175], v[216:219], v[54:57]
	v_mfma_f32_16x16x32_bf16 v[46:49], v[184:187], v[216:219], v[46:49]
	v_mfma_f32_16x16x32_bf16 v[38:41], v[172:175], v[224:227], v[38:41]
	v_mfma_f32_16x16x32_bf16 v[30:33], v[184:187], v[224:227], v[30:33]
	v_mfma_f32_16x16x32_bf16 v[22:25], v[172:175], v[232:235], v[22:25]
	v_mfma_f32_16x16x32_bf16 v[14:17], v[184:187], v[232:235], v[14:17]
	v_mfma_f32_16x16x32_bf16 v[50:53], v[188:191], v[204:207], v[50:53]
	v_mfma_f32_16x16x32_bf16 v[42:45], v[196:199], v[204:207], v[42:45]
	v_mfma_f32_16x16x32_bf16 v[34:37], v[188:191], v[212:215], v[34:37]
	v_mfma_f32_16x16x32_bf16 v[26:29], v[196:199], v[212:215], v[26:29]
	v_mfma_f32_16x16x32_bf16 v[18:21], v[188:191], v[220:223], v[18:21]
	v_mfma_f32_16x16x32_bf16 v[10:13], v[196:199], v[220:223], v[10:13]
	v_mfma_f32_16x16x32_bf16 v[6:9], v[188:191], v[228:231], v[6:9]
	v_mfma_f32_16x16x32_bf16 v[2:5], v[196:199], v[228:231], v[2:5]
	v_mfma_f32_16x16x32_bf16 v[50:53], v[192:195], v[208:211], v[50:53]
	v_mfma_f32_16x16x32_bf16 v[42:45], v[200:203], v[208:211], v[42:45]
	v_mfma_f32_16x16x32_bf16 v[34:37], v[192:195], v[216:219], v[34:37]
	v_mfma_f32_16x16x32_bf16 v[26:29], v[200:203], v[216:219], v[26:29]
	v_mfma_f32_16x16x32_bf16 v[18:21], v[192:195], v[224:227], v[18:21]
	v_mfma_f32_16x16x32_bf16 v[10:13], v[200:203], v[224:227], v[10:13]
	v_mfma_f32_16x16x32_bf16 v[6:9], v[192:195], v[232:235], v[6:9]
	v_mfma_f32_16x16x32_bf16 v[2:5], v[200:203], v[232:235], v[2:5]
	s_barrier
	s_setprio 0
	s_add_i32 s41, 0, 0x18000
	s_add_i32 s42, 0, 0x1c000
	v_add_u32_e32 v184, s41, v139
	v_add_u32_e32 v200, s42, v139
	ds_read_b128 v[164:167], v184
	ds_read_b128 v[172:175], v184 offset:1024
	ds_read_b128 v[176:179], v184 offset:2048
	ds_read_b128 v[184:187], v184 offset:3072
	ds_read_b128 v[188:191], v200
	ds_read_b128 v[192:195], v200 offset:1024
	ds_read_b128 v[196:199], v200 offset:2048
	ds_read_b128 v[200:203], v200 offset:3072
	s_add_u32 s16, s20, 0x44000
	s_addc_u32 s17, s21, 0
	s_mov_b32 m0, s27
	v_lshl_add_u64 v[240:241], s[16:17], 0, v[156:157]
	ds_read_b128 v[204:207], v171 offset:32768
	ds_read_b128 v[208:211], v171 offset:33792
	ds_read_b128 v[212:215], v171 offset:34816
	ds_read_b128 v[216:219], v171 offset:35840
	ds_read_b128 v[220:223], v171 offset:36864
	ds_read_b128 v[224:227], v171 offset:37888
	ds_read_b128 v[228:231], v171 offset:38912
	ds_read_b128 v[232:235], v171 offset:39936
	global_load_lds_dwordx4 v[240:241], off
	s_mov_b32 m0, s28
	v_lshl_add_u64 v[240:241], s[16:17], 0, v[132:133]
	global_load_lds_dwordx4 v[240:241], off
	s_waitcnt vmcnt(8)
	s_waitcnt lgkmcnt(0)
	s_setprio 1
	s_barrier
	v_mfma_f32_16x16x32_bf16 v[126:129], v[164:167], v[204:207], v[126:129]
	v_mfma_f32_16x16x32_bf16 v[122:125], v[176:179], v[204:207], v[122:125]
	v_mfma_f32_16x16x32_bf16 v[118:121], v[164:167], v[212:215], v[118:121]
	v_mfma_f32_16x16x32_bf16 v[110:113], v[176:179], v[212:215], v[110:113]
	v_mfma_f32_16x16x32_bf16 v[102:105], v[164:167], v[220:223], v[102:105]
	v_mfma_f32_16x16x32_bf16 v[94:97], v[176:179], v[220:223], v[94:97]
	v_mfma_f32_16x16x32_bf16 v[86:89], v[164:167], v[228:231], v[86:89]
	v_mfma_f32_16x16x32_bf16 v[78:81], v[176:179], v[228:231], v[78:81]
	v_mfma_f32_16x16x32_bf16 v[126:129], v[172:175], v[208:211], v[126:129]
	v_mfma_f32_16x16x32_bf16 v[122:125], v[184:187], v[208:211], v[122:125]
	v_mfma_f32_16x16x32_bf16 v[118:121], v[172:175], v[216:219], v[118:121]
	v_mfma_f32_16x16x32_bf16 v[110:113], v[184:187], v[216:219], v[110:113]
	v_mfma_f32_16x16x32_bf16 v[102:105], v[172:175], v[224:227], v[102:105]
	v_mfma_f32_16x16x32_bf16 v[94:97], v[184:187], v[224:227], v[94:97]
	v_mfma_f32_16x16x32_bf16 v[86:89], v[172:175], v[232:235], v[86:89]
	v_mfma_f32_16x16x32_bf16 v[78:81], v[184:187], v[232:235], v[78:81]
	v_mfma_f32_16x16x32_bf16 v[114:117], v[188:191], v[204:207], v[114:117]
	v_mfma_f32_16x16x32_bf16 v[106:109], v[196:199], v[204:207], v[106:109]
	v_mfma_f32_16x16x32_bf16 v[98:101], v[188:191], v[212:215], v[98:101]
	v_mfma_f32_16x16x32_bf16 v[90:93], v[196:199], v[212:215], v[90:93]
	v_mfma_f32_16x16x32_bf16 v[82:85], v[188:191], v[220:223], v[82:85]
	v_mfma_f32_16x16x32_bf16 v[74:77], v[196:199], v[220:223], v[74:77]
	v_mfma_f32_16x16x32_bf16 v[70:73], v[188:191], v[228:231], v[70:73]
	v_mfma_f32_16x16x32_bf16 v[66:69], v[196:199], v[228:231], v[66:69]
	v_mfma_f32_16x16x32_bf16 v[114:117], v[192:195], v[208:211], v[114:117]
	v_mfma_f32_16x16x32_bf16 v[106:109], v[200:203], v[208:211], v[106:109]
	v_mfma_f32_16x16x32_bf16 v[98:101], v[192:195], v[216:219], v[98:101]
	v_mfma_f32_16x16x32_bf16 v[90:93], v[200:203], v[216:219], v[90:93]
	v_mfma_f32_16x16x32_bf16 v[82:85], v[192:195], v[224:227], v[82:85]
	v_mfma_f32_16x16x32_bf16 v[74:77], v[200:203], v[224:227], v[74:77]
	v_mfma_f32_16x16x32_bf16 v[70:73], v[192:195], v[232:235], v[70:73]
	v_mfma_f32_16x16x32_bf16 v[66:69], v[200:203], v[232:235], v[66:69]
	s_barrier
; #define PG8_STAGE(bufoff, gbase, voff) do { _Pragma("unroll") for (int _i = 0; _i < 2; ++_i) \
;         __builtin_amdgcn_global_load_lds((const unsigned*)((const char*)(gbase) + (voff)[_i]), (LAS unsigned*)(lds + (bufoff) + ldsw + _i * 8192), 16, 0, 0); } while (0)
; #define PG8_LDA(dst, b, h) do { _Pragma("unroll") for (int m = 0; m < 4; ++m) _Pragma("unroll") for (int k = 0; k < 2; ++k) dst[m][k] = *(const LAS bf16x8*)(lds + PG8_SA(b, h) + aoff + m * 2048 + k * 1024); } while (0)
; #define PG8_MMA(ai, bj, At, Bt) do { __builtin_amdgcn_s_setprio(1); _Pragma("unroll") for (int m = 0; m < 4; ++m) _Pragma("unroll") for (int n = 0; n < 2; ++n) _Pragma("unroll") for (int k = 0; k < 2; ++k) \
;         acc[ai][bj][m][n] = __builtin_amdgcn_mfma_f32_16x16x32_bf16(Bt[n][k], At[m][k], acc[ai][bj][m][n], 0, 0, 0); __builtin_amdgcn_s_setprio(0); } while (0)
; #define PG8_WAIT_V(n) asm volatile("s_waitcnt vmcnt(" #n ")" ::: "memory")
; #define PG8_WAIT_L(n) asm volatile("s_waitcnt lgkmcnt(" #n ")" ::: "memory")
; #define PG8_BAR __builtin_amdgcn_s_barrier()
; #define PG8_SCHED __builtin_amdgcn_sched_barrier(0)
; template <class Epi, bool ALIGN_EPI = PG8_ALIGN, bool SP2 = PG8_SP2>
; __device__ __forceinline__ void gemm_phase(LAS uchar* lds, const Gemm g, const StaticOrder& S, const Epi& E) {
;     ...
;         for (int t = tb; t < tb + tblk; t += 2) {
;             const bool last = (t == nt - 2);
;             const char* a1 = cA + (size_t)(t + 1) * kstep;
;             const char* a2 = last ? nA : cA + (size_t)(t + 2) * kstep; const char* b2 = last ? nB : cB + (size_t)(t + 2) * kstep;
;     ...
;             PG8_LDA(At, 1, 1); PG8_STAGE(PG8_SB(1, 0), b3, voffB); PG8_STAGE(PG8_SB(1, 1), b3 + hstepB, voffB); PG8_STAGE(PG8_SA(1, 0), a3, voffA);
;             PG8_WAIT_V(8); PG8_WAIT_L(0); PG8_BAR; PG8_MMA(1, 0, At, B0); PG8_MMA(1, 1, At, B1); PG8_BAR; PG8_SCHED;
	s_setprio 0
	s_add_i32 s16, s41, s23
	v_lshl_add_u64 v[168:169], v[168:169], 0, s[84:85]
	s_mov_b32 m0, s16
	ds_read_b128 v[204:207], v171 offset:49152
	ds_read_b128 v[208:211], v171 offset:50176
	ds_read_b128 v[212:215], v171 offset:51200
	ds_read_b128 v[216:219], v171 offset:52224
	ds_read_b128 v[220:223], v171 offset:53248
	ds_read_b128 v[224:227], v171 offset:54272
	ds_read_b128 v[228:231], v171 offset:55296
	ds_read_b128 v[232:235], v171 offset:56320
	global_load_lds_dwordx4 v[168:169], off
	s_add_i32 m0, s16, 0x2000
	s_add_u32 s4, s4, 0x44080
	v_lshl_add_u64 v[168:169], v[180:181], 0, s[84:85]
	s_addc_u32 s5, s5, 0
	s_add_i32 s16, s42, s23
	global_load_lds_dwordx4 v[168:169], off
	s_mov_b32 m0, s16
	v_lshl_add_u64 v[168:169], s[4:5], 0, v[134:135]
	global_load_lds_dwordx4 v[168:169], off
	s_add_i32 m0, s16, 0x2000
	v_lshl_add_u64 v[168:169], s[4:5], 0, v[130:131]
	global_load_lds_dwordx4 v[168:169], off
	s_mov_b32 m0, s29
	v_lshl_add_u64 v[168:169], v[236:237], 0, s[84:85]
	global_load_lds_dwordx4 v[168:169], off
	s_mov_b32 m0, s30
	v_lshl_add_u64 v[168:169], v[238:239], 0, s[84:85]
	global_load_lds_dwordx4 v[168:169], off
	s_waitcnt vmcnt(8)
	s_waitcnt lgkmcnt(0)
	s_setprio 1
	s_barrier
	v_mfma_f32_16x16x32_bf16 v[62:65], v[164:167], v[204:207], v[62:65]
	v_mfma_f32_16x16x32_bf16 v[58:61], v[176:179], v[204:207], v[58:61]
	v_mfma_f32_16x16x32_bf16 v[54:57], v[164:167], v[212:215], v[54:57]
	v_mfma_f32_16x16x32_bf16 v[46:49], v[176:179], v[212:215], v[46:49]
	v_mfma_f32_16x16x32_bf16 v[38:41], v[164:167], v[220:223], v[38:41]
	v_mfma_f32_16x16x32_bf16 v[30:33], v[176:179], v[220:223], v[30:33]
	v_mfma_f32_16x16x32_bf16 v[22:25], v[164:167], v[228:231], v[22:25]
	v_mfma_f32_16x16x32_bf16 v[14:17], v[176:179], v[228:231], v[14:17]
	v_mfma_f32_16x16x32_bf16 v[62:65], v[172:175], v[208:211], v[62:65]
	v_mfma_f32_16x16x32_bf16 v[58:61], v[184:187], v[208:211], v[58:61]
	v_mfma_f32_16x16x32_bf16 v[54:57], v[172:175], v[216:219], v[54:57]
	v_mfma_f32_16x16x32_bf16 v[46:49], v[184:187], v[216:219], v[46:49]
	v_mfma_f32_16x16x32_bf16 v[38:41], v[172:175], v[224:227], v[38:41]
	v_mfma_f32_16x16x32_bf16 v[30:33], v[184:187], v[224:227], v[30:33]
	v_mfma_f32_16x16x32_bf16 v[22:25], v[172:175], v[232:235], v[22:25]
	v_mfma_f32_16x16x32_bf16 v[14:17], v[184:187], v[232:235], v[14:17]
	v_mfma_f32_16x16x32_bf16 v[50:53], v[188:191], v[204:207], v[50:53]
	v_mfma_f32_16x16x32_bf16 v[42:45], v[196:199], v[204:207], v[42:45]
	v_mfma_f32_16x16x32_bf16 v[34:37], v[188:191], v[212:215], v[34:37]
	v_mfma_f32_16x16x32_bf16 v[26:29], v[196:199], v[212:215], v[26:29]
	v_mfma_f32_16x16x32_bf16 v[18:21], v[188:191], v[220:223], v[18:21]
	v_mfma_f32_16x16x32_bf16 v[10:13], v[196:199], v[220:223], v[10:13]
	v_mfma_f32_16x16x32_bf16 v[6:9], v[188:191], v[228:231], v[6:9]
	v_mfma_f32_16x16x32_bf16 v[2:5], v[196:199], v[228:231], v[2:5]
	v_mfma_f32_16x16x32_bf16 v[50:53], v[192:195], v[208:211], v[50:53]
	v_mfma_f32_16x16x32_bf16 v[42:45], v[200:203], v[208:211], v[42:45]
	v_mfma_f32_16x16x32_bf16 v[34:37], v[192:195], v[216:219], v[34:37]
	v_mfma_f32_16x16x32_bf16 v[26:29], v[200:203], v[216:219], v[26:29]
	v_mfma_f32_16x16x32_bf16 v[18:21], v[192:195], v[224:227], v[18:21]
	v_mfma_f32_16x16x32_bf16 v[10:13], v[200:203], v[224:227], v[10:13]
	v_mfma_f32_16x16x32_bf16 v[6:9], v[192:195], v[232:235], v[6:9]
	v_mfma_f32_16x16x32_bf16 v[2:5], v[200:203], v[232:235], v[2:5]
	s_barrier
	s_setprio 0
	s_add_i32 s40, s40, 2
	s_add_u32 s38, s38, 0x100
	s_addc_u32 s39, s39, 0
	s_cmp_gt_u32 s40, 13
	s_mov_b64 s[16:17], s[18:19]
	s_cbranch_scc0 .LBB0_345
	s_mov_b32 s97, 0
	s_and_b64 vcc, exec, s[10:11]
	s_cbranch_vccnz .LBB0_350
	v_lshl_add_u32 v164, s37, 8, v1
	s_cmp_gt_i32 s36, 23
	s_mov_b64 s[4:5], -1
	s_cbranch_scc1 .LBB0_351

; #define PG8_STAGE(bufoff, gbase, voff) do { _Pragma("unroll") for (int _i = 0; _i < 2; ++_i) \
;         __builtin_amdgcn_global_load_lds((const unsigned*)((const char*)(gbase) + (voff)[_i]), (LAS unsigned*)(lds + (bufoff) + ldsw + _i * 8192), 16, 0, 0); } while (0)
; #define PG8_LDA(dst, b, h) do { _Pragma("unroll") for (int m = 0; m < 4; ++m) _Pragma("unroll") for (int k = 0; k < 2; ++k) dst[m][k] = *(const LAS bf16x8*)(lds + PG8_SA(b, h) + aoff + m * 2048 + k * 1024); } while (0)
; #define PG8_LDB(dst, b, h) do { _Pragma("unroll") for (int n = 0; n < 2; ++n) _Pragma("unroll") for (int k = 0; k < 2; ++k) dst[n][k] = *(const LAS bf16x8*)(lds + PG8_SB(b, h) + boff + n * 2048 + k * 1024); } while (0)
; #define PG8_MMA(ai, bj, At, Bt) do { __builtin_amdgcn_s_setprio(1); _Pragma("unroll") for (int m = 0; m < 4; ++m) _Pragma("unroll") for (int n = 0; n < 2; ++n) _Pragma("unroll") for (int k = 0; k < 2; ++k) \
;         acc[ai][bj][m][n] = __builtin_amdgcn_mfma_f32_16x16x32_bf16(Bt[n][k], At[m][k], acc[ai][bj][m][n], 0, 0, 0); __builtin_amdgcn_s_setprio(0); } while (0)
; #define PG8_WAIT_V(n) asm volatile("s_waitcnt vmcnt(" #n ")" ::: "memory")
; #define PG8_WAIT_L(n) asm volatile("s_waitcnt lgkmcnt(" #n ")" ::: "memory")
; #define PG8_BAR __builtin_amdgcn_s_barrier()
; #define PG8_SCHED __builtin_amdgcn_sched_barrier(0)
; template <class Epi, bool ALIGN_EPI = PG8_ALIGN, bool SP2 = PG8_SP2>
; __device__ __forceinline__ void gemm_phase(LAS uchar* lds, const Gemm g, const StaticOrder& S, const Epi& E) {
;     ...
;             PG8_LDB(B0, 0, 0); PG8_LDB(B1, 0, 1); PG8_SCHED; PG8_LDA(At, 0, 0); PG8_STAGE(PG8_SA(1, 1), a1 + hstepA, voffA);
;             PG8_WAIT_V(8); PG8_WAIT_L(0); PG8_BAR; PG8_MMA(0, 0, At, B0); PG8_MMA(0, 1, At, B1); PG8_BAR; PG8_SCHED;
;             PG8_LDA(At, 0, 1); PG8_STAGE(PG8_SB(0, 0), b2, voffB); PG8_STAGE(PG8_SB(0, 1), b2 + hstepB, voffB); PG8_STAGE(PG8_SA(0, 0), a2, voffA);
;             PG8_WAIT_V(8); PG8_WAIT_L(0); PG8_BAR; PG8_MMA(1, 0, At, B0); PG8_MMA(1, 1, At, B1); PG8_BAR; PG8_SCHED;
.LBB0_580:
	s_add_i32 s42, s42, 2
	s_add_u32 s4, s14, s18
	s_addc_u32 s5, s15, s19
	s_add_u32 s4, s4, 0x100
	s_addc_u32 s5, s5, 0
	s_add_u32 s43, s38, s18
	s_addc_u32 s44, s39, s19
	s_add_i32 s45, 0, 0x10000
	s_cmpk_eq_i32 s18, 0xf00
	s_cselect_b32 s21, s1, s5
	s_cselect_b32 s20, s0, s4
	v_add_u32_e32 v1, s45, v168
	s_cselect_b32 s5, s13, s44
	s_cselect_b32 s4, s12, s43
	s_add_i32 s43, 0, 0x14000
	ds_read_b128 v[174:177], v1
	ds_read_b128 v[178:181], v1 offset:1024
	ds_read_b128 v[184:187], v1 offset:2048
	ds_read_b128 v[188:191], v1 offset:3072
	v_add_u32_e32 v1, s43, v168
	ds_read_b128 v[192:195], v1
	ds_read_b128 v[196:199], v1 offset:1024
	ds_read_b128 v[200:203], v1 offset:2048
	ds_read_b128 v[204:207], v1 offset:3072
	v_lshl_add_u64 v[2:3], v[164:165], 0, s[18:19]
	s_add_i32 m0, s25, 0xc000
	ds_read_b128 v[208:211], v170
	ds_read_b128 v[212:215], v170 offset:1024
	ds_read_b128 v[216:219], v170 offset:2048
	ds_read_b128 v[220:223], v170 offset:3072
	ds_read_b128 v[224:227], v170 offset:4096
	ds_read_b128 v[228:231], v170 offset:5120
	ds_read_b128 v[232:235], v170 offset:6144
	ds_read_b128 v[236:239], v170 offset:7168
	global_load_lds_dwordx4 v[2:3], off
	s_add_i32 m0, s25, 0xe000
	v_lshl_add_u64 v[2:3], v[166:167], 0, s[18:19]
	global_load_lds_dwordx4 v[2:3], off
	s_waitcnt vmcnt(8)
	s_waitcnt lgkmcnt(0)
	s_setprio 1
	s_barrier
	v_mfma_f32_16x16x32_bf16 v[128:131], v[174:177], v[208:211], v[128:131]
	v_mfma_f32_16x16x32_bf16 v[124:127], v[184:187], v[208:211], v[124:127]
	v_mfma_f32_16x16x32_bf16 v[112:115], v[174:177], v[216:219], v[112:115]
	v_mfma_f32_16x16x32_bf16 v[108:111], v[184:187], v[216:219], v[108:111]
	v_mfma_f32_16x16x32_bf16 v[96:99], v[174:177], v[224:227], v[96:99]
	v_mfma_f32_16x16x32_bf16 v[92:95], v[184:187], v[224:227], v[92:95]
	v_mfma_f32_16x16x32_bf16 v[80:83], v[174:177], v[232:235], v[80:83]
	v_mfma_f32_16x16x32_bf16 v[76:79], v[184:187], v[232:235], v[76:79]
	v_mfma_f32_16x16x32_bf16 v[128:131], v[178:181], v[212:215], v[128:131]
	v_mfma_f32_16x16x32_bf16 v[124:127], v[188:191], v[212:215], v[124:127]
	v_mfma_f32_16x16x32_bf16 v[112:115], v[178:181], v[220:223], v[112:115]
	v_mfma_f32_16x16x32_bf16 v[108:111], v[188:191], v[220:223], v[108:111]
	v_mfma_f32_16x16x32_bf16 v[96:99], v[178:181], v[228:231], v[96:99]
	v_mfma_f32_16x16x32_bf16 v[92:95], v[188:191], v[228:231], v[92:95]
	v_mfma_f32_16x16x32_bf16 v[80:83], v[178:181], v[236:239], v[80:83]
	v_mfma_f32_16x16x32_bf16 v[76:79], v[188:191], v[236:239], v[76:79]
	v_mfma_f32_16x16x32_bf16 v[120:123], v[192:195], v[208:211], v[120:123]
	v_mfma_f32_16x16x32_bf16 v[116:119], v[200:203], v[208:211], v[116:119]
	v_mfma_f32_16x16x32_bf16 v[104:107], v[192:195], v[216:219], v[104:107]
	v_mfma_f32_16x16x32_bf16 v[100:103], v[200:203], v[216:219], v[100:103]
	v_mfma_f32_16x16x32_bf16 v[88:91], v[192:195], v[224:227], v[88:91]
	v_mfma_f32_16x16x32_bf16 v[84:87], v[200:203], v[224:227], v[84:87]
	v_mfma_f32_16x16x32_bf16 v[72:75], v[192:195], v[232:235], v[72:75]
	v_mfma_f32_16x16x32_bf16 v[68:71], v[200:203], v[232:235], v[68:71]
	v_mfma_f32_16x16x32_bf16 v[120:123], v[196:199], v[212:215], v[120:123]
	v_mfma_f32_16x16x32_bf16 v[116:119], v[204:207], v[212:215], v[116:119]
	v_mfma_f32_16x16x32_bf16 v[104:107], v[196:199], v[220:223], v[104:107]
	v_mfma_f32_16x16x32_bf16 v[100:103], v[204:207], v[220:223], v[100:103]
	v_mfma_f32_16x16x32_bf16 v[88:91], v[196:199], v[228:231], v[88:91]
	v_mfma_f32_16x16x32_bf16 v[84:87], v[204:207], v[228:231], v[84:87]
	v_mfma_f32_16x16x32_bf16 v[72:75], v[196:199], v[236:239], v[72:75]
	v_mfma_f32_16x16x32_bf16 v[68:71], v[204:207], v[236:239], v[68:71]
	s_barrier
	s_setprio 0
	s_add_i32 s44, s45, s24
	v_lshl_add_u64 v[240:241], s[4:5], 0, v[134:135]
	s_mov_b32 m0, s44
	ds_read_b128 v[208:211], v170 offset:16384
	ds_read_b128 v[212:215], v170 offset:17408
	ds_read_b128 v[216:219], v170 offset:18432
	ds_read_b128 v[220:223], v170 offset:19456
	ds_read_b128 v[224:227], v170 offset:20480
	ds_read_b128 v[228:231], v170 offset:21504
	ds_read_b128 v[232:235], v170 offset:22528
	ds_read_b128 v[236:239], v170 offset:23552
	global_load_lds_dwordx4 v[240:241], off
	s_add_i32 m0, s44, 0x2000
	s_add_u32 s44, s4, 0x84000
	v_lshl_add_u64 v[242:243], s[4:5], 0, v[158:159]
	s_addc_u32 s45, s5, 0
	s_add_i32 s43, s43, s24
	global_load_lds_dwordx4 v[242:243], off
	s_mov_b32 m0, s43
	v_lshl_add_u64 v[2:3], s[44:45], 0, v[134:135]
	global_load_lds_dwordx4 v[2:3], off
	s_add_i32 m0, s43, 0x2000
	v_lshl_add_u64 v[2:3], s[44:45], 0, v[158:159]
	global_load_lds_dwordx4 v[2:3], off
	s_mov_b32 m0, s25
	v_lshl_add_u64 v[244:245], s[20:21], 0, v[132:133]
	global_load_lds_dwordx4 v[244:245], off
	s_mov_b32 m0, s26
	v_lshl_add_u64 v[246:247], s[20:21], 0, v[156:157]
	global_load_lds_dwordx4 v[246:247], off
	s_waitcnt vmcnt(8)
	s_waitcnt lgkmcnt(0)
	s_setprio 1
	s_barrier
; #define PG8_STAGE(bufoff, gbase, voff) do { _Pragma("unroll") for (int _i = 0; _i < 2; ++_i) \
;         __builtin_amdgcn_global_load_lds((const unsigned*)((const char*)(gbase) + (voff)[_i]), (LAS unsigned*)(lds + (bufoff) + ldsw + _i * 8192), 16, 0, 0); } while (0)
; #define PG8_LDA(dst, b, h) do { _Pragma("unroll") for (int m = 0; m < 4; ++m) _Pragma("unroll") for (int k = 0; k < 2; ++k) dst[m][k] = *(const LAS bf16x8*)(lds + PG8_SA(b, h) + aoff + m * 2048 + k * 1024); } while (0)
; #define PG8_LDB(dst, b, h) do { _Pragma("unroll") for (int n = 0; n < 2; ++n) _Pragma("unroll") for (int k = 0; k < 2; ++k) dst[n][k] = *(const LAS bf16x8*)(lds + PG8_SB(b, h) + boff + n * 2048 + k * 1024); } while (0)
; #define PG8_MMA(ai, bj, At, Bt) do { __builtin_amdgcn_s_setprio(1); _Pragma("unroll") for (int m = 0; m < 4; ++m) _Pragma("unroll") for (int n = 0; n < 2; ++n) _Pragma("unroll") for (int k = 0; k < 2; ++k) \
;         acc[ai][bj][m][n] = __builtin_amdgcn_mfma_f32_16x16x32_bf16(Bt[n][k], At[m][k], acc[ai][bj][m][n], 0, 0, 0); __builtin_amdgcn_s_setprio(0); } while (0)
; #define PG8_WAIT_V(n) asm volatile("s_waitcnt vmcnt(" #n ")" ::: "memory")
; #define PG8_WAIT_L(n) asm volatile("s_waitcnt lgkmcnt(" #n ")" ::: "memory")
; #define PG8_BAR __builtin_amdgcn_s_barrier()
; #define PG8_SCHED __builtin_amdgcn_sched_barrier(0)
; template <class Epi, bool ALIGN_EPI = PG8_ALIGN, bool SP2 = PG8_SP2>
; __device__ __forceinline__ void gemm_phase(LAS uchar* lds, const Gemm g, const StaticOrder& S, const Epi& E) {
;     ...
;             PG8_WAIT_V(8); PG8_WAIT_L(0); PG8_BAR; PG8_MMA(1, 0, At, B0); PG8_MMA(1, 1, At, B1); PG8_BAR; PG8_SCHED;
;             PG8_LDB(B0, 1, 0); PG8_LDB(B1, 1, 1); PG8_SCHED; PG8_LDA(At, 1, 0); PG8_STAGE(PG8_SA(0, 1), a2 + hstepA, voffA);
;             PG8_WAIT_V(8); PG8_WAIT_L(0); PG8_BAR; PG8_MMA(0, 0, At, B0); PG8_MMA(0, 1, At, B1); PG8_BAR; PG8_SCHED;
	v_mfma_f32_16x16x32_bf16 v[64:67], v[174:177], v[208:211], v[64:67]
	v_mfma_f32_16x16x32_bf16 v[60:63], v[184:187], v[208:211], v[60:63]
	v_mfma_f32_16x16x32_bf16 v[48:51], v[174:177], v[216:219], v[48:51]
	v_mfma_f32_16x16x32_bf16 v[44:47], v[184:187], v[216:219], v[44:47]
	v_mfma_f32_16x16x32_bf16 v[32:35], v[174:177], v[224:227], v[32:35]
	v_mfma_f32_16x16x32_bf16 v[28:31], v[184:187], v[224:227], v[28:31]
	v_mfma_f32_16x16x32_bf16 v[16:19], v[174:177], v[232:235], v[16:19]
	v_mfma_f32_16x16x32_bf16 v[12:15], v[184:187], v[232:235], v[12:15]
	v_mfma_f32_16x16x32_bf16 v[64:67], v[178:181], v[212:215], v[64:67]
	v_mfma_f32_16x16x32_bf16 v[60:63], v[188:191], v[212:215], v[60:63]
	v_mfma_f32_16x16x32_bf16 v[48:51], v[178:181], v[220:223], v[48:51]
	v_mfma_f32_16x16x32_bf16 v[44:47], v[188:191], v[220:223], v[44:47]
	v_mfma_f32_16x16x32_bf16 v[32:35], v[178:181], v[228:231], v[32:35]
	v_mfma_f32_16x16x32_bf16 v[28:31], v[188:191], v[228:231], v[28:31]
	v_mfma_f32_16x16x32_bf16 v[16:19], v[178:181], v[236:239], v[16:19]
	v_mfma_f32_16x16x32_bf16 v[12:15], v[188:191], v[236:239], v[12:15]
	v_mfma_f32_16x16x32_bf16 v[56:59], v[192:195], v[208:211], v[56:59]
	v_mfma_f32_16x16x32_bf16 v[52:55], v[200:203], v[208:211], v[52:55]
	v_mfma_f32_16x16x32_bf16 v[40:43], v[192:195], v[216:219], v[40:43]
	v_mfma_f32_16x16x32_bf16 v[36:39], v[200:203], v[216:219], v[36:39]
	v_mfma_f32_16x16x32_bf16 v[24:27], v[192:195], v[224:227], v[24:27]
	v_mfma_f32_16x16x32_bf16 v[20:23], v[200:203], v[224:227], v[20:23]
	v_mfma_f32_16x16x32_bf16 v[8:11], v[192:195], v[232:235], v[8:11]
	v_mfma_f32_16x16x32_bf16 v[2:5], v[200:203], v[232:235], v[4:7]
	v_mfma_f32_16x16x32_bf16 v[56:59], v[196:199], v[212:215], v[56:59]
	v_mfma_f32_16x16x32_bf16 v[52:55], v[204:207], v[212:215], v[52:55]
	v_mfma_f32_16x16x32_bf16 v[40:43], v[196:199], v[220:223], v[40:43]
	v_mfma_f32_16x16x32_bf16 v[36:39], v[204:207], v[220:223], v[36:39]
	v_mfma_f32_16x16x32_bf16 v[24:27], v[196:199], v[228:231], v[24:27]
	v_mfma_f32_16x16x32_bf16 v[20:23], v[204:207], v[228:231], v[20:23]
	v_mfma_f32_16x16x32_bf16 v[8:11], v[196:199], v[236:239], v[8:11]
	v_mfma_f32_16x16x32_bf16 v[2:5], v[204:207], v[236:239], v[2:5]
	s_barrier
	s_setprio 0
	s_add_i32 s43, 0, 0x18000
	v_add_u32_e32 v1, s43, v168
	s_add_i32 s44, 0, 0x1c000
	ds_read_b128 v[174:177], v1
	ds_read_b128 v[178:181], v1 offset:1024
	ds_read_b128 v[184:187], v1 offset:2048
	ds_read_b128 v[188:191], v1 offset:3072
	v_add_u32_e32 v1, s44, v168
	ds_read_b128 v[192:195], v1
	ds_read_b128 v[196:199], v1 offset:1024
	ds_read_b128 v[200:203], v1 offset:2048
	ds_read_b128 v[204:207], v1 offset:3072
	s_add_u32 s20, s20, 0x184000
	s_addc_u32 s21, s21, 0
	s_mov_b32 m0, s27
	v_lshl_add_u64 v[6:7], s[20:21], 0, v[132:133]
	ds_read_b128 v[208:211], v170 offset:32768
	ds_read_b128 v[212:215], v170 offset:33792
	ds_read_b128 v[216:219], v170 offset:34816
	ds_read_b128 v[220:223], v170 offset:35840
	ds_read_b128 v[224:227], v170 offset:36864
	ds_read_b128 v[228:231], v170 offset:37888
	ds_read_b128 v[232:235], v170 offset:38912
	ds_read_b128 v[236:239], v170 offset:39936
	global_load_lds_dwordx4 v[6:7], off
	s_mov_b32 m0, s28
	v_lshl_add_u64 v[6:7], s[20:21], 0, v[156:157]
	global_load_lds_dwordx4 v[6:7], off
	s_waitcnt vmcnt(8)
	s_waitcnt lgkmcnt(0)
	s_setprio 1
	s_barrier
	v_mfma_f32_16x16x32_bf16 v[128:131], v[174:177], v[208:211], v[128:131]
	v_mfma_f32_16x16x32_bf16 v[124:127], v[184:187], v[208:211], v[124:127]
	v_mfma_f32_16x16x32_bf16 v[112:115], v[174:177], v[216:219], v[112:115]
	v_mfma_f32_16x16x32_bf16 v[108:111], v[184:187], v[216:219], v[108:111]
	v_mfma_f32_16x16x32_bf16 v[96:99], v[174:177], v[224:227], v[96:99]
	v_mfma_f32_16x16x32_bf16 v[92:95], v[184:187], v[224:227], v[92:95]
	v_mfma_f32_16x16x32_bf16 v[80:83], v[174:177], v[232:235], v[80:83]
	v_mfma_f32_16x16x32_bf16 v[76:79], v[184:187], v[232:235], v[76:79]
	v_mfma_f32_16x16x32_bf16 v[128:131], v[178:181], v[212:215], v[128:131]
	v_mfma_f32_16x16x32_bf16 v[124:127], v[188:191], v[212:215], v[124:127]
	v_mfma_f32_16x16x32_bf16 v[112:115], v[178:181], v[220:223], v[112:115]
	v_mfma_f32_16x16x32_bf16 v[108:111], v[188:191], v[220:223], v[108:111]
	v_mfma_f32_16x16x32_bf16 v[96:99], v[178:181], v[228:231], v[96:99]
	v_mfma_f32_16x16x32_bf16 v[92:95], v[188:191], v[228:231], v[92:95]
	v_mfma_f32_16x16x32_bf16 v[80:83], v[178:181], v[236:239], v[80:83]
	v_mfma_f32_16x16x32_bf16 v[76:79], v[188:191], v[236:239], v[76:79]
	v_mfma_f32_16x16x32_bf16 v[120:123], v[192:195], v[208:211], v[120:123]
	v_mfma_f32_16x16x32_bf16 v[116:119], v[200:203], v[208:211], v[116:119]
	v_mfma_f32_16x16x32_bf16 v[104:107], v[192:195], v[216:219], v[104:107]
	v_mfma_f32_16x16x32_bf16 v[100:103], v[200:203], v[216:219], v[100:103]
	v_mfma_f32_16x16x32_bf16 v[88:91], v[192:195], v[224:227], v[88:91]
	v_mfma_f32_16x16x32_bf16 v[84:87], v[200:203], v[224:227], v[84:87]
	v_mfma_f32_16x16x32_bf16 v[72:75], v[192:195], v[232:235], v[72:75]
	v_mfma_f32_16x16x32_bf16 v[68:71], v[200:203], v[232:235], v[68:71]
	v_mfma_f32_16x16x32_bf16 v[120:123], v[196:199], v[212:215], v[120:123]
	v_mfma_f32_16x16x32_bf16 v[116:119], v[204:207], v[212:215], v[116:119]
	v_mfma_f32_16x16x32_bf16 v[104:107], v[196:199], v[220:223], v[104:107]
	v_mfma_f32_16x16x32_bf16 v[100:103], v[204:207], v[220:223], v[100:103]
	v_mfma_f32_16x16x32_bf16 v[88:91], v[196:199], v[228:231], v[88:91]
	v_mfma_f32_16x16x32_bf16 v[84:87], v[204:207], v[228:231], v[84:87]
	v_mfma_f32_16x16x32_bf16 v[72:75], v[196:199], v[236:239], v[72:75]
	v_mfma_f32_16x16x32_bf16 v[68:71], v[204:207], v[236:239], v[68:71]
	s_barrier
; #define LAS __attribute__((address_space(3)))
; #define PG8_STAGE(bufoff, gbase, voff) do { _Pragma("unroll") for (int _i = 0; _i < 2; ++_i) \
;         __builtin_amdgcn_global_load_lds((const unsigned*)((const char*)(gbase) + (voff)[_i]), (LAS unsigned*)(lds + (bufoff) + ldsw + _i * 8192), 16, 0, 0); } while (0)
; #define PG8_LDA(dst, b, h) do { _Pragma("unroll") for (int m = 0; m < 4; ++m) _Pragma("unroll") for (int k = 0; k < 2; ++k) dst[m][k] = *(const LAS bf16x8*)(lds + PG8_SA(b, h) + aoff + m * 2048 + k * 1024); } while (0)
; #define PG8_MMA(ai, bj, At, Bt) do { __builtin_amdgcn_s_setprio(1); _Pragma("unroll") for (int m = 0; m < 4; ++m) _Pragma("unroll") for (int n = 0; n < 2; ++n) _Pragma("unroll") for (int k = 0; k < 2; ++k) \
;         acc[ai][bj][m][n] = __builtin_amdgcn_mfma_f32_16x16x32_bf16(Bt[n][k], At[m][k], acc[ai][bj][m][n], 0, 0, 0); __builtin_amdgcn_s_setprio(0); } while (0)
; #define PG8_WAIT_V(n) asm volatile("s_waitcnt vmcnt(" #n ")" ::: "memory")
; #define PG8_WAIT_L(n) asm volatile("s_waitcnt lgkmcnt(" #n ")" ::: "memory")
; #define PG8_BAR __builtin_amdgcn_s_barrier()
; #define PG8_SCHED __builtin_amdgcn_sched_barrier(0)
; template <class Epi, bool ALIGN_EPI = PG8_ALIGN, bool SP2 = PG8_SP2>
; __device__ __forceinline__ void gemm_phase(LAS uchar* lds, const Gemm g, const StaticOrder& S, const Epi& E) {
;     ...
; #pragma unroll 1
;         for (int tb = 0; tb < nt; tb += tblk) {
;         if constexpr (Epi::GROUPS) { if (tb > 0) {
;             const LAS float* rt = (const LAS float*)(lds + LDS_RT) + ((ui & 1) * 256 + wr * 64 + fr) * 8 + ((tb >> 2) - 1);
; #pragma unroll
;             for (int a = 0; a < 2; ++a)
; #pragma unroll
;                 for (int m = 0; m < 4; ++m) { const float f = rt[(a * 128 + m * 16) * 8];
; #pragma unroll
;                     for (int b = 0; b < 2; ++b)
; #pragma unroll
;                         for (int n = 0; n < 2; ++n) acc[a][b][m][n] *= f; } } }
; #pragma unroll 1
;         for (int t = tb; t < tb + tblk; t += 2) {
;     ...
;             PG8_LDA(At, 1, 1); PG8_STAGE(PG8_SB(1, 0), b3, voffB); PG8_STAGE(PG8_SB(1, 1), b3 + hstepB, voffB); PG8_STAGE(PG8_SA(1, 0), a3, voffA);
;             PG8_WAIT_V(8); PG8_WAIT_L(0); PG8_BAR; PG8_MMA(1, 0, At, B0); PG8_MMA(1, 1, At, B1); PG8_BAR; PG8_SCHED;
	s_setprio 0
	s_add_i32 s20, s43, s24
	v_lshl_add_u64 v[6:7], v[240:241], 0, s[84:85]
	s_mov_b32 m0, s20
	ds_read_b128 v[208:211], v170 offset:49152
	ds_read_b128 v[212:215], v170 offset:50176
	ds_read_b128 v[216:219], v170 offset:51200
	ds_read_b128 v[220:223], v170 offset:52224
	ds_read_b128 v[224:227], v170 offset:53248
	ds_read_b128 v[228:231], v170 offset:54272
	ds_read_b128 v[232:235], v170 offset:55296
	ds_read_b128 v[236:239], v170 offset:56320
	global_load_lds_dwordx4 v[6:7], off
	s_add_i32 m0, s20, 0x2000
	s_add_u32 s4, s4, 0x84080
	v_lshl_add_u64 v[6:7], v[242:243], 0, s[84:85]
	s_addc_u32 s5, s5, 0
	s_add_i32 s20, s44, s24
	global_load_lds_dwordx4 v[6:7], off
	s_mov_b32 m0, s20
	v_lshl_add_u64 v[6:7], s[4:5], 0, v[134:135]
	global_load_lds_dwordx4 v[6:7], off
	s_add_i32 m0, s20, 0x2000
	v_lshl_add_u64 v[6:7], s[4:5], 0, v[158:159]
	global_load_lds_dwordx4 v[6:7], off
	s_mov_b32 m0, s29
	v_lshl_add_u64 v[6:7], v[244:245], 0, s[84:85]
	global_load_lds_dwordx4 v[6:7], off
	s_mov_b32 m0, s30
	v_lshl_add_u64 v[6:7], v[246:247], 0, s[84:85]
	global_load_lds_dwordx4 v[6:7], off
	s_waitcnt vmcnt(8)
	s_waitcnt lgkmcnt(0)
	s_setprio 1
	s_barrier
	v_mfma_f32_16x16x32_bf16 v[64:67], v[174:177], v[208:211], v[64:67]
	v_mfma_f32_16x16x32_bf16 v[60:63], v[184:187], v[208:211], v[60:63]
	v_mfma_f32_16x16x32_bf16 v[48:51], v[174:177], v[216:219], v[48:51]
	v_mfma_f32_16x16x32_bf16 v[44:47], v[184:187], v[216:219], v[44:47]
	v_mfma_f32_16x16x32_bf16 v[32:35], v[174:177], v[224:227], v[32:35]
	v_mfma_f32_16x16x32_bf16 v[28:31], v[184:187], v[224:227], v[28:31]
	v_mfma_f32_16x16x32_bf16 v[16:19], v[174:177], v[232:235], v[16:19]
	v_mfma_f32_16x16x32_bf16 v[12:15], v[184:187], v[232:235], v[12:15]
	v_mfma_f32_16x16x32_bf16 v[64:67], v[178:181], v[212:215], v[64:67]
	v_mfma_f32_16x16x32_bf16 v[60:63], v[188:191], v[212:215], v[60:63]
	v_mfma_f32_16x16x32_bf16 v[48:51], v[178:181], v[220:223], v[48:51]
	v_mfma_f32_16x16x32_bf16 v[44:47], v[188:191], v[220:223], v[44:47]
	v_mfma_f32_16x16x32_bf16 v[32:35], v[178:181], v[228:231], v[32:35]
	v_mfma_f32_16x16x32_bf16 v[28:31], v[188:191], v[228:231], v[28:31]
	v_mfma_f32_16x16x32_bf16 v[16:19], v[178:181], v[236:239], v[16:19]
	v_mfma_f32_16x16x32_bf16 v[12:15], v[188:191], v[236:239], v[12:15]
	v_mfma_f32_16x16x32_bf16 v[56:59], v[192:195], v[208:211], v[56:59]
	v_mfma_f32_16x16x32_bf16 v[52:55], v[200:203], v[208:211], v[52:55]
	v_mfma_f32_16x16x32_bf16 v[40:43], v[192:195], v[216:219], v[40:43]
	v_mfma_f32_16x16x32_bf16 v[36:39], v[200:203], v[216:219], v[36:39]
	v_mfma_f32_16x16x32_bf16 v[24:27], v[192:195], v[224:227], v[24:27]
	v_mfma_f32_16x16x32_bf16 v[20:23], v[200:203], v[224:227], v[20:23]
	v_mfma_f32_16x16x32_bf16 v[6:9], v[192:195], v[232:235], v[8:11]
	v_mfma_f32_16x16x32_bf16 v[2:5], v[200:203], v[232:235], v[2:5]
	v_mfma_f32_16x16x32_bf16 v[56:59], v[196:199], v[212:215], v[56:59]
	v_mfma_f32_16x16x32_bf16 v[52:55], v[204:207], v[212:215], v[52:55]
	v_mfma_f32_16x16x32_bf16 v[40:43], v[196:199], v[220:223], v[40:43]
	v_mfma_f32_16x16x32_bf16 v[36:39], v[204:207], v[220:223], v[36:39]
	v_mfma_f32_16x16x32_bf16 v[24:27], v[196:199], v[228:231], v[24:27]
	v_mfma_f32_16x16x32_bf16 v[20:23], v[204:207], v[228:231], v[20:23]
	v_mfma_f32_16x16x32_bf16 v[8:11], v[196:199], v[236:239], v[6:9]
	v_mfma_f32_16x16x32_bf16 v[4:7], v[204:207], v[236:239], v[2:5]
	s_barrier
	s_setprio 0
	s_add_u32 s18, s18, 0x100
	s_addc_u32 s19, s19, 0
	s_cmp_ge_u32 s42, s41
	s_cbranch_scc0 .LBB0_580
	s_add_u32 s16, s16, 0x200
	s_addc_u32 s17, s17, 0
	s_cmp_lt_u32 s40, 28
	s_cbranch_scc0 .LBB0_583
	s_mov_b32 s40, s41
	s_cmp_eq_u32 s40, 0
	s_cbranch_scc0 .LBB0_578
	s_branch .LBB0_579

; #define PG8_STAGE(bufoff, gbase, voff) do { _Pragma("unroll") for (int _i = 0; _i < 2; ++_i) \
;         __builtin_amdgcn_global_load_lds((const unsigned*)((const char*)(gbase) + (voff)[_i]), (LAS unsigned*)(lds + (bufoff) + ldsw + _i * 8192), 16, 0, 0); } while (0)
; #define PG8_LDA(dst, b, h) do { _Pragma("unroll") for (int m = 0; m < 4; ++m) _Pragma("unroll") for (int k = 0; k < 2; ++k) dst[m][k] = *(const LAS bf16x8*)(lds + PG8_SA(b, h) + aoff + m * 2048 + k * 1024); } while (0)
; #define PG8_LDB(dst, b, h) do { _Pragma("unroll") for (int n = 0; n < 2; ++n) _Pragma("unroll") for (int k = 0; k < 2; ++k) dst[n][k] = *(const LAS bf16x8*)(lds + PG8_SB(b, h) + boff + n * 2048 + k * 1024); } while (0)
; #define PG8_MMA(ai, bj, At, Bt) do { __builtin_amdgcn_s_setprio(1); _Pragma("unroll") for (int m = 0; m < 4; ++m) _Pragma("unroll") for (int n = 0; n < 2; ++n) _Pragma("unroll") for (int k = 0; k < 2; ++k) \
;         acc[ai][bj][m][n] = __builtin_amdgcn_mfma_f32_16x16x32_bf16(Bt[n][k], At[m][k], acc[ai][bj][m][n], 0, 0, 0); __builtin_amdgcn_s_setprio(0); } while (0)
; #define PG8_WAIT_V(n) asm volatile("s_waitcnt vmcnt(" #n ")" ::: "memory")
; #define PG8_WAIT_L(n) asm volatile("s_waitcnt lgkmcnt(" #n ")" ::: "memory")
; #define PG8_BAR __builtin_amdgcn_s_barrier()
; #define PG8_SCHED __builtin_amdgcn_sched_barrier(0)
; template <class Epi, bool ALIGN_EPI = PG8_ALIGN, bool SP2 = PG8_SP2>
; __device__ __forceinline__ void gemm_phase(LAS uchar* lds, const Gemm g, const StaticOrder& S, const Epi& E) {
;     ...
;             PG8_LDB(B0, 0, 0); PG8_LDB(B1, 0, 1); PG8_SCHED; PG8_LDA(At, 0, 0); PG8_STAGE(PG8_SA(1, 1), a1 + hstepA, voffA);
;             PG8_WAIT_V(8); PG8_WAIT_L(0); PG8_BAR; PG8_MMA(0, 0, At, B0); PG8_MMA(0, 1, At, B1); PG8_BAR; PG8_SCHED;
;             PG8_LDA(At, 0, 1); PG8_STAGE(PG8_SB(0, 0), b2, voffB); PG8_STAGE(PG8_SB(0, 1), b2 + hstepB, voffB); PG8_STAGE(PG8_SA(0, 0), a2, voffA);
;             PG8_WAIT_V(8); PG8_WAIT_L(0); PG8_BAR; PG8_MMA(1, 0, At, B0); PG8_MMA(1, 1, At, B1); PG8_BAR; PG8_SCHED;
;     ...
; #pragma unroll
;         for (int a = 0; a < 2; ++a)
; #pragma unroll
;             for (int b = 0; b < 2; ++b)
; #pragma unroll
;                 for (int m = 0; m < 4; ++m)
; #pragma unroll
;                     for (int n = 0; n < 2; ++n) acc[a][b][m][n] = (f32x4){0.f, 0.f, 0.f, 0.f};
.LBB0_668:
	s_add_u32 s36, s14, 0x100
	s_addc_u32 s37, s15, 0
	s_mov_b32 s38, -2
	s_add_u32 s14, s12, 0x100
	s_addc_u32 s15, s13, 0
	s_add_i32 s39, 0, 0x10000
	s_cmp_eq_u32 s38, 12
	s_cselect_b32 s19, s5, s15
	s_cselect_b32 s18, s4, s14
	s_cselect_b32 s17, s11, s37
	s_cselect_b32 s16, s10, s36
	s_add_i32 s40, 0, 0x14000
	v_add_u32_e32 v174, s39, v139
	v_add_u32_e32 v192, s40, v139
	ds_read_b128 v[160:163], v174
	ds_read_b128 v[164:167], v174 offset:1024
	ds_read_b128 v[168:171], v174 offset:2048
	ds_read_b128 v[174:177], v174 offset:3072
	ds_read_b128 v[178:181], v192
	ds_read_b128 v[184:187], v192 offset:1024
	ds_read_b128 v[188:191], v192 offset:2048
	ds_read_b128 v[192:195], v192 offset:3072
	v_lshl_add_u64 v[228:229], s[12:13], 0, v[156:157]
	s_add_i32 m0, s23, 0xc000
	ds_read_b128 v[196:199], v173
	ds_read_b128 v[200:203], v173 offset:1024
	ds_read_b128 v[204:207], v173 offset:2048
	ds_read_b128 v[208:211], v173 offset:3072
	ds_read_b128 v[212:215], v173 offset:4096
	ds_read_b128 v[216:219], v173 offset:5120
	ds_read_b128 v[220:223], v173 offset:6144
	ds_read_b128 v[224:227], v173 offset:7168
	global_load_lds_dwordx4 v[228:229], off
	s_add_i32 m0, s23, 0xe000
	v_lshl_add_u64 v[228:229], s[12:13], 0, v[158:159]
	global_load_lds_dwordx4 v[228:229], off
	s_waitcnt vmcnt(8)
	s_waitcnt lgkmcnt(0)
	s_setprio 1
	s_barrier
	v_mfma_f32_16x16x32_bf16 v[126:129], v[160:163], v[196:199], 0
	v_mfma_f32_16x16x32_bf16 v[122:125], v[168:171], v[196:199], 0
	v_mfma_f32_16x16x32_bf16 v[118:121], v[160:163], v[204:207], 0
	v_mfma_f32_16x16x32_bf16 v[110:113], v[168:171], v[204:207], 0
	v_mfma_f32_16x16x32_bf16 v[102:105], v[160:163], v[212:215], 0
	v_mfma_f32_16x16x32_bf16 v[94:97], v[168:171], v[212:215], 0
	v_mfma_f32_16x16x32_bf16 v[86:89], v[160:163], v[220:223], 0
	v_mfma_f32_16x16x32_bf16 v[78:81], v[168:171], v[220:223], 0
	v_mfma_f32_16x16x32_bf16 v[126:129], v[164:167], v[200:203], v[126:129]
	v_mfma_f32_16x16x32_bf16 v[122:125], v[174:177], v[200:203], v[122:125]
	v_mfma_f32_16x16x32_bf16 v[118:121], v[164:167], v[208:211], v[118:121]
	v_mfma_f32_16x16x32_bf16 v[110:113], v[174:177], v[208:211], v[110:113]
	v_mfma_f32_16x16x32_bf16 v[102:105], v[164:167], v[216:219], v[102:105]
	v_mfma_f32_16x16x32_bf16 v[94:97], v[174:177], v[216:219], v[94:97]
	v_mfma_f32_16x16x32_bf16 v[86:89], v[164:167], v[224:227], v[86:89]
	v_mfma_f32_16x16x32_bf16 v[78:81], v[174:177], v[224:227], v[78:81]
	v_mfma_f32_16x16x32_bf16 v[114:117], v[178:181], v[196:199], 0
	v_mfma_f32_16x16x32_bf16 v[106:109], v[188:191], v[196:199], 0
	v_mfma_f32_16x16x32_bf16 v[98:101], v[178:181], v[204:207], 0
	v_mfma_f32_16x16x32_bf16 v[90:93], v[188:191], v[204:207], 0
	v_mfma_f32_16x16x32_bf16 v[82:85], v[178:181], v[212:215], 0
	v_mfma_f32_16x16x32_bf16 v[74:77], v[188:191], v[212:215], 0
	v_mfma_f32_16x16x32_bf16 v[70:73], v[178:181], v[220:223], 0
	v_mfma_f32_16x16x32_bf16 v[66:69], v[188:191], v[220:223], 0
	v_mfma_f32_16x16x32_bf16 v[114:117], v[184:187], v[200:203], v[114:117]
	v_mfma_f32_16x16x32_bf16 v[106:109], v[192:195], v[200:203], v[106:109]
	v_mfma_f32_16x16x32_bf16 v[98:101], v[184:187], v[208:211], v[98:101]
	v_mfma_f32_16x16x32_bf16 v[90:93], v[192:195], v[208:211], v[90:93]
	v_mfma_f32_16x16x32_bf16 v[82:85], v[184:187], v[216:219], v[82:85]
	v_mfma_f32_16x16x32_bf16 v[74:77], v[192:195], v[216:219], v[74:77]
	v_mfma_f32_16x16x32_bf16 v[70:73], v[184:187], v[224:227], v[70:73]
	v_mfma_f32_16x16x32_bf16 v[66:69], v[192:195], v[224:227], v[66:69]
	s_barrier
	s_setprio 0
	s_add_i32 s12, s39, s21
	v_lshl_add_u64 v[228:229], s[16:17], 0, v[134:135]
	s_mov_b32 m0, s12
	ds_read_b128 v[196:199], v173 offset:16384
	ds_read_b128 v[200:203], v173 offset:17408
	ds_read_b128 v[204:207], v173 offset:18432
	ds_read_b128 v[208:211], v173 offset:19456
	ds_read_b128 v[212:215], v173 offset:20480
	ds_read_b128 v[216:219], v173 offset:21504
	ds_read_b128 v[220:223], v173 offset:22528
	ds_read_b128 v[224:227], v173 offset:23552
	global_load_lds_dwordx4 v[228:229], off
	s_add_i32 m0, s12, 0x2000
	s_add_u32 s12, s16, 0x44000
	v_lshl_add_u64 v[230:231], s[16:17], 0, v[130:131]
	s_addc_u32 s13, s17, 0
	s_add_i32 s39, s40, s21
	global_load_lds_dwordx4 v[230:231], off
	s_mov_b32 m0, s39
	v_lshl_add_u64 v[232:233], s[12:13], 0, v[134:135]
	global_load_lds_dwordx4 v[232:233], off
	s_add_i32 m0, s39, 0x2000
	v_lshl_add_u64 v[232:233], s[12:13], 0, v[130:131]
	global_load_lds_dwordx4 v[232:233], off
	s_mov_b32 m0, s23
	v_lshl_add_u64 v[232:233], s[18:19], 0, v[152:153]
	global_load_lds_dwordx4 v[232:233], off
	s_mov_b32 m0, s24
	v_lshl_add_u64 v[234:235], s[18:19], 0, v[132:133]
	global_load_lds_dwordx4 v[234:235], off
	s_waitcnt vmcnt(8)
	s_waitcnt lgkmcnt(0)
	s_setprio 1
	s_barrier
; #define PG8_STAGE(bufoff, gbase, voff) do { _Pragma("unroll") for (int _i = 0; _i < 2; ++_i) \
;         __builtin_amdgcn_global_load_lds((const unsigned*)((const char*)(gbase) + (voff)[_i]), (LAS unsigned*)(lds + (bufoff) + ldsw + _i * 8192), 16, 0, 0); } while (0)
; #define PG8_LDA(dst, b, h) do { _Pragma("unroll") for (int m = 0; m < 4; ++m) _Pragma("unroll") for (int k = 0; k < 2; ++k) dst[m][k] = *(const LAS bf16x8*)(lds + PG8_SA(b, h) + aoff + m * 2048 + k * 1024); } while (0)
; #define PG8_LDB(dst, b, h) do { _Pragma("unroll") for (int n = 0; n < 2; ++n) _Pragma("unroll") for (int k = 0; k < 2; ++k) dst[n][k] = *(const LAS bf16x8*)(lds + PG8_SB(b, h) + boff + n * 2048 + k * 1024); } while (0)
; #define PG8_MMA(ai, bj, At, Bt) do { __builtin_amdgcn_s_setprio(1); _Pragma("unroll") for (int m = 0; m < 4; ++m) _Pragma("unroll") for (int n = 0; n < 2; ++n) _Pragma("unroll") for (int k = 0; k < 2; ++k) \
;         acc[ai][bj][m][n] = __builtin_amdgcn_mfma_f32_16x16x32_bf16(Bt[n][k], At[m][k], acc[ai][bj][m][n], 0, 0, 0); __builtin_amdgcn_s_setprio(0); } while (0)
; #define PG8_WAIT_V(n) asm volatile("s_waitcnt vmcnt(" #n ")" ::: "memory")
; #define PG8_WAIT_L(n) asm volatile("s_waitcnt lgkmcnt(" #n ")" ::: "memory")
; #define PG8_BAR __builtin_amdgcn_s_barrier()
; #define PG8_SCHED __builtin_amdgcn_sched_barrier(0)
; template <class Epi, bool ALIGN_EPI = PG8_ALIGN, bool SP2 = PG8_SP2>
; __device__ __forceinline__ void gemm_phase(LAS uchar* lds, const Gemm g, const StaticOrder& S, const Epi& E) {
;     ...
;             PG8_WAIT_V(8); PG8_WAIT_L(0); PG8_BAR; PG8_MMA(1, 0, At, B0); PG8_MMA(1, 1, At, B1); PG8_BAR; PG8_SCHED;
;             PG8_LDB(B0, 1, 0); PG8_LDB(B1, 1, 1); PG8_SCHED; PG8_LDA(At, 1, 0); PG8_STAGE(PG8_SA(0, 1), a2 + hstepA, voffA);
;             PG8_WAIT_V(8); PG8_WAIT_L(0); PG8_BAR; PG8_MMA(0, 0, At, B0); PG8_MMA(0, 1, At, B1); PG8_BAR; PG8_SCHED;
	v_mfma_f32_16x16x32_bf16 v[62:65], v[160:163], v[196:199], 0
	v_mfma_f32_16x16x32_bf16 v[58:61], v[168:171], v[196:199], 0
	v_mfma_f32_16x16x32_bf16 v[54:57], v[160:163], v[204:207], 0
	v_mfma_f32_16x16x32_bf16 v[46:49], v[168:171], v[204:207], 0
	v_mfma_f32_16x16x32_bf16 v[38:41], v[160:163], v[212:215], 0
	v_mfma_f32_16x16x32_bf16 v[30:33], v[168:171], v[212:215], 0
	v_mfma_f32_16x16x32_bf16 v[22:25], v[160:163], v[220:223], 0
	v_mfma_f32_16x16x32_bf16 v[14:17], v[168:171], v[220:223], 0
	v_mfma_f32_16x16x32_bf16 v[62:65], v[164:167], v[200:203], v[62:65]
	v_mfma_f32_16x16x32_bf16 v[58:61], v[174:177], v[200:203], v[58:61]
	v_mfma_f32_16x16x32_bf16 v[54:57], v[164:167], v[208:211], v[54:57]
	v_mfma_f32_16x16x32_bf16 v[46:49], v[174:177], v[208:211], v[46:49]
	v_mfma_f32_16x16x32_bf16 v[38:41], v[164:167], v[216:219], v[38:41]
	v_mfma_f32_16x16x32_bf16 v[30:33], v[174:177], v[216:219], v[30:33]
	v_mfma_f32_16x16x32_bf16 v[22:25], v[164:167], v[224:227], v[22:25]
	v_mfma_f32_16x16x32_bf16 v[14:17], v[174:177], v[224:227], v[14:17]
	v_mfma_f32_16x16x32_bf16 v[50:53], v[178:181], v[196:199], 0
	v_mfma_f32_16x16x32_bf16 v[42:45], v[188:191], v[196:199], 0
	v_mfma_f32_16x16x32_bf16 v[34:37], v[178:181], v[204:207], 0
	v_mfma_f32_16x16x32_bf16 v[26:29], v[188:191], v[204:207], 0
	v_mfma_f32_16x16x32_bf16 v[18:21], v[178:181], v[212:215], 0
	v_mfma_f32_16x16x32_bf16 v[10:13], v[188:191], v[212:215], 0
	v_mfma_f32_16x16x32_bf16 v[6:9], v[178:181], v[220:223], 0
	v_mfma_f32_16x16x32_bf16 v[2:5], v[188:191], v[220:223], 0
	v_mfma_f32_16x16x32_bf16 v[50:53], v[184:187], v[200:203], v[50:53]
	v_mfma_f32_16x16x32_bf16 v[42:45], v[192:195], v[200:203], v[42:45]
	v_mfma_f32_16x16x32_bf16 v[34:37], v[184:187], v[208:211], v[34:37]
	v_mfma_f32_16x16x32_bf16 v[26:29], v[192:195], v[208:211], v[26:29]
	v_mfma_f32_16x16x32_bf16 v[18:21], v[184:187], v[216:219], v[18:21]
	v_mfma_f32_16x16x32_bf16 v[10:13], v[192:195], v[216:219], v[10:13]
	v_mfma_f32_16x16x32_bf16 v[6:9], v[184:187], v[224:227], v[6:9]
	v_mfma_f32_16x16x32_bf16 v[2:5], v[192:195], v[224:227], v[2:5]
	s_barrier
	s_setprio 0
	s_add_i32 s39, 0, 0x18000
	s_add_i32 s40, 0, 0x1c000
	v_add_u32_e32 v174, s39, v139
	v_add_u32_e32 v192, s40, v139
	ds_read_b128 v[160:163], v174
	ds_read_b128 v[164:167], v174 offset:1024
	ds_read_b128 v[168:171], v174 offset:2048
	ds_read_b128 v[174:177], v174 offset:3072
	ds_read_b128 v[178:181], v192
	ds_read_b128 v[184:187], v192 offset:1024
	ds_read_b128 v[188:191], v192 offset:2048
	ds_read_b128 v[192:195], v192 offset:3072
	s_add_u32 s12, s18, 0x44000
	s_addc_u32 s13, s19, 0
	s_mov_b32 m0, s25
	v_lshl_add_u64 v[236:237], s[12:13], 0, v[152:153]
	ds_read_b128 v[196:199], v173 offset:32768
	ds_read_b128 v[200:203], v173 offset:33792
	ds_read_b128 v[204:207], v173 offset:34816
	ds_read_b128 v[208:211], v173 offset:35840
	ds_read_b128 v[212:215], v173 offset:36864
	ds_read_b128 v[216:219], v173 offset:37888
	ds_read_b128 v[220:223], v173 offset:38912
	ds_read_b128 v[224:227], v173 offset:39936
	global_load_lds_dwordx4 v[236:237], off
	s_mov_b32 m0, s26
	v_lshl_add_u64 v[236:237], s[12:13], 0, v[132:133]
	global_load_lds_dwordx4 v[236:237], off
	s_waitcnt vmcnt(8)
	s_waitcnt lgkmcnt(0)
	s_setprio 1
	s_barrier
	v_mfma_f32_16x16x32_bf16 v[126:129], v[160:163], v[196:199], v[126:129]
	v_mfma_f32_16x16x32_bf16 v[122:125], v[168:171], v[196:199], v[122:125]
	v_mfma_f32_16x16x32_bf16 v[118:121], v[160:163], v[204:207], v[118:121]
	v_mfma_f32_16x16x32_bf16 v[110:113], v[168:171], v[204:207], v[110:113]
	v_mfma_f32_16x16x32_bf16 v[102:105], v[160:163], v[212:215], v[102:105]
	v_mfma_f32_16x16x32_bf16 v[94:97], v[168:171], v[212:215], v[94:97]
	v_mfma_f32_16x16x32_bf16 v[86:89], v[160:163], v[220:223], v[86:89]
	v_mfma_f32_16x16x32_bf16 v[78:81], v[168:171], v[220:223], v[78:81]
	v_mfma_f32_16x16x32_bf16 v[126:129], v[164:167], v[200:203], v[126:129]
	v_mfma_f32_16x16x32_bf16 v[122:125], v[174:177], v[200:203], v[122:125]
	v_mfma_f32_16x16x32_bf16 v[118:121], v[164:167], v[208:211], v[118:121]
	v_mfma_f32_16x16x32_bf16 v[110:113], v[174:177], v[208:211], v[110:113]
	v_mfma_f32_16x16x32_bf16 v[102:105], v[164:167], v[216:219], v[102:105]
	v_mfma_f32_16x16x32_bf16 v[94:97], v[174:177], v[216:219], v[94:97]
	v_mfma_f32_16x16x32_bf16 v[86:89], v[164:167], v[224:227], v[86:89]
	v_mfma_f32_16x16x32_bf16 v[78:81], v[174:177], v[224:227], v[78:81]
	v_mfma_f32_16x16x32_bf16 v[114:117], v[178:181], v[196:199], v[114:117]
	v_mfma_f32_16x16x32_bf16 v[106:109], v[188:191], v[196:199], v[106:109]
	v_mfma_f32_16x16x32_bf16 v[98:101], v[178:181], v[204:207], v[98:101]
	v_mfma_f32_16x16x32_bf16 v[90:93], v[188:191], v[204:207], v[90:93]
	v_mfma_f32_16x16x32_bf16 v[82:85], v[178:181], v[212:215], v[82:85]
	v_mfma_f32_16x16x32_bf16 v[74:77], v[188:191], v[212:215], v[74:77]
	v_mfma_f32_16x16x32_bf16 v[70:73], v[178:181], v[220:223], v[70:73]
	v_mfma_f32_16x16x32_bf16 v[66:69], v[188:191], v[220:223], v[66:69]
	v_mfma_f32_16x16x32_bf16 v[114:117], v[184:187], v[200:203], v[114:117]
	v_mfma_f32_16x16x32_bf16 v[106:109], v[192:195], v[200:203], v[106:109]
	v_mfma_f32_16x16x32_bf16 v[98:101], v[184:187], v[208:211], v[98:101]
	v_mfma_f32_16x16x32_bf16 v[90:93], v[192:195], v[208:211], v[90:93]
	v_mfma_f32_16x16x32_bf16 v[82:85], v[184:187], v[216:219], v[82:85]
	v_mfma_f32_16x16x32_bf16 v[74:77], v[192:195], v[216:219], v[74:77]
	v_mfma_f32_16x16x32_bf16 v[70:73], v[184:187], v[224:227], v[70:73]
	v_mfma_f32_16x16x32_bf16 v[66:69], v[192:195], v[224:227], v[66:69]
	s_barrier
; #define PG8_STAGE(bufoff, gbase, voff) do { _Pragma("unroll") for (int _i = 0; _i < 2; ++_i) \
;         __builtin_amdgcn_global_load_lds((const unsigned*)((const char*)(gbase) + (voff)[_i]), (LAS unsigned*)(lds + (bufoff) + ldsw + _i * 8192), 16, 0, 0); } while (0)
; #define PG8_LDA(dst, b, h) do { _Pragma("unroll") for (int m = 0; m < 4; ++m) _Pragma("unroll") for (int k = 0; k < 2; ++k) dst[m][k] = *(const LAS bf16x8*)(lds + PG8_SA(b, h) + aoff + m * 2048 + k * 1024); } while (0)
; #define PG8_LDB(dst, b, h) do { _Pragma("unroll") for (int n = 0; n < 2; ++n) _Pragma("unroll") for (int k = 0; k < 2; ++k) dst[n][k] = *(const LAS bf16x8*)(lds + PG8_SB(b, h) + boff + n * 2048 + k * 1024); } while (0)
; #define PG8_MMA(ai, bj, At, Bt) do { __builtin_amdgcn_s_setprio(1); _Pragma("unroll") for (int m = 0; m < 4; ++m) _Pragma("unroll") for (int n = 0; n < 2; ++n) _Pragma("unroll") for (int k = 0; k < 2; ++k) \
;         acc[ai][bj][m][n] = __builtin_amdgcn_mfma_f32_16x16x32_bf16(Bt[n][k], At[m][k], acc[ai][bj][m][n], 0, 0, 0); __builtin_amdgcn_s_setprio(0); } while (0)
; #define PG8_WAIT_V(n) asm volatile("s_waitcnt vmcnt(" #n ")" ::: "memory")
; #define PG8_WAIT_L(n) asm volatile("s_waitcnt lgkmcnt(" #n ")" ::: "memory")
; #define PG8_BAR __builtin_amdgcn_s_barrier()
; #define PG8_SCHED __builtin_amdgcn_sched_barrier(0)
; template <class Epi, bool ALIGN_EPI = PG8_ALIGN, bool SP2 = PG8_SP2>
; __device__ __forceinline__ void gemm_phase(LAS uchar* lds, const Gemm g, const StaticOrder& S, const Epi& E) {
;     ...
;             PG8_LDB(B0, 0, 0); PG8_LDB(B1, 0, 1); PG8_SCHED; PG8_LDA(At, 0, 0); PG8_STAGE(PG8_SA(1, 1), a1 + hstepA, voffA);
;             PG8_WAIT_V(8); PG8_WAIT_L(0); PG8_BAR; PG8_MMA(0, 0, At, B0); PG8_MMA(0, 1, At, B1); PG8_BAR; PG8_SCHED;
;     ...
;             PG8_LDA(At, 1, 1); PG8_STAGE(PG8_SB(1, 0), b3, voffB); PG8_STAGE(PG8_SB(1, 1), b3 + hstepB, voffB); PG8_STAGE(PG8_SA(1, 0), a3, voffA);
;             PG8_WAIT_V(8); PG8_WAIT_L(0); PG8_BAR; PG8_MMA(1, 0, At, B0); PG8_MMA(1, 1, At, B1); PG8_BAR; PG8_SCHED;
	s_setprio 0
	s_add_i32 s12, s39, s21
	v_lshl_add_u64 v[228:229], v[228:229], 0, s[84:85]
	s_mov_b32 m0, s12
	ds_read_b128 v[196:199], v173 offset:49152
	ds_read_b128 v[200:203], v173 offset:50176
	ds_read_b128 v[204:207], v173 offset:51200
	ds_read_b128 v[208:211], v173 offset:52224
	ds_read_b128 v[212:215], v173 offset:53248
	ds_read_b128 v[216:219], v173 offset:54272
	ds_read_b128 v[220:223], v173 offset:55296
	ds_read_b128 v[224:227], v173 offset:56320
	global_load_lds_dwordx4 v[228:229], off
	s_add_i32 m0, s12, 0x2000
	s_add_u32 s12, s16, 0x44080
	v_lshl_add_u64 v[228:229], v[230:231], 0, s[84:85]
	s_addc_u32 s13, s17, 0
	s_add_i32 s16, s40, s21
	global_load_lds_dwordx4 v[228:229], off
	s_mov_b32 m0, s16
	v_lshl_add_u64 v[228:229], s[12:13], 0, v[134:135]
	global_load_lds_dwordx4 v[228:229], off
	s_add_i32 m0, s16, 0x2000
	v_lshl_add_u64 v[228:229], s[12:13], 0, v[130:131]
	global_load_lds_dwordx4 v[228:229], off
	s_mov_b32 m0, s27
	v_lshl_add_u64 v[228:229], v[232:233], 0, s[84:85]
	global_load_lds_dwordx4 v[228:229], off
	s_mov_b32 m0, s28
	v_lshl_add_u64 v[228:229], v[234:235], 0, s[84:85]
	global_load_lds_dwordx4 v[228:229], off
	s_waitcnt vmcnt(8)
	s_waitcnt lgkmcnt(0)
	s_setprio 1
	s_barrier
	v_mfma_f32_16x16x32_bf16 v[62:65], v[160:163], v[196:199], v[62:65]
	v_mfma_f32_16x16x32_bf16 v[58:61], v[168:171], v[196:199], v[58:61]
	v_mfma_f32_16x16x32_bf16 v[54:57], v[160:163], v[204:207], v[54:57]
	v_mfma_f32_16x16x32_bf16 v[46:49], v[168:171], v[204:207], v[46:49]
	v_mfma_f32_16x16x32_bf16 v[38:41], v[160:163], v[212:215], v[38:41]
	v_mfma_f32_16x16x32_bf16 v[30:33], v[168:171], v[212:215], v[30:33]
	v_mfma_f32_16x16x32_bf16 v[22:25], v[160:163], v[220:223], v[22:25]
	v_mfma_f32_16x16x32_bf16 v[14:17], v[168:171], v[220:223], v[14:17]
	v_mfma_f32_16x16x32_bf16 v[62:65], v[164:167], v[200:203], v[62:65]
	v_mfma_f32_16x16x32_bf16 v[58:61], v[174:177], v[200:203], v[58:61]
	v_mfma_f32_16x16x32_bf16 v[54:57], v[164:167], v[208:211], v[54:57]
	v_mfma_f32_16x16x32_bf16 v[46:49], v[174:177], v[208:211], v[46:49]
	v_mfma_f32_16x16x32_bf16 v[38:41], v[164:167], v[216:219], v[38:41]
	v_mfma_f32_16x16x32_bf16 v[30:33], v[174:177], v[216:219], v[30:33]
	v_mfma_f32_16x16x32_bf16 v[22:25], v[164:167], v[224:227], v[22:25]
	v_mfma_f32_16x16x32_bf16 v[14:17], v[174:177], v[224:227], v[14:17]
	v_mfma_f32_16x16x32_bf16 v[50:53], v[178:181], v[196:199], v[50:53]
	v_mfma_f32_16x16x32_bf16 v[42:45], v[188:191], v[196:199], v[42:45]
	v_mfma_f32_16x16x32_bf16 v[34:37], v[178:181], v[204:207], v[34:37]
	v_mfma_f32_16x16x32_bf16 v[26:29], v[188:191], v[204:207], v[26:29]
	v_mfma_f32_16x16x32_bf16 v[18:21], v[178:181], v[212:215], v[18:21]
	v_mfma_f32_16x16x32_bf16 v[10:13], v[188:191], v[212:215], v[10:13]
	v_mfma_f32_16x16x32_bf16 v[6:9], v[178:181], v[220:223], v[6:9]
	v_mfma_f32_16x16x32_bf16 v[2:5], v[188:191], v[220:223], v[2:5]
	v_mfma_f32_16x16x32_bf16 v[50:53], v[184:187], v[200:203], v[50:53]
	v_mfma_f32_16x16x32_bf16 v[42:45], v[192:195], v[200:203], v[42:45]
	v_mfma_f32_16x16x32_bf16 v[34:37], v[184:187], v[208:211], v[34:37]
	v_mfma_f32_16x16x32_bf16 v[26:29], v[192:195], v[208:211], v[26:29]
	v_mfma_f32_16x16x32_bf16 v[18:21], v[184:187], v[216:219], v[18:21]
	v_mfma_f32_16x16x32_bf16 v[10:13], v[192:195], v[216:219], v[10:13]
	v_mfma_f32_16x16x32_bf16 v[6:9], v[184:187], v[224:227], v[6:9]
	v_mfma_f32_16x16x32_bf16 v[2:5], v[192:195], v[224:227], v[2:5]
	s_barrier
	s_setprio 0
	s_add_i32 s38, s38, 2
	s_add_u32 s36, s36, 0x100
	s_addc_u32 s37, s37, 0
	s_cmp_gt_u32 s38, 13
	s_mov_b64 s[12:13], s[14:15]
.LBB0_669:
	s_add_u32 s14, s12, 0x100
	s_addc_u32 s15, s13, 0
	s_add_i32 s39, 0, 0x10000
	s_cmp_eq_u32 s38, 12
	s_cselect_b32 s19, s5, s15
	s_cselect_b32 s18, s4, s14
	s_cselect_b32 s17, s11, s37
	s_cselect_b32 s16, s10, s36
	s_add_i32 s40, 0, 0x14000
	v_add_u32_e32 v174, s39, v139
	v_add_u32_e32 v192, s40, v139
	ds_read_b128 v[160:163], v174
	ds_read_b128 v[164:167], v174 offset:1024
	ds_read_b128 v[168:171], v174 offset:2048
	ds_read_b128 v[174:177], v174 offset:3072
	ds_read_b128 v[178:181], v192
	ds_read_b128 v[184:187], v192 offset:1024
	ds_read_b128 v[188:191], v192 offset:2048
	ds_read_b128 v[192:195], v192 offset:3072
	v_lshl_add_u64 v[228:229], s[12:13], 0, v[156:157]
	s_add_i32 m0, s23, 0xc000
	ds_read_b128 v[196:199], v173
	ds_read_b128 v[200:203], v173 offset:1024
	ds_read_b128 v[204:207], v173 offset:2048
	ds_read_b128 v[208:211], v173 offset:3072
	ds_read_b128 v[212:215], v173 offset:4096
	ds_read_b128 v[216:219], v173 offset:5120
	ds_read_b128 v[220:223], v173 offset:6144
	ds_read_b128 v[224:227], v173 offset:7168
	global_load_lds_dwordx4 v[228:229], off
	s_add_i32 m0, s23, 0xe000
	v_lshl_add_u64 v[228:229], s[12:13], 0, v[158:159]
	global_load_lds_dwordx4 v[228:229], off
	s_waitcnt vmcnt(8)
	s_waitcnt lgkmcnt(0)
	s_setprio 1
	s_barrier
; #define PG8_STAGE(bufoff, gbase, voff) do { _Pragma("unroll") for (int _i = 0; _i < 2; ++_i) \
;         __builtin_amdgcn_global_load_lds((const unsigned*)((const char*)(gbase) + (voff)[_i]), (LAS unsigned*)(lds + (bufoff) + ldsw + _i * 8192), 16, 0, 0); } while (0)
; #define PG8_LDA(dst, b, h) do { _Pragma("unroll") for (int m = 0; m < 4; ++m) _Pragma("unroll") for (int k = 0; k < 2; ++k) dst[m][k] = *(const LAS bf16x8*)(lds + PG8_SA(b, h) + aoff + m * 2048 + k * 1024); } while (0)
; #define PG8_MMA(ai, bj, At, Bt) do { __builtin_amdgcn_s_setprio(1); _Pragma("unroll") for (int m = 0; m < 4; ++m) _Pragma("unroll") for (int n = 0; n < 2; ++n) _Pragma("unroll") for (int k = 0; k < 2; ++k) \
;         acc[ai][bj][m][n] = __builtin_amdgcn_mfma_f32_16x16x32_bf16(Bt[n][k], At[m][k], acc[ai][bj][m][n], 0, 0, 0); __builtin_amdgcn_s_setprio(0); } while (0)
; #define PG8_WAIT_V(n) asm volatile("s_waitcnt vmcnt(" #n ")" ::: "memory")
; #define PG8_WAIT_L(n) asm volatile("s_waitcnt lgkmcnt(" #n ")" ::: "memory")
; #define PG8_BAR __builtin_amdgcn_s_barrier()
; #define PG8_SCHED __builtin_amdgcn_sched_barrier(0)
; template <class Epi, bool ALIGN_EPI = PG8_ALIGN, bool SP2 = PG8_SP2>
; __device__ __forceinline__ void gemm_phase(LAS uchar* lds, const Gemm g, const StaticOrder& S, const Epi& E) {
;     ...
;             PG8_WAIT_V(8); PG8_WAIT_L(0); PG8_BAR; PG8_MMA(0, 0, At, B0); PG8_MMA(0, 1, At, B1); PG8_BAR; PG8_SCHED;
;             PG8_LDA(At, 0, 1); PG8_STAGE(PG8_SB(0, 0), b2, voffB); PG8_STAGE(PG8_SB(0, 1), b2 + hstepB, voffB); PG8_STAGE(PG8_SA(0, 0), a2, voffA);
;             PG8_WAIT_V(8); PG8_WAIT_L(0); PG8_BAR; PG8_MMA(1, 0, At, B0); PG8_MMA(1, 1, At, B1); PG8_BAR; PG8_SCHED;
	v_mfma_f32_16x16x32_bf16 v[126:129], v[160:163], v[196:199], v[126:129]
	v_mfma_f32_16x16x32_bf16 v[122:125], v[168:171], v[196:199], v[122:125]
	v_mfma_f32_16x16x32_bf16 v[118:121], v[160:163], v[204:207], v[118:121]
	v_mfma_f32_16x16x32_bf16 v[110:113], v[168:171], v[204:207], v[110:113]
	v_mfma_f32_16x16x32_bf16 v[102:105], v[160:163], v[212:215], v[102:105]
	v_mfma_f32_16x16x32_bf16 v[94:97], v[168:171], v[212:215], v[94:97]
	v_mfma_f32_16x16x32_bf16 v[86:89], v[160:163], v[220:223], v[86:89]
	v_mfma_f32_16x16x32_bf16 v[78:81], v[168:171], v[220:223], v[78:81]
	v_mfma_f32_16x16x32_bf16 v[126:129], v[164:167], v[200:203], v[126:129]
	v_mfma_f32_16x16x32_bf16 v[122:125], v[174:177], v[200:203], v[122:125]
	v_mfma_f32_16x16x32_bf16 v[118:121], v[164:167], v[208:211], v[118:121]
	v_mfma_f32_16x16x32_bf16 v[110:113], v[174:177], v[208:211], v[110:113]
	v_mfma_f32_16x16x32_bf16 v[102:105], v[164:167], v[216:219], v[102:105]
	v_mfma_f32_16x16x32_bf16 v[94:97], v[174:177], v[216:219], v[94:97]
	v_mfma_f32_16x16x32_bf16 v[86:89], v[164:167], v[224:227], v[86:89]
	v_mfma_f32_16x16x32_bf16 v[78:81], v[174:177], v[224:227], v[78:81]
	v_mfma_f32_16x16x32_bf16 v[114:117], v[178:181], v[196:199], v[114:117]
	v_mfma_f32_16x16x32_bf16 v[106:109], v[188:191], v[196:199], v[106:109]
	v_mfma_f32_16x16x32_bf16 v[98:101], v[178:181], v[204:207], v[98:101]
	v_mfma_f32_16x16x32_bf16 v[90:93], v[188:191], v[204:207], v[90:93]
	v_mfma_f32_16x16x32_bf16 v[82:85], v[178:181], v[212:215], v[82:85]
	v_mfma_f32_16x16x32_bf16 v[74:77], v[188:191], v[212:215], v[74:77]
	v_mfma_f32_16x16x32_bf16 v[70:73], v[178:181], v[220:223], v[70:73]
	v_mfma_f32_16x16x32_bf16 v[66:69], v[188:191], v[220:223], v[66:69]
	v_mfma_f32_16x16x32_bf16 v[114:117], v[184:187], v[200:203], v[114:117]
	v_mfma_f32_16x16x32_bf16 v[106:109], v[192:195], v[200:203], v[106:109]
	v_mfma_f32_16x16x32_bf16 v[98:101], v[184:187], v[208:211], v[98:101]
	v_mfma_f32_16x16x32_bf16 v[90:93], v[192:195], v[208:211], v[90:93]
	v_mfma_f32_16x16x32_bf16 v[82:85], v[184:187], v[216:219], v[82:85]
	v_mfma_f32_16x16x32_bf16 v[74:77], v[192:195], v[216:219], v[74:77]
	v_mfma_f32_16x16x32_bf16 v[70:73], v[184:187], v[224:227], v[70:73]
	v_mfma_f32_16x16x32_bf16 v[66:69], v[192:195], v[224:227], v[66:69]
	s_barrier
	s_setprio 0
	s_add_i32 s12, s39, s21
	v_lshl_add_u64 v[228:229], s[16:17], 0, v[134:135]
	s_mov_b32 m0, s12
	ds_read_b128 v[196:199], v173 offset:16384
	ds_read_b128 v[200:203], v173 offset:17408
	ds_read_b128 v[204:207], v173 offset:18432
	ds_read_b128 v[208:211], v173 offset:19456
	ds_read_b128 v[212:215], v173 offset:20480
	ds_read_b128 v[216:219], v173 offset:21504
	ds_read_b128 v[220:223], v173 offset:22528
	ds_read_b128 v[224:227], v173 offset:23552
	global_load_lds_dwordx4 v[228:229], off
	s_add_i32 m0, s12, 0x2000
	s_add_u32 s12, s16, 0x44000
	v_lshl_add_u64 v[230:231], s[16:17], 0, v[130:131]
	s_addc_u32 s13, s17, 0
	s_add_i32 s39, s40, s21
	global_load_lds_dwordx4 v[230:231], off
	s_mov_b32 m0, s39
	v_lshl_add_u64 v[232:233], s[12:13], 0, v[134:135]
	global_load_lds_dwordx4 v[232:233], off
	s_add_i32 m0, s39, 0x2000
	v_lshl_add_u64 v[232:233], s[12:13], 0, v[130:131]
	global_load_lds_dwordx4 v[232:233], off
	s_mov_b32 m0, s23
	v_lshl_add_u64 v[232:233], s[18:19], 0, v[152:153]
	global_load_lds_dwordx4 v[232:233], off
	s_mov_b32 m0, s24
	v_lshl_add_u64 v[234:235], s[18:19], 0, v[132:133]
	global_load_lds_dwordx4 v[234:235], off
	s_waitcnt vmcnt(8)
	s_waitcnt lgkmcnt(0)
	s_setprio 1
	s_barrier
	v_mfma_f32_16x16x32_bf16 v[62:65], v[160:163], v[196:199], v[62:65]
	v_mfma_f32_16x16x32_bf16 v[58:61], v[168:171], v[196:199], v[58:61]
	v_mfma_f32_16x16x32_bf16 v[54:57], v[160:163], v[204:207], v[54:57]
	v_mfma_f32_16x16x32_bf16 v[46:49], v[168:171], v[204:207], v[46:49]
	v_mfma_f32_16x16x32_bf16 v[38:41], v[160:163], v[212:215], v[38:41]
	v_mfma_f32_16x16x32_bf16 v[30:33], v[168:171], v[212:215], v[30:33]
	v_mfma_f32_16x16x32_bf16 v[22:25], v[160:163], v[220:223], v[22:25]
	v_mfma_f32_16x16x32_bf16 v[14:17], v[168:171], v[220:223], v[14:17]
	v_mfma_f32_16x16x32_bf16 v[62:65], v[164:167], v[200:203], v[62:65]
	v_mfma_f32_16x16x32_bf16 v[58:61], v[174:177], v[200:203], v[58:61]
	v_mfma_f32_16x16x32_bf16 v[54:57], v[164:167], v[208:211], v[54:57]
	v_mfma_f32_16x16x32_bf16 v[46:49], v[174:177], v[208:211], v[46:49]
	v_mfma_f32_16x16x32_bf16 v[38:41], v[164:167], v[216:219], v[38:41]
	v_mfma_f32_16x16x32_bf16 v[30:33], v[174:177], v[216:219], v[30:33]
	v_mfma_f32_16x16x32_bf16 v[22:25], v[164:167], v[224:227], v[22:25]
	v_mfma_f32_16x16x32_bf16 v[14:17], v[174:177], v[224:227], v[14:17]
	v_mfma_f32_16x16x32_bf16 v[50:53], v[178:181], v[196:199], v[50:53]
	v_mfma_f32_16x16x32_bf16 v[42:45], v[188:191], v[196:199], v[42:45]
	v_mfma_f32_16x16x32_bf16 v[34:37], v[178:181], v[204:207], v[34:37]
	v_mfma_f32_16x16x32_bf16 v[26:29], v[188:191], v[204:207], v[26:29]
	v_mfma_f32_16x16x32_bf16 v[18:21], v[178:181], v[212:215], v[18:21]
	v_mfma_f32_16x16x32_bf16 v[10:13], v[188:191], v[212:215], v[10:13]
	v_mfma_f32_16x16x32_bf16 v[6:9], v[178:181], v[220:223], v[6:9]
	v_mfma_f32_16x16x32_bf16 v[2:5], v[188:191], v[220:223], v[2:5]
	v_mfma_f32_16x16x32_bf16 v[50:53], v[184:187], v[200:203], v[50:53]
	v_mfma_f32_16x16x32_bf16 v[42:45], v[192:195], v[200:203], v[42:45]
	v_mfma_f32_16x16x32_bf16 v[34:37], v[184:187], v[208:211], v[34:37]
	v_mfma_f32_16x16x32_bf16 v[26:29], v[192:195], v[208:211], v[26:29]
	v_mfma_f32_16x16x32_bf16 v[18:21], v[184:187], v[216:219], v[18:21]
	v_mfma_f32_16x16x32_bf16 v[10:13], v[192:195], v[216:219], v[10:13]
	v_mfma_f32_16x16x32_bf16 v[6:9], v[184:187], v[224:227], v[6:9]
	v_mfma_f32_16x16x32_bf16 v[2:5], v[192:195], v[224:227], v[2:5]
	s_barrier
; #define PG8_STAGE(bufoff, gbase, voff) do { _Pragma("unroll") for (int _i = 0; _i < 2; ++_i) \
;         __builtin_amdgcn_global_load_lds((const unsigned*)((const char*)(gbase) + (voff)[_i]), (LAS unsigned*)(lds + (bufoff) + ldsw + _i * 8192), 16, 0, 0); } while (0)
; #define PG8_LDA(dst, b, h) do { _Pragma("unroll") for (int m = 0; m < 4; ++m) _Pragma("unroll") for (int k = 0; k < 2; ++k) dst[m][k] = *(const LAS bf16x8*)(lds + PG8_SA(b, h) + aoff + m * 2048 + k * 1024); } while (0)
; #define PG8_LDB(dst, b, h) do { _Pragma("unroll") for (int n = 0; n < 2; ++n) _Pragma("unroll") for (int k = 0; k < 2; ++k) dst[n][k] = *(const LAS bf16x8*)(lds + PG8_SB(b, h) + boff + n * 2048 + k * 1024); } while (0)
; #define PG8_MMA(ai, bj, At, Bt) do { __builtin_amdgcn_s_setprio(1); _Pragma("unroll") for (int m = 0; m < 4; ++m) _Pragma("unroll") for (int n = 0; n < 2; ++n) _Pragma("unroll") for (int k = 0; k < 2; ++k) \
;         acc[ai][bj][m][n] = __builtin_amdgcn_mfma_f32_16x16x32_bf16(Bt[n][k], At[m][k], acc[ai][bj][m][n], 0, 0, 0); __builtin_amdgcn_s_setprio(0); } while (0)
; #define PG8_WAIT_V(n) asm volatile("s_waitcnt vmcnt(" #n ")" ::: "memory")
; #define PG8_WAIT_L(n) asm volatile("s_waitcnt lgkmcnt(" #n ")" ::: "memory")
; #define PG8_BAR __builtin_amdgcn_s_barrier()
; #define PG8_SCHED __builtin_amdgcn_sched_barrier(0)
; template <class Epi, bool ALIGN_EPI = PG8_ALIGN, bool SP2 = PG8_SP2>
; __device__ __forceinline__ void gemm_phase(LAS uchar* lds, const Gemm g, const StaticOrder& S, const Epi& E) {
;     ...
;             PG8_LDB(B0, 1, 0); PG8_LDB(B1, 1, 1); PG8_SCHED; PG8_LDA(At, 1, 0); PG8_STAGE(PG8_SA(0, 1), a2 + hstepA, voffA);
;             PG8_WAIT_V(8); PG8_WAIT_L(0); PG8_BAR; PG8_MMA(0, 0, At, B0); PG8_MMA(0, 1, At, B1); PG8_BAR; PG8_SCHED;
	s_setprio 0
	s_add_i32 s39, 0, 0x18000
	s_add_i32 s40, 0, 0x1c000
	v_add_u32_e32 v174, s39, v139
	v_add_u32_e32 v192, s40, v139
	ds_read_b128 v[160:163], v174
	ds_read_b128 v[164:167], v174 offset:1024
	ds_read_b128 v[168:171], v174 offset:2048
	ds_read_b128 v[174:177], v174 offset:3072
	ds_read_b128 v[178:181], v192
	ds_read_b128 v[184:187], v192 offset:1024
	ds_read_b128 v[188:191], v192 offset:2048
	ds_read_b128 v[192:195], v192 offset:3072
	s_add_u32 s12, s18, 0x44000
	s_addc_u32 s13, s19, 0
	s_mov_b32 m0, s25
	v_lshl_add_u64 v[236:237], s[12:13], 0, v[152:153]
	ds_read_b128 v[196:199], v173 offset:32768
	ds_read_b128 v[200:203], v173 offset:33792
	ds_read_b128 v[204:207], v173 offset:34816
	ds_read_b128 v[208:211], v173 offset:35840
	ds_read_b128 v[212:215], v173 offset:36864
	ds_read_b128 v[216:219], v173 offset:37888
	ds_read_b128 v[220:223], v173 offset:38912
	ds_read_b128 v[224:227], v173 offset:39936
	global_load_lds_dwordx4 v[236:237], off
	s_mov_b32 m0, s26
	v_lshl_add_u64 v[236:237], s[12:13], 0, v[132:133]
	global_load_lds_dwordx4 v[236:237], off
	s_waitcnt vmcnt(8)
	s_waitcnt lgkmcnt(0)
	s_setprio 1
	s_barrier
	v_mfma_f32_16x16x32_bf16 v[126:129], v[160:163], v[196:199], v[126:129]
	v_mfma_f32_16x16x32_bf16 v[122:125], v[168:171], v[196:199], v[122:125]
	v_mfma_f32_16x16x32_bf16 v[118:121], v[160:163], v[204:207], v[118:121]
	v_mfma_f32_16x16x32_bf16 v[110:113], v[168:171], v[204:207], v[110:113]
	v_mfma_f32_16x16x32_bf16 v[102:105], v[160:163], v[212:215], v[102:105]
	v_mfma_f32_16x16x32_bf16 v[94:97], v[168:171], v[212:215], v[94:97]
	v_mfma_f32_16x16x32_bf16 v[86:89], v[160:163], v[220:223], v[86:89]
	v_mfma_f32_16x16x32_bf16 v[78:81], v[168:171], v[220:223], v[78:81]
	v_mfma_f32_16x16x32_bf16 v[126:129], v[164:167], v[200:203], v[126:129]
	v_mfma_f32_16x16x32_bf16 v[122:125], v[174:177], v[200:203], v[122:125]
	v_mfma_f32_16x16x32_bf16 v[118:121], v[164:167], v[208:211], v[118:121]
	v_mfma_f32_16x16x32_bf16 v[110:113], v[174:177], v[208:211], v[110:113]
	v_mfma_f32_16x16x32_bf16 v[102:105], v[164:167], v[216:219], v[102:105]
	v_mfma_f32_16x16x32_bf16 v[94:97], v[174:177], v[216:219], v[94:97]
	v_mfma_f32_16x16x32_bf16 v[86:89], v[164:167], v[224:227], v[86:89]
	v_mfma_f32_16x16x32_bf16 v[78:81], v[174:177], v[224:227], v[78:81]
	v_mfma_f32_16x16x32_bf16 v[114:117], v[178:181], v[196:199], v[114:117]
	v_mfma_f32_16x16x32_bf16 v[106:109], v[188:191], v[196:199], v[106:109]
	v_mfma_f32_16x16x32_bf16 v[98:101], v[178:181], v[204:207], v[98:101]
	v_mfma_f32_16x16x32_bf16 v[90:93], v[188:191], v[204:207], v[90:93]
	v_mfma_f32_16x16x32_bf16 v[82:85], v[178:181], v[212:215], v[82:85]
	v_mfma_f32_16x16x32_bf16 v[74:77], v[188:191], v[212:215], v[74:77]
	v_mfma_f32_16x16x32_bf16 v[70:73], v[178:181], v[220:223], v[70:73]
	v_mfma_f32_16x16x32_bf16 v[66:69], v[188:191], v[220:223], v[66:69]
	v_mfma_f32_16x16x32_bf16 v[114:117], v[184:187], v[200:203], v[114:117]
	v_mfma_f32_16x16x32_bf16 v[106:109], v[192:195], v[200:203], v[106:109]
	v_mfma_f32_16x16x32_bf16 v[98:101], v[184:187], v[208:211], v[98:101]
	v_mfma_f32_16x16x32_bf16 v[90:93], v[192:195], v[208:211], v[90:93]
	v_mfma_f32_16x16x32_bf16 v[82:85], v[184:187], v[216:219], v[82:85]
	v_mfma_f32_16x16x32_bf16 v[74:77], v[192:195], v[216:219], v[74:77]
	v_mfma_f32_16x16x32_bf16 v[70:73], v[184:187], v[224:227], v[70:73]
	v_mfma_f32_16x16x32_bf16 v[66:69], v[192:195], v[224:227], v[66:69]
	s_barrier
; #define PG8_STAGE(bufoff, gbase, voff) do { _Pragma("unroll") for (int _i = 0; _i < 2; ++_i) \
;         __builtin_amdgcn_global_load_lds((const unsigned*)((const char*)(gbase) + (voff)[_i]), (LAS unsigned*)(lds + (bufoff) + ldsw + _i * 8192), 16, 0, 0); } while (0)
; #define PG8_LDA(dst, b, h) do { _Pragma("unroll") for (int m = 0; m < 4; ++m) _Pragma("unroll") for (int k = 0; k < 2; ++k) dst[m][k] = *(const LAS bf16x8*)(lds + PG8_SA(b, h) + aoff + m * 2048 + k * 1024); } while (0)
; #define PG8_MMA(ai, bj, At, Bt) do { __builtin_amdgcn_s_setprio(1); _Pragma("unroll") for (int m = 0; m < 4; ++m) _Pragma("unroll") for (int n = 0; n < 2; ++n) _Pragma("unroll") for (int k = 0; k < 2; ++k) \
;         acc[ai][bj][m][n] = __builtin_amdgcn_mfma_f32_16x16x32_bf16(Bt[n][k], At[m][k], acc[ai][bj][m][n], 0, 0, 0); __builtin_amdgcn_s_setprio(0); } while (0)
; #define PG8_WAIT_V(n) asm volatile("s_waitcnt vmcnt(" #n ")" ::: "memory")
; #define PG8_WAIT_L(n) asm volatile("s_waitcnt lgkmcnt(" #n ")" ::: "memory")
; #define PG8_BAR __builtin_amdgcn_s_barrier()
; #define PG8_SCHED __builtin_amdgcn_sched_barrier(0)
; template <class Epi, bool ALIGN_EPI = PG8_ALIGN, bool SP2 = PG8_SP2>
; __device__ __forceinline__ void gemm_phase(LAS uchar* lds, const Gemm g, const StaticOrder& S, const Epi& E) {
;     ...
;             PG8_LDA(At, 1, 1); PG8_STAGE(PG8_SB(1, 0), b3, voffB); PG8_STAGE(PG8_SB(1, 1), b3 + hstepB, voffB); PG8_STAGE(PG8_SA(1, 0), a3, voffA);
;             PG8_WAIT_V(8); PG8_WAIT_L(0); PG8_BAR; PG8_MMA(1, 0, At, B0); PG8_MMA(1, 1, At, B1); PG8_BAR; PG8_SCHED;
;     ...
;         if constexpr (ALIGN_EPI) { if (wr == 0) PG8_BAR; }
	s_setprio 0
	s_add_i32 s12, s39, s21
	v_lshl_add_u64 v[228:229], v[228:229], 0, s[84:85]
	s_mov_b32 m0, s12
	ds_read_b128 v[196:199], v173 offset:49152
	ds_read_b128 v[200:203], v173 offset:50176
	ds_read_b128 v[204:207], v173 offset:51200
	ds_read_b128 v[208:211], v173 offset:52224
	ds_read_b128 v[212:215], v173 offset:53248
	ds_read_b128 v[216:219], v173 offset:54272
	ds_read_b128 v[220:223], v173 offset:55296
	ds_read_b128 v[224:227], v173 offset:56320
	global_load_lds_dwordx4 v[228:229], off
	s_add_i32 m0, s12, 0x2000
	s_add_u32 s12, s16, 0x44080
	v_lshl_add_u64 v[228:229], v[230:231], 0, s[84:85]
	s_addc_u32 s13, s17, 0
	s_add_i32 s16, s40, s21
	global_load_lds_dwordx4 v[228:229], off
	s_mov_b32 m0, s16
	v_lshl_add_u64 v[228:229], s[12:13], 0, v[134:135]
	global_load_lds_dwordx4 v[228:229], off
	s_add_i32 m0, s16, 0x2000
	v_lshl_add_u64 v[228:229], s[12:13], 0, v[130:131]
	global_load_lds_dwordx4 v[228:229], off
	s_mov_b32 m0, s27
	v_lshl_add_u64 v[228:229], v[232:233], 0, s[84:85]
	global_load_lds_dwordx4 v[228:229], off
	s_mov_b32 m0, s28
	v_lshl_add_u64 v[228:229], v[234:235], 0, s[84:85]
	global_load_lds_dwordx4 v[228:229], off
	s_waitcnt vmcnt(8)
	s_waitcnt lgkmcnt(0)
	s_setprio 1
	s_barrier
	v_mfma_f32_16x16x32_bf16 v[62:65], v[160:163], v[196:199], v[62:65]
	v_mfma_f32_16x16x32_bf16 v[58:61], v[168:171], v[196:199], v[58:61]
	v_mfma_f32_16x16x32_bf16 v[54:57], v[160:163], v[204:207], v[54:57]
	v_mfma_f32_16x16x32_bf16 v[46:49], v[168:171], v[204:207], v[46:49]
	v_mfma_f32_16x16x32_bf16 v[38:41], v[160:163], v[212:215], v[38:41]
	v_mfma_f32_16x16x32_bf16 v[30:33], v[168:171], v[212:215], v[30:33]
	v_mfma_f32_16x16x32_bf16 v[22:25], v[160:163], v[220:223], v[22:25]
	v_mfma_f32_16x16x32_bf16 v[14:17], v[168:171], v[220:223], v[14:17]
	v_mfma_f32_16x16x32_bf16 v[62:65], v[164:167], v[200:203], v[62:65]
	v_mfma_f32_16x16x32_bf16 v[58:61], v[174:177], v[200:203], v[58:61]
	v_mfma_f32_16x16x32_bf16 v[54:57], v[164:167], v[208:211], v[54:57]
	v_mfma_f32_16x16x32_bf16 v[46:49], v[174:177], v[208:211], v[46:49]
	v_mfma_f32_16x16x32_bf16 v[38:41], v[164:167], v[216:219], v[38:41]
	v_mfma_f32_16x16x32_bf16 v[30:33], v[174:177], v[216:219], v[30:33]
	v_mfma_f32_16x16x32_bf16 v[22:25], v[164:167], v[224:227], v[22:25]
	v_mfma_f32_16x16x32_bf16 v[14:17], v[174:177], v[224:227], v[14:17]
	v_mfma_f32_16x16x32_bf16 v[50:53], v[178:181], v[196:199], v[50:53]
	v_mfma_f32_16x16x32_bf16 v[42:45], v[188:191], v[196:199], v[42:45]
	v_mfma_f32_16x16x32_bf16 v[34:37], v[178:181], v[204:207], v[34:37]
	v_mfma_f32_16x16x32_bf16 v[26:29], v[188:191], v[204:207], v[26:29]
	v_mfma_f32_16x16x32_bf16 v[18:21], v[178:181], v[212:215], v[18:21]
	v_mfma_f32_16x16x32_bf16 v[10:13], v[188:191], v[212:215], v[10:13]
	v_mfma_f32_16x16x32_bf16 v[6:9], v[178:181], v[220:223], v[6:9]
	v_mfma_f32_16x16x32_bf16 v[2:5], v[188:191], v[220:223], v[2:5]
	v_mfma_f32_16x16x32_bf16 v[50:53], v[184:187], v[200:203], v[50:53]
	v_mfma_f32_16x16x32_bf16 v[42:45], v[192:195], v[200:203], v[42:45]
	v_mfma_f32_16x16x32_bf16 v[34:37], v[184:187], v[208:211], v[34:37]
	v_mfma_f32_16x16x32_bf16 v[26:29], v[192:195], v[208:211], v[26:29]
	v_mfma_f32_16x16x32_bf16 v[18:21], v[184:187], v[216:219], v[18:21]
	v_mfma_f32_16x16x32_bf16 v[10:13], v[192:195], v[216:219], v[10:13]
	v_mfma_f32_16x16x32_bf16 v[6:9], v[184:187], v[224:227], v[6:9]
	v_mfma_f32_16x16x32_bf16 v[2:5], v[192:195], v[224:227], v[2:5]
	s_barrier
	s_setprio 0
	s_add_i32 s38, s38, 2
	s_add_u32 s36, s36, 0x100
	s_addc_u32 s37, s37, 0
	s_cmp_gt_u32 s38, 13
	s_mov_b64 s[12:13], s[14:15]
	s_cbranch_scc0 .LBB0_669
	s_and_b64 vcc, exec, s[8:9]
	s_cbranch_vccz .LBB0_672
	s_barrier

; #define PG8_STAGE(bufoff, gbase, voff) do { _Pragma("unroll") for (int _i = 0; _i < 2; ++_i) \
;         __builtin_amdgcn_global_load_lds((const unsigned*)((const char*)(gbase) + (voff)[_i]), (LAS unsigned*)(lds + (bufoff) + ldsw + _i * 8192), 16, 0, 0); } while (0)
; #define PG8_LDA(dst, b, h) do { _Pragma("unroll") for (int m = 0; m < 4; ++m) _Pragma("unroll") for (int k = 0; k < 2; ++k) dst[m][k] = *(const LAS bf16x8*)(lds + PG8_SA(b, h) + aoff + m * 2048 + k * 1024); } while (0)
; #define PG8_LDB(dst, b, h) do { _Pragma("unroll") for (int n = 0; n < 2; ++n) _Pragma("unroll") for (int k = 0; k < 2; ++k) dst[n][k] = *(const LAS bf16x8*)(lds + PG8_SB(b, h) + boff + n * 2048 + k * 1024); } while (0)
; #define PG8_MMA(ai, bj, At, Bt) do { __builtin_amdgcn_s_setprio(1); _Pragma("unroll") for (int m = 0; m < 4; ++m) _Pragma("unroll") for (int n = 0; n < 2; ++n) _Pragma("unroll") for (int k = 0; k < 2; ++k) \
;         acc[ai][bj][m][n] = __builtin_amdgcn_mfma_f32_16x16x32_bf16(Bt[n][k], At[m][k], acc[ai][bj][m][n], 0, 0, 0); __builtin_amdgcn_s_setprio(0); } while (0)
; #define PG8_WAIT_V(n) asm volatile("s_waitcnt vmcnt(" #n ")" ::: "memory")
; #define PG8_WAIT_L(n) asm volatile("s_waitcnt lgkmcnt(" #n ")" ::: "memory")
; #define PG8_BAR __builtin_amdgcn_s_barrier()
; #define PG8_SCHED __builtin_amdgcn_sched_barrier(0)
; template <class Epi, bool ALIGN_EPI = PG8_ALIGN, bool SP2 = PG8_SP2>
; __device__ __forceinline__ void gemm_phase(LAS uchar* lds, const Gemm g, const StaticOrder& S, const Epi& E) {
;     ...
;             PG8_LDB(B0, 0, 0); PG8_LDB(B1, 0, 1); PG8_SCHED; PG8_LDA(At, 0, 0); PG8_STAGE(PG8_SA(1, 1), a1 + hstepA, voffA);
;             PG8_WAIT_V(8); PG8_WAIT_L(0); PG8_BAR; PG8_MMA(0, 0, At, B0); PG8_MMA(0, 1, At, B1); PG8_BAR; PG8_SCHED;
;             PG8_LDA(At, 0, 1); PG8_STAGE(PG8_SB(0, 0), b2, voffB); PG8_STAGE(PG8_SB(0, 1), b2 + hstepB, voffB); PG8_STAGE(PG8_SA(0, 0), a2, voffA);
;             PG8_WAIT_V(8); PG8_WAIT_L(0); PG8_BAR; PG8_MMA(1, 0, At, B0); PG8_MMA(1, 1, At, B1); PG8_BAR; PG8_SCHED;
;     ...
; #pragma unroll
;         for (int a = 0; a < 2; ++a)
; #pragma unroll
;             for (int b = 0; b < 2; ++b)
; #pragma unroll
;                 for (int m = 0; m < 4; ++m)
; #pragma unroll
;                     for (int n = 0; n < 2; ++n) acc[a][b][m][n] = (f32x4){0.f, 0.f, 0.f, 0.f};
.LBB0_836:
	s_add_u32 s36, s14, 0x100
	s_addc_u32 s37, s15, 0
	s_mov_b32 s38, -2
	s_add_u32 s14, s12, 0x100
	s_addc_u32 s15, s13, 0
	s_add_i32 s39, 0, 0x10000
	s_cmp_eq_u32 s38, 12
	s_cselect_b32 s19, s5, s15
	s_cselect_b32 s18, s4, s14
	s_cselect_b32 s17, s11, s37
	s_cselect_b32 s16, s10, s36
	s_add_i32 s40, 0, 0x14000
	v_add_u32_e32 v174, s39, v139
	v_add_u32_e32 v192, s40, v139
	ds_read_b128 v[160:163], v174
	ds_read_b128 v[166:169], v174 offset:1024
	ds_read_b128 v[170:173], v174 offset:2048
	ds_read_b128 v[174:177], v174 offset:3072
	ds_read_b128 v[178:181], v192
	ds_read_b128 v[184:187], v192 offset:1024
	ds_read_b128 v[188:191], v192 offset:2048
	ds_read_b128 v[192:195], v192 offset:3072
	v_lshl_add_u64 v[228:229], s[12:13], 0, v[156:157]
	s_add_i32 m0, s23, 0xc000
	ds_read_b128 v[196:199], v165
	ds_read_b128 v[200:203], v165 offset:1024
	ds_read_b128 v[204:207], v165 offset:2048
	ds_read_b128 v[208:211], v165 offset:3072
	ds_read_b128 v[212:215], v165 offset:4096
	ds_read_b128 v[216:219], v165 offset:5120
	ds_read_b128 v[220:223], v165 offset:6144
	ds_read_b128 v[224:227], v165 offset:7168
	global_load_lds_dwordx4 v[228:229], off
	s_add_i32 m0, s23, 0xe000
	v_lshl_add_u64 v[228:229], s[12:13], 0, v[158:159]
	global_load_lds_dwordx4 v[228:229], off
	s_waitcnt vmcnt(8)
	s_waitcnt lgkmcnt(0)
	s_setprio 1
	s_barrier
	v_mfma_f32_16x16x32_bf16 v[126:129], v[160:163], v[196:199], 0
	v_mfma_f32_16x16x32_bf16 v[122:125], v[170:173], v[196:199], 0
	v_mfma_f32_16x16x32_bf16 v[118:121], v[160:163], v[204:207], 0
	v_mfma_f32_16x16x32_bf16 v[110:113], v[170:173], v[204:207], 0
	v_mfma_f32_16x16x32_bf16 v[102:105], v[160:163], v[212:215], 0
	v_mfma_f32_16x16x32_bf16 v[94:97], v[170:173], v[212:215], 0
	v_mfma_f32_16x16x32_bf16 v[86:89], v[160:163], v[220:223], 0
	v_mfma_f32_16x16x32_bf16 v[78:81], v[170:173], v[220:223], 0
	v_mfma_f32_16x16x32_bf16 v[126:129], v[166:169], v[200:203], v[126:129]
	v_mfma_f32_16x16x32_bf16 v[122:125], v[174:177], v[200:203], v[122:125]
	v_mfma_f32_16x16x32_bf16 v[118:121], v[166:169], v[208:211], v[118:121]
	v_mfma_f32_16x16x32_bf16 v[110:113], v[174:177], v[208:211], v[110:113]
	v_mfma_f32_16x16x32_bf16 v[102:105], v[166:169], v[216:219], v[102:105]
	v_mfma_f32_16x16x32_bf16 v[94:97], v[174:177], v[216:219], v[94:97]
	v_mfma_f32_16x16x32_bf16 v[86:89], v[166:169], v[224:227], v[86:89]
	v_mfma_f32_16x16x32_bf16 v[78:81], v[174:177], v[224:227], v[78:81]
	v_mfma_f32_16x16x32_bf16 v[114:117], v[178:181], v[196:199], 0
	v_mfma_f32_16x16x32_bf16 v[106:109], v[188:191], v[196:199], 0
	v_mfma_f32_16x16x32_bf16 v[98:101], v[178:181], v[204:207], 0
	v_mfma_f32_16x16x32_bf16 v[90:93], v[188:191], v[204:207], 0
	v_mfma_f32_16x16x32_bf16 v[82:85], v[178:181], v[212:215], 0
	v_mfma_f32_16x16x32_bf16 v[74:77], v[188:191], v[212:215], 0
	v_mfma_f32_16x16x32_bf16 v[70:73], v[178:181], v[220:223], 0
	v_mfma_f32_16x16x32_bf16 v[66:69], v[188:191], v[220:223], 0
	v_mfma_f32_16x16x32_bf16 v[114:117], v[184:187], v[200:203], v[114:117]
	v_mfma_f32_16x16x32_bf16 v[106:109], v[192:195], v[200:203], v[106:109]
	v_mfma_f32_16x16x32_bf16 v[98:101], v[184:187], v[208:211], v[98:101]
	v_mfma_f32_16x16x32_bf16 v[90:93], v[192:195], v[208:211], v[90:93]
	v_mfma_f32_16x16x32_bf16 v[82:85], v[184:187], v[216:219], v[82:85]
	v_mfma_f32_16x16x32_bf16 v[74:77], v[192:195], v[216:219], v[74:77]
	v_mfma_f32_16x16x32_bf16 v[70:73], v[184:187], v[224:227], v[70:73]
	v_mfma_f32_16x16x32_bf16 v[66:69], v[192:195], v[224:227], v[66:69]
	s_barrier
	s_setprio 0
	s_add_i32 s12, s39, s22
	v_lshl_add_u64 v[228:229], s[16:17], 0, v[132:133]
	s_mov_b32 m0, s12
	ds_read_b128 v[196:199], v165 offset:16384
	ds_read_b128 v[200:203], v165 offset:17408
	ds_read_b128 v[204:207], v165 offset:18432
	ds_read_b128 v[208:211], v165 offset:19456
	ds_read_b128 v[212:215], v165 offset:20480
	ds_read_b128 v[216:219], v165 offset:21504
	ds_read_b128 v[220:223], v165 offset:22528
	ds_read_b128 v[224:227], v165 offset:23552
	global_load_lds_dwordx4 v[228:229], off
	s_add_i32 m0, s12, 0x2000
	s_add_u32 s12, s16, 0x44000
	v_lshl_add_u64 v[230:231], s[16:17], 0, v[152:153]
	s_addc_u32 s13, s17, 0
	s_add_i32 s39, s40, s22
	global_load_lds_dwordx4 v[230:231], off
	s_mov_b32 m0, s39
	v_lshl_add_u64 v[232:233], s[12:13], 0, v[132:133]
	global_load_lds_dwordx4 v[232:233], off
	s_add_i32 m0, s39, 0x2000
	v_lshl_add_u64 v[232:233], s[12:13], 0, v[152:153]
	global_load_lds_dwordx4 v[232:233], off
	s_mov_b32 m0, s23
	v_lshl_add_u64 v[232:233], s[18:19], 0, v[130:131]
	global_load_lds_dwordx4 v[232:233], off
	s_mov_b32 m0, s24
	v_lshl_add_u64 v[234:235], s[18:19], 0, v[134:135]
	global_load_lds_dwordx4 v[234:235], off
	s_waitcnt vmcnt(8)
	s_waitcnt lgkmcnt(0)
	s_setprio 1
	s_barrier
; #define PG8_STAGE(bufoff, gbase, voff) do { _Pragma("unroll") for (int _i = 0; _i < 2; ++_i) \
;         __builtin_amdgcn_global_load_lds((const unsigned*)((const char*)(gbase) + (voff)[_i]), (LAS unsigned*)(lds + (bufoff) + ldsw + _i * 8192), 16, 0, 0); } while (0)
; #define PG8_LDA(dst, b, h) do { _Pragma("unroll") for (int m = 0; m < 4; ++m) _Pragma("unroll") for (int k = 0; k < 2; ++k) dst[m][k] = *(const LAS bf16x8*)(lds + PG8_SA(b, h) + aoff + m * 2048 + k * 1024); } while (0)
; #define PG8_LDB(dst, b, h) do { _Pragma("unroll") for (int n = 0; n < 2; ++n) _Pragma("unroll") for (int k = 0; k < 2; ++k) dst[n][k] = *(const LAS bf16x8*)(lds + PG8_SB(b, h) + boff + n * 2048 + k * 1024); } while (0)
; #define PG8_MMA(ai, bj, At, Bt) do { __builtin_amdgcn_s_setprio(1); _Pragma("unroll") for (int m = 0; m < 4; ++m) _Pragma("unroll") for (int n = 0; n < 2; ++n) _Pragma("unroll") for (int k = 0; k < 2; ++k) \
;         acc[ai][bj][m][n] = __builtin_amdgcn_mfma_f32_16x16x32_bf16(Bt[n][k], At[m][k], acc[ai][bj][m][n], 0, 0, 0); __builtin_amdgcn_s_setprio(0); } while (0)
; #define PG8_WAIT_V(n) asm volatile("s_waitcnt vmcnt(" #n ")" ::: "memory")
; #define PG8_WAIT_L(n) asm volatile("s_waitcnt lgkmcnt(" #n ")" ::: "memory")
; #define PG8_BAR __builtin_amdgcn_s_barrier()
; #define PG8_SCHED __builtin_amdgcn_sched_barrier(0)
; template <class Epi, bool ALIGN_EPI = PG8_ALIGN, bool SP2 = PG8_SP2>
; __device__ __forceinline__ void gemm_phase(LAS uchar* lds, const Gemm g, const StaticOrder& S, const Epi& E) {
;     ...
;             PG8_WAIT_V(8); PG8_WAIT_L(0); PG8_BAR; PG8_MMA(1, 0, At, B0); PG8_MMA(1, 1, At, B1); PG8_BAR; PG8_SCHED;
;             PG8_LDB(B0, 1, 0); PG8_LDB(B1, 1, 1); PG8_SCHED; PG8_LDA(At, 1, 0); PG8_STAGE(PG8_SA(0, 1), a2 + hstepA, voffA);
;             PG8_WAIT_V(8); PG8_WAIT_L(0); PG8_BAR; PG8_MMA(0, 0, At, B0); PG8_MMA(0, 1, At, B1); PG8_BAR; PG8_SCHED;
	v_mfma_f32_16x16x32_bf16 v[62:65], v[160:163], v[196:199], 0
	v_mfma_f32_16x16x32_bf16 v[58:61], v[170:173], v[196:199], 0
	v_mfma_f32_16x16x32_bf16 v[54:57], v[160:163], v[204:207], 0
	v_mfma_f32_16x16x32_bf16 v[46:49], v[170:173], v[204:207], 0
	v_mfma_f32_16x16x32_bf16 v[38:41], v[160:163], v[212:215], 0
	v_mfma_f32_16x16x32_bf16 v[30:33], v[170:173], v[212:215], 0
	v_mfma_f32_16x16x32_bf16 v[22:25], v[160:163], v[220:223], 0
	v_mfma_f32_16x16x32_bf16 v[14:17], v[170:173], v[220:223], 0
	v_mfma_f32_16x16x32_bf16 v[62:65], v[166:169], v[200:203], v[62:65]
	v_mfma_f32_16x16x32_bf16 v[58:61], v[174:177], v[200:203], v[58:61]
	v_mfma_f32_16x16x32_bf16 v[54:57], v[166:169], v[208:211], v[54:57]
	v_mfma_f32_16x16x32_bf16 v[46:49], v[174:177], v[208:211], v[46:49]
	v_mfma_f32_16x16x32_bf16 v[38:41], v[166:169], v[216:219], v[38:41]
	v_mfma_f32_16x16x32_bf16 v[30:33], v[174:177], v[216:219], v[30:33]
	v_mfma_f32_16x16x32_bf16 v[22:25], v[166:169], v[224:227], v[22:25]
	v_mfma_f32_16x16x32_bf16 v[14:17], v[174:177], v[224:227], v[14:17]
	v_mfma_f32_16x16x32_bf16 v[50:53], v[178:181], v[196:199], 0
	v_mfma_f32_16x16x32_bf16 v[42:45], v[188:191], v[196:199], 0
	v_mfma_f32_16x16x32_bf16 v[34:37], v[178:181], v[204:207], 0
	v_mfma_f32_16x16x32_bf16 v[26:29], v[188:191], v[204:207], 0
	v_mfma_f32_16x16x32_bf16 v[18:21], v[178:181], v[212:215], 0
	v_mfma_f32_16x16x32_bf16 v[10:13], v[188:191], v[212:215], 0
	v_mfma_f32_16x16x32_bf16 v[6:9], v[178:181], v[220:223], 0
	v_mfma_f32_16x16x32_bf16 v[2:5], v[188:191], v[220:223], 0
	v_mfma_f32_16x16x32_bf16 v[50:53], v[184:187], v[200:203], v[50:53]
	v_mfma_f32_16x16x32_bf16 v[42:45], v[192:195], v[200:203], v[42:45]
	v_mfma_f32_16x16x32_bf16 v[34:37], v[184:187], v[208:211], v[34:37]
	v_mfma_f32_16x16x32_bf16 v[26:29], v[192:195], v[208:211], v[26:29]
	v_mfma_f32_16x16x32_bf16 v[18:21], v[184:187], v[216:219], v[18:21]
	v_mfma_f32_16x16x32_bf16 v[10:13], v[192:195], v[216:219], v[10:13]
	v_mfma_f32_16x16x32_bf16 v[6:9], v[184:187], v[224:227], v[6:9]
	v_mfma_f32_16x16x32_bf16 v[2:5], v[192:195], v[224:227], v[2:5]
	s_barrier
	s_setprio 0
	s_add_i32 s39, 0, 0x18000
	s_add_i32 s40, 0, 0x1c000
	v_add_u32_e32 v174, s39, v139
	v_add_u32_e32 v192, s40, v139
	ds_read_b128 v[160:163], v174
	ds_read_b128 v[166:169], v174 offset:1024
	ds_read_b128 v[170:173], v174 offset:2048
	ds_read_b128 v[174:177], v174 offset:3072
	ds_read_b128 v[178:181], v192
	ds_read_b128 v[184:187], v192 offset:1024
	ds_read_b128 v[188:191], v192 offset:2048
	ds_read_b128 v[192:195], v192 offset:3072
	s_add_u32 s12, s18, 0x44000
	s_addc_u32 s13, s19, 0
	s_mov_b32 m0, s25
	v_lshl_add_u64 v[236:237], s[12:13], 0, v[130:131]
	ds_read_b128 v[196:199], v165 offset:32768
	ds_read_b128 v[200:203], v165 offset:33792
	ds_read_b128 v[204:207], v165 offset:34816
	ds_read_b128 v[208:211], v165 offset:35840
	ds_read_b128 v[212:215], v165 offset:36864
	ds_read_b128 v[216:219], v165 offset:37888
	ds_read_b128 v[220:223], v165 offset:38912
	ds_read_b128 v[224:227], v165 offset:39936
	global_load_lds_dwordx4 v[236:237], off
	s_mov_b32 m0, s26
	v_lshl_add_u64 v[236:237], s[12:13], 0, v[134:135]
	global_load_lds_dwordx4 v[236:237], off
	s_waitcnt vmcnt(8)
	s_waitcnt lgkmcnt(0)
	s_setprio 1
	s_barrier
	v_mfma_f32_16x16x32_bf16 v[126:129], v[160:163], v[196:199], v[126:129]
	v_mfma_f32_16x16x32_bf16 v[122:125], v[170:173], v[196:199], v[122:125]
	v_mfma_f32_16x16x32_bf16 v[118:121], v[160:163], v[204:207], v[118:121]
	v_mfma_f32_16x16x32_bf16 v[110:113], v[170:173], v[204:207], v[110:113]
	v_mfma_f32_16x16x32_bf16 v[102:105], v[160:163], v[212:215], v[102:105]
	v_mfma_f32_16x16x32_bf16 v[94:97], v[170:173], v[212:215], v[94:97]
	v_mfma_f32_16x16x32_bf16 v[86:89], v[160:163], v[220:223], v[86:89]
	v_mfma_f32_16x16x32_bf16 v[78:81], v[170:173], v[220:223], v[78:81]
	v_mfma_f32_16x16x32_bf16 v[126:129], v[166:169], v[200:203], v[126:129]
	v_mfma_f32_16x16x32_bf16 v[122:125], v[174:177], v[200:203], v[122:125]
	v_mfma_f32_16x16x32_bf16 v[118:121], v[166:169], v[208:211], v[118:121]
	v_mfma_f32_16x16x32_bf16 v[110:113], v[174:177], v[208:211], v[110:113]
	v_mfma_f32_16x16x32_bf16 v[102:105], v[166:169], v[216:219], v[102:105]
	v_mfma_f32_16x16x32_bf16 v[94:97], v[174:177], v[216:219], v[94:97]
	v_mfma_f32_16x16x32_bf16 v[86:89], v[166:169], v[224:227], v[86:89]
	v_mfma_f32_16x16x32_bf16 v[78:81], v[174:177], v[224:227], v[78:81]
	v_mfma_f32_16x16x32_bf16 v[114:117], v[178:181], v[196:199], v[114:117]
	v_mfma_f32_16x16x32_bf16 v[106:109], v[188:191], v[196:199], v[106:109]
	v_mfma_f32_16x16x32_bf16 v[98:101], v[178:181], v[204:207], v[98:101]
	v_mfma_f32_16x16x32_bf16 v[90:93], v[188:191], v[204:207], v[90:93]
	v_mfma_f32_16x16x32_bf16 v[82:85], v[178:181], v[212:215], v[82:85]
	v_mfma_f32_16x16x32_bf16 v[74:77], v[188:191], v[212:215], v[74:77]
	v_mfma_f32_16x16x32_bf16 v[70:73], v[178:181], v[220:223], v[70:73]
	v_mfma_f32_16x16x32_bf16 v[66:69], v[188:191], v[220:223], v[66:69]
	v_mfma_f32_16x16x32_bf16 v[114:117], v[184:187], v[200:203], v[114:117]
	v_mfma_f32_16x16x32_bf16 v[106:109], v[192:195], v[200:203], v[106:109]
	v_mfma_f32_16x16x32_bf16 v[98:101], v[184:187], v[208:211], v[98:101]
	v_mfma_f32_16x16x32_bf16 v[90:93], v[192:195], v[208:211], v[90:93]
	v_mfma_f32_16x16x32_bf16 v[82:85], v[184:187], v[216:219], v[82:85]
	v_mfma_f32_16x16x32_bf16 v[74:77], v[192:195], v[216:219], v[74:77]
	v_mfma_f32_16x16x32_bf16 v[70:73], v[184:187], v[224:227], v[70:73]
	v_mfma_f32_16x16x32_bf16 v[66:69], v[192:195], v[224:227], v[66:69]
	s_barrier
; #define PG8_STAGE(bufoff, gbase, voff) do { _Pragma("unroll") for (int _i = 0; _i < 2; ++_i) \
;         __builtin_amdgcn_global_load_lds((const unsigned*)((const char*)(gbase) + (voff)[_i]), (LAS unsigned*)(lds + (bufoff) + ldsw + _i * 8192), 16, 0, 0); } while (0)
; #define PG8_LDA(dst, b, h) do { _Pragma("unroll") for (int m = 0; m < 4; ++m) _Pragma("unroll") for (int k = 0; k < 2; ++k) dst[m][k] = *(const LAS bf16x8*)(lds + PG8_SA(b, h) + aoff + m * 2048 + k * 1024); } while (0)
; #define PG8_LDB(dst, b, h) do { _Pragma("unroll") for (int n = 0; n < 2; ++n) _Pragma("unroll") for (int k = 0; k < 2; ++k) dst[n][k] = *(const LAS bf16x8*)(lds + PG8_SB(b, h) + boff + n * 2048 + k * 1024); } while (0)
; #define PG8_MMA(ai, bj, At, Bt) do { __builtin_amdgcn_s_setprio(1); _Pragma("unroll") for (int m = 0; m < 4; ++m) _Pragma("unroll") for (int n = 0; n < 2; ++n) _Pragma("unroll") for (int k = 0; k < 2; ++k) \
;         acc[ai][bj][m][n] = __builtin_amdgcn_mfma_f32_16x16x32_bf16(Bt[n][k], At[m][k], acc[ai][bj][m][n], 0, 0, 0); __builtin_amdgcn_s_setprio(0); } while (0)
; #define PG8_WAIT_V(n) asm volatile("s_waitcnt vmcnt(" #n ")" ::: "memory")
; #define PG8_WAIT_L(n) asm volatile("s_waitcnt lgkmcnt(" #n ")" ::: "memory")
; #define PG8_BAR __builtin_amdgcn_s_barrier()
; #define PG8_SCHED __builtin_amdgcn_sched_barrier(0)
; template <class Epi, bool ALIGN_EPI = PG8_ALIGN, bool SP2 = PG8_SP2>
; __device__ __forceinline__ void gemm_phase(LAS uchar* lds, const Gemm g, const StaticOrder& S, const Epi& E) {
;     ...
;             PG8_LDB(B0, 0, 0); PG8_LDB(B1, 0, 1); PG8_SCHED; PG8_LDA(At, 0, 0); PG8_STAGE(PG8_SA(1, 1), a1 + hstepA, voffA);
;             PG8_WAIT_V(8); PG8_WAIT_L(0); PG8_BAR; PG8_MMA(0, 0, At, B0); PG8_MMA(0, 1, At, B1); PG8_BAR; PG8_SCHED;
;     ...
;             PG8_LDA(At, 1, 1); PG8_STAGE(PG8_SB(1, 0), b3, voffB); PG8_STAGE(PG8_SB(1, 1), b3 + hstepB, voffB); PG8_STAGE(PG8_SA(1, 0), a3, voffA);
;             PG8_WAIT_V(8); PG8_WAIT_L(0); PG8_BAR; PG8_MMA(1, 0, At, B0); PG8_MMA(1, 1, At, B1); PG8_BAR; PG8_SCHED;
	s_setprio 0
	s_add_i32 s12, s39, s22
	v_lshl_add_u64 v[228:229], v[228:229], 0, s[84:85]
	s_mov_b32 m0, s12
	ds_read_b128 v[196:199], v165 offset:49152
	ds_read_b128 v[200:203], v165 offset:50176
	ds_read_b128 v[204:207], v165 offset:51200
	ds_read_b128 v[208:211], v165 offset:52224
	ds_read_b128 v[212:215], v165 offset:53248
	ds_read_b128 v[216:219], v165 offset:54272
	ds_read_b128 v[220:223], v165 offset:55296
	ds_read_b128 v[224:227], v165 offset:56320
	global_load_lds_dwordx4 v[228:229], off
	s_add_i32 m0, s12, 0x2000
	s_add_u32 s12, s16, 0x44080
	v_lshl_add_u64 v[228:229], v[230:231], 0, s[84:85]
	s_addc_u32 s13, s17, 0
	s_add_i32 s16, s40, s22
	global_load_lds_dwordx4 v[228:229], off
	s_mov_b32 m0, s16
	v_lshl_add_u64 v[228:229], s[12:13], 0, v[132:133]
	global_load_lds_dwordx4 v[228:229], off
	s_add_i32 m0, s16, 0x2000
	v_lshl_add_u64 v[228:229], s[12:13], 0, v[152:153]
	global_load_lds_dwordx4 v[228:229], off
	s_mov_b32 m0, s27
	v_lshl_add_u64 v[228:229], v[232:233], 0, s[84:85]
	global_load_lds_dwordx4 v[228:229], off
	s_mov_b32 m0, s28
	v_lshl_add_u64 v[228:229], v[234:235], 0, s[84:85]
	global_load_lds_dwordx4 v[228:229], off
	s_waitcnt vmcnt(8)
	s_waitcnt lgkmcnt(0)
	s_setprio 1
	s_barrier
	v_mfma_f32_16x16x32_bf16 v[62:65], v[160:163], v[196:199], v[62:65]
	v_mfma_f32_16x16x32_bf16 v[58:61], v[170:173], v[196:199], v[58:61]
	v_mfma_f32_16x16x32_bf16 v[54:57], v[160:163], v[204:207], v[54:57]
	v_mfma_f32_16x16x32_bf16 v[46:49], v[170:173], v[204:207], v[46:49]
	v_mfma_f32_16x16x32_bf16 v[38:41], v[160:163], v[212:215], v[38:41]
	v_mfma_f32_16x16x32_bf16 v[30:33], v[170:173], v[212:215], v[30:33]
	v_mfma_f32_16x16x32_bf16 v[22:25], v[160:163], v[220:223], v[22:25]
	v_mfma_f32_16x16x32_bf16 v[14:17], v[170:173], v[220:223], v[14:17]
	v_mfma_f32_16x16x32_bf16 v[62:65], v[166:169], v[200:203], v[62:65]
	v_mfma_f32_16x16x32_bf16 v[58:61], v[174:177], v[200:203], v[58:61]
	v_mfma_f32_16x16x32_bf16 v[54:57], v[166:169], v[208:211], v[54:57]
	v_mfma_f32_16x16x32_bf16 v[46:49], v[174:177], v[208:211], v[46:49]
	v_mfma_f32_16x16x32_bf16 v[38:41], v[166:169], v[216:219], v[38:41]
	v_mfma_f32_16x16x32_bf16 v[30:33], v[174:177], v[216:219], v[30:33]
	v_mfma_f32_16x16x32_bf16 v[22:25], v[166:169], v[224:227], v[22:25]
	v_mfma_f32_16x16x32_bf16 v[14:17], v[174:177], v[224:227], v[14:17]
	v_mfma_f32_16x16x32_bf16 v[50:53], v[178:181], v[196:199], v[50:53]
	v_mfma_f32_16x16x32_bf16 v[42:45], v[188:191], v[196:199], v[42:45]
	v_mfma_f32_16x16x32_bf16 v[34:37], v[178:181], v[204:207], v[34:37]
	v_mfma_f32_16x16x32_bf16 v[26:29], v[188:191], v[204:207], v[26:29]
	v_mfma_f32_16x16x32_bf16 v[18:21], v[178:181], v[212:215], v[18:21]
	v_mfma_f32_16x16x32_bf16 v[10:13], v[188:191], v[212:215], v[10:13]
	v_mfma_f32_16x16x32_bf16 v[6:9], v[178:181], v[220:223], v[6:9]
	v_mfma_f32_16x16x32_bf16 v[2:5], v[188:191], v[220:223], v[2:5]
	v_mfma_f32_16x16x32_bf16 v[50:53], v[184:187], v[200:203], v[50:53]
	v_mfma_f32_16x16x32_bf16 v[42:45], v[192:195], v[200:203], v[42:45]
	v_mfma_f32_16x16x32_bf16 v[34:37], v[184:187], v[208:211], v[34:37]
	v_mfma_f32_16x16x32_bf16 v[26:29], v[192:195], v[208:211], v[26:29]
	v_mfma_f32_16x16x32_bf16 v[18:21], v[184:187], v[216:219], v[18:21]
	v_mfma_f32_16x16x32_bf16 v[10:13], v[192:195], v[216:219], v[10:13]
	v_mfma_f32_16x16x32_bf16 v[6:9], v[184:187], v[224:227], v[6:9]
	v_mfma_f32_16x16x32_bf16 v[2:5], v[192:195], v[224:227], v[2:5]
	s_barrier
	s_setprio 0
	s_add_i32 s38, s38, 2
	s_add_u32 s36, s36, 0x100
	s_addc_u32 s37, s37, 0
	s_cmp_gt_u32 s38, 13
	s_mov_b64 s[12:13], s[14:15]
.LBB0_837:
	s_add_u32 s14, s12, 0x100
	s_addc_u32 s15, s13, 0
	s_add_i32 s39, 0, 0x10000
	s_cmp_eq_u32 s38, 12
	s_cselect_b32 s19, s5, s15
	s_cselect_b32 s18, s4, s14
	s_cselect_b32 s17, s11, s37
	s_cselect_b32 s16, s10, s36
	s_add_i32 s40, 0, 0x14000
	v_add_u32_e32 v174, s39, v139
	v_add_u32_e32 v192, s40, v139
	ds_read_b128 v[160:163], v174
	ds_read_b128 v[166:169], v174 offset:1024
	ds_read_b128 v[170:173], v174 offset:2048
	ds_read_b128 v[174:177], v174 offset:3072
	ds_read_b128 v[178:181], v192
	ds_read_b128 v[184:187], v192 offset:1024
	ds_read_b128 v[188:191], v192 offset:2048
	ds_read_b128 v[192:195], v192 offset:3072
	v_lshl_add_u64 v[228:229], s[12:13], 0, v[156:157]
	s_add_i32 m0, s23, 0xc000
	ds_read_b128 v[196:199], v165
	ds_read_b128 v[200:203], v165 offset:1024
	ds_read_b128 v[204:207], v165 offset:2048
	ds_read_b128 v[208:211], v165 offset:3072
	ds_read_b128 v[212:215], v165 offset:4096
	ds_read_b128 v[216:219], v165 offset:5120
	ds_read_b128 v[220:223], v165 offset:6144
	ds_read_b128 v[224:227], v165 offset:7168
	global_load_lds_dwordx4 v[228:229], off
	s_add_i32 m0, s23, 0xe000
	v_lshl_add_u64 v[228:229], s[12:13], 0, v[158:159]
	global_load_lds_dwordx4 v[228:229], off
	s_waitcnt vmcnt(8)
	s_waitcnt lgkmcnt(0)
	s_setprio 1
	s_barrier
; #define PG8_STAGE(bufoff, gbase, voff) do { _Pragma("unroll") for (int _i = 0; _i < 2; ++_i) \
;         __builtin_amdgcn_global_load_lds((const unsigned*)((const char*)(gbase) + (voff)[_i]), (LAS unsigned*)(lds + (bufoff) + ldsw + _i * 8192), 16, 0, 0); } while (0)
; #define PG8_LDA(dst, b, h) do { _Pragma("unroll") for (int m = 0; m < 4; ++m) _Pragma("unroll") for (int k = 0; k < 2; ++k) dst[m][k] = *(const LAS bf16x8*)(lds + PG8_SA(b, h) + aoff + m * 2048 + k * 1024); } while (0)
; #define PG8_MMA(ai, bj, At, Bt) do { __builtin_amdgcn_s_setprio(1); _Pragma("unroll") for (int m = 0; m < 4; ++m) _Pragma("unroll") for (int n = 0; n < 2; ++n) _Pragma("unroll") for (int k = 0; k < 2; ++k) \
;         acc[ai][bj][m][n] = __builtin_amdgcn_mfma_f32_16x16x32_bf16(Bt[n][k], At[m][k], acc[ai][bj][m][n], 0, 0, 0); __builtin_amdgcn_s_setprio(0); } while (0)
; #define PG8_WAIT_V(n) asm volatile("s_waitcnt vmcnt(" #n ")" ::: "memory")
; #define PG8_WAIT_L(n) asm volatile("s_waitcnt lgkmcnt(" #n ")" ::: "memory")
; #define PG8_BAR __builtin_amdgcn_s_barrier()
; #define PG8_SCHED __builtin_amdgcn_sched_barrier(0)
; template <class Epi, bool ALIGN_EPI = PG8_ALIGN, bool SP2 = PG8_SP2>
; __device__ __forceinline__ void gemm_phase(LAS uchar* lds, const Gemm g, const StaticOrder& S, const Epi& E) {
;     ...
;             PG8_WAIT_V(8); PG8_WAIT_L(0); PG8_BAR; PG8_MMA(0, 0, At, B0); PG8_MMA(0, 1, At, B1); PG8_BAR; PG8_SCHED;
;             PG8_LDA(At, 0, 1); PG8_STAGE(PG8_SB(0, 0), b2, voffB); PG8_STAGE(PG8_SB(0, 1), b2 + hstepB, voffB); PG8_STAGE(PG8_SA(0, 0), a2, voffA);
;             PG8_WAIT_V(8); PG8_WAIT_L(0); PG8_BAR; PG8_MMA(1, 0, At, B0); PG8_MMA(1, 1, At, B1); PG8_BAR; PG8_SCHED;
	v_mfma_f32_16x16x32_bf16 v[126:129], v[160:163], v[196:199], v[126:129]
	v_mfma_f32_16x16x32_bf16 v[122:125], v[170:173], v[196:199], v[122:125]
	v_mfma_f32_16x16x32_bf16 v[118:121], v[160:163], v[204:207], v[118:121]
	v_mfma_f32_16x16x32_bf16 v[110:113], v[170:173], v[204:207], v[110:113]
	v_mfma_f32_16x16x32_bf16 v[102:105], v[160:163], v[212:215], v[102:105]
	v_mfma_f32_16x16x32_bf16 v[94:97], v[170:173], v[212:215], v[94:97]
	v_mfma_f32_16x16x32_bf16 v[86:89], v[160:163], v[220:223], v[86:89]
	v_mfma_f32_16x16x32_bf16 v[78:81], v[170:173], v[220:223], v[78:81]
	v_mfma_f32_16x16x32_bf16 v[126:129], v[166:169], v[200:203], v[126:129]
	v_mfma_f32_16x16x32_bf16 v[122:125], v[174:177], v[200:203], v[122:125]
	v_mfma_f32_16x16x32_bf16 v[118:121], v[166:169], v[208:211], v[118:121]
	v_mfma_f32_16x16x32_bf16 v[110:113], v[174:177], v[208:211], v[110:113]
	v_mfma_f32_16x16x32_bf16 v[102:105], v[166:169], v[216:219], v[102:105]
	v_mfma_f32_16x16x32_bf16 v[94:97], v[174:177], v[216:219], v[94:97]
	v_mfma_f32_16x16x32_bf16 v[86:89], v[166:169], v[224:227], v[86:89]
	v_mfma_f32_16x16x32_bf16 v[78:81], v[174:177], v[224:227], v[78:81]
	v_mfma_f32_16x16x32_bf16 v[114:117], v[178:181], v[196:199], v[114:117]
	v_mfma_f32_16x16x32_bf16 v[106:109], v[188:191], v[196:199], v[106:109]
	v_mfma_f32_16x16x32_bf16 v[98:101], v[178:181], v[204:207], v[98:101]
	v_mfma_f32_16x16x32_bf16 v[90:93], v[188:191], v[204:207], v[90:93]
	v_mfma_f32_16x16x32_bf16 v[82:85], v[178:181], v[212:215], v[82:85]
	v_mfma_f32_16x16x32_bf16 v[74:77], v[188:191], v[212:215], v[74:77]
	v_mfma_f32_16x16x32_bf16 v[70:73], v[178:181], v[220:223], v[70:73]
	v_mfma_f32_16x16x32_bf16 v[66:69], v[188:191], v[220:223], v[66:69]
	v_mfma_f32_16x16x32_bf16 v[114:117], v[184:187], v[200:203], v[114:117]
	v_mfma_f32_16x16x32_bf16 v[106:109], v[192:195], v[200:203], v[106:109]
	v_mfma_f32_16x16x32_bf16 v[98:101], v[184:187], v[208:211], v[98:101]
	v_mfma_f32_16x16x32_bf16 v[90:93], v[192:195], v[208:211], v[90:93]
	v_mfma_f32_16x16x32_bf16 v[82:85], v[184:187], v[216:219], v[82:85]
	v_mfma_f32_16x16x32_bf16 v[74:77], v[192:195], v[216:219], v[74:77]
	v_mfma_f32_16x16x32_bf16 v[70:73], v[184:187], v[224:227], v[70:73]
	v_mfma_f32_16x16x32_bf16 v[66:69], v[192:195], v[224:227], v[66:69]
	s_barrier
	s_setprio 0
	s_add_i32 s12, s39, s22
	v_lshl_add_u64 v[228:229], s[16:17], 0, v[132:133]
	s_mov_b32 m0, s12
	ds_read_b128 v[196:199], v165 offset:16384
	ds_read_b128 v[200:203], v165 offset:17408
	ds_read_b128 v[204:207], v165 offset:18432
	ds_read_b128 v[208:211], v165 offset:19456
	ds_read_b128 v[212:215], v165 offset:20480
	ds_read_b128 v[216:219], v165 offset:21504
	ds_read_b128 v[220:223], v165 offset:22528
	ds_read_b128 v[224:227], v165 offset:23552
	global_load_lds_dwordx4 v[228:229], off
	s_add_i32 m0, s12, 0x2000
	s_add_u32 s12, s16, 0x44000
	v_lshl_add_u64 v[230:231], s[16:17], 0, v[152:153]
	s_addc_u32 s13, s17, 0
	s_add_i32 s39, s40, s22
	global_load_lds_dwordx4 v[230:231], off
	s_mov_b32 m0, s39
	v_lshl_add_u64 v[232:233], s[12:13], 0, v[132:133]
	global_load_lds_dwordx4 v[232:233], off
	s_add_i32 m0, s39, 0x2000
	v_lshl_add_u64 v[232:233], s[12:13], 0, v[152:153]
	global_load_lds_dwordx4 v[232:233], off
	s_mov_b32 m0, s23
	v_lshl_add_u64 v[232:233], s[18:19], 0, v[130:131]
	global_load_lds_dwordx4 v[232:233], off
	s_mov_b32 m0, s24
	v_lshl_add_u64 v[234:235], s[18:19], 0, v[134:135]
	global_load_lds_dwordx4 v[234:235], off
	s_waitcnt vmcnt(8)
	s_waitcnt lgkmcnt(0)
	s_setprio 1
	s_barrier
	v_mfma_f32_16x16x32_bf16 v[62:65], v[160:163], v[196:199], v[62:65]
	v_mfma_f32_16x16x32_bf16 v[58:61], v[170:173], v[196:199], v[58:61]
	v_mfma_f32_16x16x32_bf16 v[54:57], v[160:163], v[204:207], v[54:57]
	v_mfma_f32_16x16x32_bf16 v[46:49], v[170:173], v[204:207], v[46:49]
	v_mfma_f32_16x16x32_bf16 v[38:41], v[160:163], v[212:215], v[38:41]
	v_mfma_f32_16x16x32_bf16 v[30:33], v[170:173], v[212:215], v[30:33]
	v_mfma_f32_16x16x32_bf16 v[22:25], v[160:163], v[220:223], v[22:25]
	v_mfma_f32_16x16x32_bf16 v[14:17], v[170:173], v[220:223], v[14:17]
	v_mfma_f32_16x16x32_bf16 v[62:65], v[166:169], v[200:203], v[62:65]
	v_mfma_f32_16x16x32_bf16 v[58:61], v[174:177], v[200:203], v[58:61]
	v_mfma_f32_16x16x32_bf16 v[54:57], v[166:169], v[208:211], v[54:57]
	v_mfma_f32_16x16x32_bf16 v[46:49], v[174:177], v[208:211], v[46:49]
	v_mfma_f32_16x16x32_bf16 v[38:41], v[166:169], v[216:219], v[38:41]
	v_mfma_f32_16x16x32_bf16 v[30:33], v[174:177], v[216:219], v[30:33]
	v_mfma_f32_16x16x32_bf16 v[22:25], v[166:169], v[224:227], v[22:25]
	v_mfma_f32_16x16x32_bf16 v[14:17], v[174:177], v[224:227], v[14:17]
	v_mfma_f32_16x16x32_bf16 v[50:53], v[178:181], v[196:199], v[50:53]
	v_mfma_f32_16x16x32_bf16 v[42:45], v[188:191], v[196:199], v[42:45]
	v_mfma_f32_16x16x32_bf16 v[34:37], v[178:181], v[204:207], v[34:37]
	v_mfma_f32_16x16x32_bf16 v[26:29], v[188:191], v[204:207], v[26:29]
	v_mfma_f32_16x16x32_bf16 v[18:21], v[178:181], v[212:215], v[18:21]
	v_mfma_f32_16x16x32_bf16 v[10:13], v[188:191], v[212:215], v[10:13]
	v_mfma_f32_16x16x32_bf16 v[6:9], v[178:181], v[220:223], v[6:9]
	v_mfma_f32_16x16x32_bf16 v[2:5], v[188:191], v[220:223], v[2:5]
	v_mfma_f32_16x16x32_bf16 v[50:53], v[184:187], v[200:203], v[50:53]
	v_mfma_f32_16x16x32_bf16 v[42:45], v[192:195], v[200:203], v[42:45]
	v_mfma_f32_16x16x32_bf16 v[34:37], v[184:187], v[208:211], v[34:37]
	v_mfma_f32_16x16x32_bf16 v[26:29], v[192:195], v[208:211], v[26:29]
	v_mfma_f32_16x16x32_bf16 v[18:21], v[184:187], v[216:219], v[18:21]
	v_mfma_f32_16x16x32_bf16 v[10:13], v[192:195], v[216:219], v[10:13]
	v_mfma_f32_16x16x32_bf16 v[6:9], v[184:187], v[224:227], v[6:9]
	v_mfma_f32_16x16x32_bf16 v[2:5], v[192:195], v[224:227], v[2:5]
	s_barrier
; #define PG8_STAGE(bufoff, gbase, voff) do { _Pragma("unroll") for (int _i = 0; _i < 2; ++_i) \
;         __builtin_amdgcn_global_load_lds((const unsigned*)((const char*)(gbase) + (voff)[_i]), (LAS unsigned*)(lds + (bufoff) + ldsw + _i * 8192), 16, 0, 0); } while (0)
; #define PG8_LDA(dst, b, h) do { _Pragma("unroll") for (int m = 0; m < 4; ++m) _Pragma("unroll") for (int k = 0; k < 2; ++k) dst[m][k] = *(const LAS bf16x8*)(lds + PG8_SA(b, h) + aoff + m * 2048 + k * 1024); } while (0)
; #define PG8_LDB(dst, b, h) do { _Pragma("unroll") for (int n = 0; n < 2; ++n) _Pragma("unroll") for (int k = 0; k < 2; ++k) dst[n][k] = *(const LAS bf16x8*)(lds + PG8_SB(b, h) + boff + n * 2048 + k * 1024); } while (0)
; #define PG8_MMA(ai, bj, At, Bt) do { __builtin_amdgcn_s_setprio(1); _Pragma("unroll") for (int m = 0; m < 4; ++m) _Pragma("unroll") for (int n = 0; n < 2; ++n) _Pragma("unroll") for (int k = 0; k < 2; ++k) \
;         acc[ai][bj][m][n] = __builtin_amdgcn_mfma_f32_16x16x32_bf16(Bt[n][k], At[m][k], acc[ai][bj][m][n], 0, 0, 0); __builtin_amdgcn_s_setprio(0); } while (0)
; #define PG8_WAIT_V(n) asm volatile("s_waitcnt vmcnt(" #n ")" ::: "memory")
; #define PG8_WAIT_L(n) asm volatile("s_waitcnt lgkmcnt(" #n ")" ::: "memory")
; #define PG8_BAR __builtin_amdgcn_s_barrier()
; #define PG8_SCHED __builtin_amdgcn_sched_barrier(0)
; template <class Epi, bool ALIGN_EPI = PG8_ALIGN, bool SP2 = PG8_SP2>
; __device__ __forceinline__ void gemm_phase(LAS uchar* lds, const Gemm g, const StaticOrder& S, const Epi& E) {
;     ...
;             PG8_LDB(B0, 1, 0); PG8_LDB(B1, 1, 1); PG8_SCHED; PG8_LDA(At, 1, 0); PG8_STAGE(PG8_SA(0, 1), a2 + hstepA, voffA);
;             PG8_WAIT_V(8); PG8_WAIT_L(0); PG8_BAR; PG8_MMA(0, 0, At, B0); PG8_MMA(0, 1, At, B1); PG8_BAR; PG8_SCHED;
	s_setprio 0
	s_add_i32 s39, 0, 0x18000
	s_add_i32 s40, 0, 0x1c000
	v_add_u32_e32 v174, s39, v139
	v_add_u32_e32 v192, s40, v139
	ds_read_b128 v[160:163], v174
	ds_read_b128 v[166:169], v174 offset:1024
	ds_read_b128 v[170:173], v174 offset:2048
	ds_read_b128 v[174:177], v174 offset:3072
	ds_read_b128 v[178:181], v192
	ds_read_b128 v[184:187], v192 offset:1024
	ds_read_b128 v[188:191], v192 offset:2048
	ds_read_b128 v[192:195], v192 offset:3072
	s_add_u32 s12, s18, 0x44000
	s_addc_u32 s13, s19, 0
	s_mov_b32 m0, s25
	v_lshl_add_u64 v[236:237], s[12:13], 0, v[130:131]
	ds_read_b128 v[196:199], v165 offset:32768
	ds_read_b128 v[200:203], v165 offset:33792
	ds_read_b128 v[204:207], v165 offset:34816
	ds_read_b128 v[208:211], v165 offset:35840
	ds_read_b128 v[212:215], v165 offset:36864
	ds_read_b128 v[216:219], v165 offset:37888
	ds_read_b128 v[220:223], v165 offset:38912
	ds_read_b128 v[224:227], v165 offset:39936
	global_load_lds_dwordx4 v[236:237], off
	s_mov_b32 m0, s26
	v_lshl_add_u64 v[236:237], s[12:13], 0, v[134:135]
	global_load_lds_dwordx4 v[236:237], off
	s_waitcnt vmcnt(8)
	s_waitcnt lgkmcnt(0)
	s_setprio 1
	s_barrier
	v_mfma_f32_16x16x32_bf16 v[126:129], v[160:163], v[196:199], v[126:129]
	v_mfma_f32_16x16x32_bf16 v[122:125], v[170:173], v[196:199], v[122:125]
	v_mfma_f32_16x16x32_bf16 v[118:121], v[160:163], v[204:207], v[118:121]
	v_mfma_f32_16x16x32_bf16 v[110:113], v[170:173], v[204:207], v[110:113]
	v_mfma_f32_16x16x32_bf16 v[102:105], v[160:163], v[212:215], v[102:105]
	v_mfma_f32_16x16x32_bf16 v[94:97], v[170:173], v[212:215], v[94:97]
	v_mfma_f32_16x16x32_bf16 v[86:89], v[160:163], v[220:223], v[86:89]
	v_mfma_f32_16x16x32_bf16 v[78:81], v[170:173], v[220:223], v[78:81]
	v_mfma_f32_16x16x32_bf16 v[126:129], v[166:169], v[200:203], v[126:129]
	v_mfma_f32_16x16x32_bf16 v[122:125], v[174:177], v[200:203], v[122:125]
	v_mfma_f32_16x16x32_bf16 v[118:121], v[166:169], v[208:211], v[118:121]
	v_mfma_f32_16x16x32_bf16 v[110:113], v[174:177], v[208:211], v[110:113]
	v_mfma_f32_16x16x32_bf16 v[102:105], v[166:169], v[216:219], v[102:105]
	v_mfma_f32_16x16x32_bf16 v[94:97], v[174:177], v[216:219], v[94:97]
	v_mfma_f32_16x16x32_bf16 v[86:89], v[166:169], v[224:227], v[86:89]
	v_mfma_f32_16x16x32_bf16 v[78:81], v[174:177], v[224:227], v[78:81]
	v_mfma_f32_16x16x32_bf16 v[114:117], v[178:181], v[196:199], v[114:117]
	v_mfma_f32_16x16x32_bf16 v[106:109], v[188:191], v[196:199], v[106:109]
	v_mfma_f32_16x16x32_bf16 v[98:101], v[178:181], v[204:207], v[98:101]
	v_mfma_f32_16x16x32_bf16 v[90:93], v[188:191], v[204:207], v[90:93]
	v_mfma_f32_16x16x32_bf16 v[82:85], v[178:181], v[212:215], v[82:85]
	v_mfma_f32_16x16x32_bf16 v[74:77], v[188:191], v[212:215], v[74:77]
	v_mfma_f32_16x16x32_bf16 v[70:73], v[178:181], v[220:223], v[70:73]
	v_mfma_f32_16x16x32_bf16 v[66:69], v[188:191], v[220:223], v[66:69]
	v_mfma_f32_16x16x32_bf16 v[114:117], v[184:187], v[200:203], v[114:117]
	v_mfma_f32_16x16x32_bf16 v[106:109], v[192:195], v[200:203], v[106:109]
	v_mfma_f32_16x16x32_bf16 v[98:101], v[184:187], v[208:211], v[98:101]
	v_mfma_f32_16x16x32_bf16 v[90:93], v[192:195], v[208:211], v[90:93]
	v_mfma_f32_16x16x32_bf16 v[82:85], v[184:187], v[216:219], v[82:85]
	v_mfma_f32_16x16x32_bf16 v[74:77], v[192:195], v[216:219], v[74:77]
	v_mfma_f32_16x16x32_bf16 v[70:73], v[184:187], v[224:227], v[70:73]
	v_mfma_f32_16x16x32_bf16 v[66:69], v[192:195], v[224:227], v[66:69]
	s_barrier
; #define PG8_STAGE(bufoff, gbase, voff) do { _Pragma("unroll") for (int _i = 0; _i < 2; ++_i) \
;         __builtin_amdgcn_global_load_lds((const unsigned*)((const char*)(gbase) + (voff)[_i]), (LAS unsigned*)(lds + (bufoff) + ldsw + _i * 8192), 16, 0, 0); } while (0)
; #define PG8_LDA(dst, b, h) do { _Pragma("unroll") for (int m = 0; m < 4; ++m) _Pragma("unroll") for (int k = 0; k < 2; ++k) dst[m][k] = *(const LAS bf16x8*)(lds + PG8_SA(b, h) + aoff + m * 2048 + k * 1024); } while (0)
; #define PG8_MMA(ai, bj, At, Bt) do { __builtin_amdgcn_s_setprio(1); _Pragma("unroll") for (int m = 0; m < 4; ++m) _Pragma("unroll") for (int n = 0; n < 2; ++n) _Pragma("unroll") for (int k = 0; k < 2; ++k) \
;         acc[ai][bj][m][n] = __builtin_amdgcn_mfma_f32_16x16x32_bf16(Bt[n][k], At[m][k], acc[ai][bj][m][n], 0, 0, 0); __builtin_amdgcn_s_setprio(0); } while (0)
; #define PG8_WAIT_V(n) asm volatile("s_waitcnt vmcnt(" #n ")" ::: "memory")
; #define PG8_WAIT_L(n) asm volatile("s_waitcnt lgkmcnt(" #n ")" ::: "memory")
; #define PG8_BAR __builtin_amdgcn_s_barrier()
; #define PG8_SCHED __builtin_amdgcn_sched_barrier(0)
; template <class Epi, bool ALIGN_EPI = PG8_ALIGN, bool SP2 = PG8_SP2>
; __device__ __forceinline__ void gemm_phase(LAS uchar* lds, const Gemm g, const StaticOrder& S, const Epi& E) {
;     ...
;             PG8_LDA(At, 1, 1); PG8_STAGE(PG8_SB(1, 0), b3, voffB); PG8_STAGE(PG8_SB(1, 1), b3 + hstepB, voffB); PG8_STAGE(PG8_SA(1, 0), a3, voffA);
;             PG8_WAIT_V(8); PG8_WAIT_L(0); PG8_BAR; PG8_MMA(1, 0, At, B0); PG8_MMA(1, 1, At, B1); PG8_BAR; PG8_SCHED;
;     ...
;         if constexpr (ALIGN_EPI) { if (wr == 0) PG8_BAR; }
	s_setprio 0
	s_add_i32 s12, s39, s22
	v_lshl_add_u64 v[228:229], v[228:229], 0, s[84:85]
	s_mov_b32 m0, s12
	ds_read_b128 v[196:199], v165 offset:49152
	ds_read_b128 v[200:203], v165 offset:50176
	ds_read_b128 v[204:207], v165 offset:51200
	ds_read_b128 v[208:211], v165 offset:52224
	ds_read_b128 v[212:215], v165 offset:53248
	ds_read_b128 v[216:219], v165 offset:54272
	ds_read_b128 v[220:223], v165 offset:55296
	ds_read_b128 v[224:227], v165 offset:56320
	global_load_lds_dwordx4 v[228:229], off
	s_add_i32 m0, s12, 0x2000
	s_add_u32 s12, s16, 0x44080
	v_lshl_add_u64 v[228:229], v[230:231], 0, s[84:85]
	s_addc_u32 s13, s17, 0
	s_add_i32 s16, s40, s22
	global_load_lds_dwordx4 v[228:229], off
	s_mov_b32 m0, s16
	v_lshl_add_u64 v[228:229], s[12:13], 0, v[132:133]
	global_load_lds_dwordx4 v[228:229], off
	s_add_i32 m0, s16, 0x2000
	v_lshl_add_u64 v[228:229], s[12:13], 0, v[152:153]
	global_load_lds_dwordx4 v[228:229], off
	s_mov_b32 m0, s27
	v_lshl_add_u64 v[228:229], v[232:233], 0, s[84:85]
	global_load_lds_dwordx4 v[228:229], off
	s_mov_b32 m0, s28
	v_lshl_add_u64 v[228:229], v[234:235], 0, s[84:85]
	global_load_lds_dwordx4 v[228:229], off
	s_waitcnt vmcnt(8)
	s_waitcnt lgkmcnt(0)
	s_setprio 1
	s_barrier
	v_mfma_f32_16x16x32_bf16 v[62:65], v[160:163], v[196:199], v[62:65]
	v_mfma_f32_16x16x32_bf16 v[58:61], v[170:173], v[196:199], v[58:61]
	v_mfma_f32_16x16x32_bf16 v[54:57], v[160:163], v[204:207], v[54:57]
	v_mfma_f32_16x16x32_bf16 v[46:49], v[170:173], v[204:207], v[46:49]
	v_mfma_f32_16x16x32_bf16 v[38:41], v[160:163], v[212:215], v[38:41]
	v_mfma_f32_16x16x32_bf16 v[30:33], v[170:173], v[212:215], v[30:33]
	v_mfma_f32_16x16x32_bf16 v[22:25], v[160:163], v[220:223], v[22:25]
	v_mfma_f32_16x16x32_bf16 v[14:17], v[170:173], v[220:223], v[14:17]
	v_mfma_f32_16x16x32_bf16 v[62:65], v[166:169], v[200:203], v[62:65]
	v_mfma_f32_16x16x32_bf16 v[58:61], v[174:177], v[200:203], v[58:61]
	v_mfma_f32_16x16x32_bf16 v[54:57], v[166:169], v[208:211], v[54:57]
	v_mfma_f32_16x16x32_bf16 v[46:49], v[174:177], v[208:211], v[46:49]
	v_mfma_f32_16x16x32_bf16 v[38:41], v[166:169], v[216:219], v[38:41]
	v_mfma_f32_16x16x32_bf16 v[30:33], v[174:177], v[216:219], v[30:33]
	v_mfma_f32_16x16x32_bf16 v[22:25], v[166:169], v[224:227], v[22:25]
	v_mfma_f32_16x16x32_bf16 v[14:17], v[174:177], v[224:227], v[14:17]
	v_mfma_f32_16x16x32_bf16 v[50:53], v[178:181], v[196:199], v[50:53]
	v_mfma_f32_16x16x32_bf16 v[42:45], v[188:191], v[196:199], v[42:45]
	v_mfma_f32_16x16x32_bf16 v[34:37], v[178:181], v[204:207], v[34:37]
	v_mfma_f32_16x16x32_bf16 v[26:29], v[188:191], v[204:207], v[26:29]
	v_mfma_f32_16x16x32_bf16 v[18:21], v[178:181], v[212:215], v[18:21]
	v_mfma_f32_16x16x32_bf16 v[10:13], v[188:191], v[212:215], v[10:13]
	v_mfma_f32_16x16x32_bf16 v[6:9], v[178:181], v[220:223], v[6:9]
	v_mfma_f32_16x16x32_bf16 v[2:5], v[188:191], v[220:223], v[2:5]
	v_mfma_f32_16x16x32_bf16 v[50:53], v[184:187], v[200:203], v[50:53]
	v_mfma_f32_16x16x32_bf16 v[42:45], v[192:195], v[200:203], v[42:45]
	v_mfma_f32_16x16x32_bf16 v[34:37], v[184:187], v[208:211], v[34:37]
	v_mfma_f32_16x16x32_bf16 v[26:29], v[192:195], v[208:211], v[26:29]
	v_mfma_f32_16x16x32_bf16 v[18:21], v[184:187], v[216:219], v[18:21]
	v_mfma_f32_16x16x32_bf16 v[10:13], v[192:195], v[216:219], v[10:13]
	v_mfma_f32_16x16x32_bf16 v[6:9], v[184:187], v[224:227], v[6:9]
	v_mfma_f32_16x16x32_bf16 v[2:5], v[192:195], v[224:227], v[2:5]
	s_barrier
	s_setprio 0
	s_add_i32 s38, s38, 2
	s_add_u32 s36, s36, 0x100
	s_addc_u32 s37, s37, 0
	s_cmp_gt_u32 s38, 13
	s_mov_b64 s[12:13], s[14:15]
	s_cbranch_scc0 .LBB0_837
	s_and_b64 vcc, exec, s[8:9]
	s_cbranch_vccz .LBB0_840
	s_barrier

; #define PG8_STAGE(bufoff, gbase, voff) do { _Pragma("unroll") for (int _i = 0; _i < 2; ++_i) \
;         __builtin_amdgcn_global_load_lds((const unsigned*)((const char*)(gbase) + (voff)[_i]), (LAS unsigned*)(lds + (bufoff) + ldsw + _i * 8192), 16, 0, 0); } while (0)
; #define PG8_LDA(dst, b, h) do { _Pragma("unroll") for (int m = 0; m < 4; ++m) _Pragma("unroll") for (int k = 0; k < 2; ++k) dst[m][k] = *(const LAS bf16x8*)(lds + PG8_SA(b, h) + aoff + m * 2048 + k * 1024); } while (0)
; #define PG8_LDB(dst, b, h) do { _Pragma("unroll") for (int n = 0; n < 2; ++n) _Pragma("unroll") for (int k = 0; k < 2; ++k) dst[n][k] = *(const LAS bf16x8*)(lds + PG8_SB(b, h) + boff + n * 2048 + k * 1024); } while (0)
; #define PG8_MMA(ai, bj, At, Bt) do { __builtin_amdgcn_s_setprio(1); _Pragma("unroll") for (int m = 0; m < 4; ++m) _Pragma("unroll") for (int n = 0; n < 2; ++n) _Pragma("unroll") for (int k = 0; k < 2; ++k) \
;         acc[ai][bj][m][n] = __builtin_amdgcn_mfma_f32_16x16x32_bf16(Bt[n][k], At[m][k], acc[ai][bj][m][n], 0, 0, 0); __builtin_amdgcn_s_setprio(0); } while (0)
; #define PG8_WAIT_V(n) asm volatile("s_waitcnt vmcnt(" #n ")" ::: "memory")
; #define PG8_WAIT_L(n) asm volatile("s_waitcnt lgkmcnt(" #n ")" ::: "memory")
; #define PG8_BAR __builtin_amdgcn_s_barrier()
; #define PG8_SCHED __builtin_amdgcn_sched_barrier(0)
; template <class Epi, bool ALIGN_EPI = PG8_ALIGN, bool SP2 = PG8_SP2>
; __device__ __forceinline__ void gemm_phase(LAS uchar* lds, const Gemm g, const StaticOrder& S, const Epi& E) {
;     ...
;             PG8_LDB(B0, 0, 0); PG8_LDB(B1, 0, 1); PG8_SCHED; PG8_LDA(At, 0, 0); PG8_STAGE(PG8_SA(1, 1), a1 + hstepA, voffA);
;             PG8_WAIT_V(8); PG8_WAIT_L(0); PG8_BAR; PG8_MMA(0, 0, At, B0); PG8_MMA(0, 1, At, B1); PG8_BAR; PG8_SCHED;
;             PG8_LDA(At, 0, 1); PG8_STAGE(PG8_SB(0, 0), b2, voffB); PG8_STAGE(PG8_SB(0, 1), b2 + hstepB, voffB); PG8_STAGE(PG8_SA(0, 0), a2, voffA);
;             PG8_WAIT_V(8); PG8_WAIT_L(0); PG8_BAR; PG8_MMA(1, 0, At, B0); PG8_MMA(1, 1, At, B1); PG8_BAR; PG8_SCHED;
.LBB0_1050:
	s_add_u32 s14, s12, 0x100
	s_addc_u32 s15, s13, 0
	s_add_i32 s39, 0, 0x10000
	s_cmp_eq_u32 s38, 12
	s_cselect_b32 s19, s1, s15
	s_cselect_b32 s18, s0, s14
	v_add_u32_e32 v144, s39, v139
	s_cselect_b32 s17, s11, s37
	s_cselect_b32 s16, s10, s36
	s_add_i32 s40, 0, 0x14000
	ds_read_b128 v[164:167], v144
	ds_read_b128 v[168:171], v144 offset:1024
	ds_read_b128 v[172:175], v144 offset:2048
	ds_read_b128 v[176:179], v144 offset:3072
	v_add_u32_e32 v144, s40, v139
	ds_read_b128 v[184:187], v144
	ds_read_b128 v[188:191], v144 offset:1024
	ds_read_b128 v[192:195], v144 offset:2048
	ds_read_b128 v[196:199], v144 offset:3072
	v_lshl_add_u64 v[160:161], s[12:13], 0, v[156:157]
	s_add_i32 m0, s23, 0xc000
	ds_read_b128 v[200:203], v163
	ds_read_b128 v[204:207], v163 offset:1024
	ds_read_b128 v[208:211], v163 offset:2048
	ds_read_b128 v[212:215], v163 offset:3072
	ds_read_b128 v[216:219], v163 offset:4096
	ds_read_b128 v[220:223], v163 offset:5120
	ds_read_b128 v[224:227], v163 offset:6144
	ds_read_b128 v[228:231], v163 offset:7168
	global_load_lds_dwordx4 v[160:161], off
	s_add_i32 m0, s23, 0xe000
	v_lshl_add_u64 v[160:161], s[12:13], 0, v[158:159]
	global_load_lds_dwordx4 v[160:161], off
	s_waitcnt vmcnt(8)
	s_waitcnt lgkmcnt(0)
	s_setprio 1
	s_barrier
	v_mfma_f32_16x16x32_bf16 v[126:129], v[164:167], v[200:203], v[126:129]
	v_mfma_f32_16x16x32_bf16 v[118:121], v[172:175], v[200:203], v[118:121]
	v_mfma_f32_16x16x32_bf16 v[110:113], v[164:167], v[208:211], v[110:113]
	v_mfma_f32_16x16x32_bf16 v[102:105], v[172:175], v[208:211], v[102:105]
	v_mfma_f32_16x16x32_bf16 v[94:97], v[164:167], v[216:219], v[94:97]
	v_mfma_f32_16x16x32_bf16 v[86:89], v[172:175], v[216:219], v[86:89]
	v_mfma_f32_16x16x32_bf16 v[78:81], v[164:167], v[224:227], v[78:81]
	v_mfma_f32_16x16x32_bf16 v[70:73], v[172:175], v[224:227], v[70:73]
	v_mfma_f32_16x16x32_bf16 v[126:129], v[168:171], v[204:207], v[126:129]
	v_mfma_f32_16x16x32_bf16 v[118:121], v[176:179], v[204:207], v[118:121]
	v_mfma_f32_16x16x32_bf16 v[110:113], v[168:171], v[212:215], v[110:113]
	v_mfma_f32_16x16x32_bf16 v[102:105], v[176:179], v[212:215], v[102:105]
	v_mfma_f32_16x16x32_bf16 v[94:97], v[168:171], v[220:223], v[94:97]
	v_mfma_f32_16x16x32_bf16 v[86:89], v[176:179], v[220:223], v[86:89]
	v_mfma_f32_16x16x32_bf16 v[78:81], v[168:171], v[228:231], v[78:81]
	v_mfma_f32_16x16x32_bf16 v[70:73], v[176:179], v[228:231], v[70:73]
	v_mfma_f32_16x16x32_bf16 v[122:125], v[184:187], v[200:203], v[122:125]
	v_mfma_f32_16x16x32_bf16 v[114:117], v[192:195], v[200:203], v[114:117]
	v_mfma_f32_16x16x32_bf16 v[106:109], v[184:187], v[208:211], v[106:109]
	v_mfma_f32_16x16x32_bf16 v[98:101], v[192:195], v[208:211], v[98:101]
	v_mfma_f32_16x16x32_bf16 v[90:93], v[184:187], v[216:219], v[90:93]
	v_mfma_f32_16x16x32_bf16 v[82:85], v[192:195], v[216:219], v[82:85]
	v_mfma_f32_16x16x32_bf16 v[74:77], v[184:187], v[224:227], v[74:77]
	v_mfma_f32_16x16x32_bf16 v[66:69], v[192:195], v[224:227], v[66:69]
	v_mfma_f32_16x16x32_bf16 v[122:125], v[188:191], v[204:207], v[122:125]
	v_mfma_f32_16x16x32_bf16 v[114:117], v[196:199], v[204:207], v[114:117]
	v_mfma_f32_16x16x32_bf16 v[106:109], v[188:191], v[212:215], v[106:109]
	v_mfma_f32_16x16x32_bf16 v[98:101], v[196:199], v[212:215], v[98:101]
	v_mfma_f32_16x16x32_bf16 v[90:93], v[188:191], v[220:223], v[90:93]
	v_mfma_f32_16x16x32_bf16 v[82:85], v[196:199], v[220:223], v[82:85]
	v_mfma_f32_16x16x32_bf16 v[74:77], v[188:191], v[228:231], v[74:77]
	v_mfma_f32_16x16x32_bf16 v[66:69], v[196:199], v[228:231], v[66:69]
	s_barrier
	s_setprio 0
	s_add_i32 s12, s39, s21
	v_lshl_add_u64 v[160:161], s[16:17], 0, v[134:135]
	s_mov_b32 m0, s12
	ds_read_b128 v[200:203], v163 offset:16384
	ds_read_b128 v[204:207], v163 offset:17408
	ds_read_b128 v[208:211], v163 offset:18432
	ds_read_b128 v[212:215], v163 offset:19456
	ds_read_b128 v[216:219], v163 offset:20480
	ds_read_b128 v[220:223], v163 offset:21504
	ds_read_b128 v[224:227], v163 offset:22528
	ds_read_b128 v[228:231], v163 offset:23552
	global_load_lds_dwordx4 v[160:161], off
	s_add_i32 m0, s12, 0x2000
	s_add_u32 s12, s16, 0x44000
	v_lshl_add_u64 v[180:181], s[16:17], 0, v[130:131]
	s_addc_u32 s13, s17, 0
	s_add_i32 s39, s40, s21
	global_load_lds_dwordx4 v[180:181], off
	s_mov_b32 m0, s39
	v_lshl_add_u64 v[232:233], s[12:13], 0, v[134:135]
	global_load_lds_dwordx4 v[232:233], off
	s_add_i32 m0, s39, 0x2000
	v_lshl_add_u64 v[232:233], s[12:13], 0, v[130:131]
	global_load_lds_dwordx4 v[232:233], off
	s_mov_b32 m0, s23
	v_lshl_add_u64 v[232:233], s[18:19], 0, v[154:155]
	global_load_lds_dwordx4 v[232:233], off
	s_mov_b32 m0, s24
	v_lshl_add_u64 v[234:235], s[18:19], 0, v[132:133]
	global_load_lds_dwordx4 v[234:235], off
	s_waitcnt vmcnt(8)
	s_waitcnt lgkmcnt(0)
	s_setprio 1
	s_barrier
; #define PG8_STAGE(bufoff, gbase, voff) do { _Pragma("unroll") for (int _i = 0; _i < 2; ++_i) \
;         __builtin_amdgcn_global_load_lds((const unsigned*)((const char*)(gbase) + (voff)[_i]), (LAS unsigned*)(lds + (bufoff) + ldsw + _i * 8192), 16, 0, 0); } while (0)
; #define PG8_LDA(dst, b, h) do { _Pragma("unroll") for (int m = 0; m < 4; ++m) _Pragma("unroll") for (int k = 0; k < 2; ++k) dst[m][k] = *(const LAS bf16x8*)(lds + PG8_SA(b, h) + aoff + m * 2048 + k * 1024); } while (0)
; #define PG8_LDB(dst, b, h) do { _Pragma("unroll") for (int n = 0; n < 2; ++n) _Pragma("unroll") for (int k = 0; k < 2; ++k) dst[n][k] = *(const LAS bf16x8*)(lds + PG8_SB(b, h) + boff + n * 2048 + k * 1024); } while (0)
; #define PG8_MMA(ai, bj, At, Bt) do { __builtin_amdgcn_s_setprio(1); _Pragma("unroll") for (int m = 0; m < 4; ++m) _Pragma("unroll") for (int n = 0; n < 2; ++n) _Pragma("unroll") for (int k = 0; k < 2; ++k) \
;         acc[ai][bj][m][n] = __builtin_amdgcn_mfma_f32_16x16x32_bf16(Bt[n][k], At[m][k], acc[ai][bj][m][n], 0, 0, 0); __builtin_amdgcn_s_setprio(0); } while (0)
; #define PG8_WAIT_V(n) asm volatile("s_waitcnt vmcnt(" #n ")" ::: "memory")
; #define PG8_WAIT_L(n) asm volatile("s_waitcnt lgkmcnt(" #n ")" ::: "memory")
; #define PG8_BAR __builtin_amdgcn_s_barrier()
; #define PG8_SCHED __builtin_amdgcn_sched_barrier(0)
; template <class Epi, bool ALIGN_EPI = PG8_ALIGN, bool SP2 = PG8_SP2>
; __device__ __forceinline__ void gemm_phase(LAS uchar* lds, const Gemm g, const StaticOrder& S, const Epi& E) {
;     ...
;             PG8_WAIT_V(8); PG8_WAIT_L(0); PG8_BAR; PG8_MMA(0, 0, At, B0); PG8_MMA(0, 1, At, B1); PG8_BAR; PG8_SCHED;
;             PG8_LDA(At, 0, 1); PG8_STAGE(PG8_SB(0, 0), b2, voffB); PG8_STAGE(PG8_SB(0, 1), b2 + hstepB, voffB); PG8_STAGE(PG8_SA(0, 0), a2, voffA);
;             PG8_WAIT_V(8); PG8_WAIT_L(0); PG8_BAR; PG8_MMA(1, 0, At, B0); PG8_MMA(1, 1, At, B1); PG8_BAR; PG8_SCHED;
;             PG8_LDB(B0, 1, 0); PG8_LDB(B1, 1, 1); PG8_SCHED; PG8_LDA(At, 1, 0); PG8_STAGE(PG8_SA(0, 1), a2 + hstepA, voffA);
;             PG8_WAIT_V(8); PG8_WAIT_L(0); PG8_BAR; PG8_MMA(0, 0, At, B0); PG8_MMA(0, 1, At, B1); PG8_BAR; PG8_SCHED;
	v_mfma_f32_16x16x32_bf16 v[62:65], v[164:167], v[200:203], v[62:65]
	v_mfma_f32_16x16x32_bf16 v[54:57], v[172:175], v[200:203], v[54:57]
	v_mfma_f32_16x16x32_bf16 v[46:49], v[164:167], v[208:211], v[46:49]
	v_mfma_f32_16x16x32_bf16 v[38:41], v[172:175], v[208:211], v[38:41]
	v_mfma_f32_16x16x32_bf16 v[30:33], v[164:167], v[216:219], v[30:33]
	v_mfma_f32_16x16x32_bf16 v[22:25], v[172:175], v[216:219], v[22:25]
	v_mfma_f32_16x16x32_bf16 v[14:17], v[164:167], v[224:227], v[14:17]
	v_mfma_f32_16x16x32_bf16 v[6:9], v[172:175], v[224:227], v[6:9]
	v_mfma_f32_16x16x32_bf16 v[62:65], v[168:171], v[204:207], v[62:65]
	v_mfma_f32_16x16x32_bf16 v[54:57], v[176:179], v[204:207], v[54:57]
	v_mfma_f32_16x16x32_bf16 v[46:49], v[168:171], v[212:215], v[46:49]
	v_mfma_f32_16x16x32_bf16 v[38:41], v[176:179], v[212:215], v[38:41]
	v_mfma_f32_16x16x32_bf16 v[30:33], v[168:171], v[220:223], v[30:33]
	v_mfma_f32_16x16x32_bf16 v[22:25], v[176:179], v[220:223], v[22:25]
	v_mfma_f32_16x16x32_bf16 v[14:17], v[168:171], v[228:231], v[14:17]
	v_mfma_f32_16x16x32_bf16 v[6:9], v[176:179], v[228:231], v[6:9]
	v_mfma_f32_16x16x32_bf16 v[58:61], v[184:187], v[200:203], v[58:61]
	v_mfma_f32_16x16x32_bf16 v[50:53], v[192:195], v[200:203], v[50:53]
	v_mfma_f32_16x16x32_bf16 v[42:45], v[184:187], v[208:211], v[42:45]
	v_mfma_f32_16x16x32_bf16 v[34:37], v[192:195], v[208:211], v[34:37]
	v_mfma_f32_16x16x32_bf16 v[26:29], v[184:187], v[216:219], v[26:29]
	v_mfma_f32_16x16x32_bf16 v[18:21], v[192:195], v[216:219], v[18:21]
	v_mfma_f32_16x16x32_bf16 v[10:13], v[184:187], v[224:227], v[10:13]
	v_mfma_f32_16x16x32_bf16 v[2:5], v[192:195], v[224:227], v[2:5]
	v_mfma_f32_16x16x32_bf16 v[58:61], v[188:191], v[204:207], v[58:61]
	v_mfma_f32_16x16x32_bf16 v[50:53], v[196:199], v[204:207], v[50:53]
	v_mfma_f32_16x16x32_bf16 v[42:45], v[188:191], v[212:215], v[42:45]
	v_mfma_f32_16x16x32_bf16 v[34:37], v[196:199], v[212:215], v[34:37]
	v_mfma_f32_16x16x32_bf16 v[26:29], v[188:191], v[220:223], v[26:29]
	v_mfma_f32_16x16x32_bf16 v[18:21], v[196:199], v[220:223], v[18:21]
	v_mfma_f32_16x16x32_bf16 v[10:13], v[188:191], v[228:231], v[10:13]
	v_mfma_f32_16x16x32_bf16 v[2:5], v[196:199], v[228:231], v[2:5]
	s_barrier
	s_setprio 0
	s_add_i32 s39, 0, 0x18000
	v_add_u32_e32 v144, s39, v139
	s_add_i32 s40, 0, 0x1c000
	ds_read_b128 v[164:167], v144
	ds_read_b128 v[168:171], v144 offset:1024
	ds_read_b128 v[172:175], v144 offset:2048
	ds_read_b128 v[176:179], v144 offset:3072
	v_add_u32_e32 v144, s40, v139
	ds_read_b128 v[184:187], v144
	ds_read_b128 v[188:191], v144 offset:1024
	ds_read_b128 v[192:195], v144 offset:2048
	ds_read_b128 v[196:199], v144 offset:3072
	s_add_u32 s12, s18, 0x44000
	s_addc_u32 s13, s19, 0
	s_mov_b32 m0, s25
	v_lshl_add_u64 v[236:237], s[12:13], 0, v[154:155]
	ds_read_b128 v[200:203], v163 offset:32768
	ds_read_b128 v[204:207], v163 offset:33792
	ds_read_b128 v[208:211], v163 offset:34816
	ds_read_b128 v[212:215], v163 offset:35840
	ds_read_b128 v[216:219], v163 offset:36864
	ds_read_b128 v[220:223], v163 offset:37888
	ds_read_b128 v[224:227], v163 offset:38912
	ds_read_b128 v[228:231], v163 offset:39936
	global_load_lds_dwordx4 v[236:237], off
	s_mov_b32 m0, s26
	v_lshl_add_u64 v[236:237], s[12:13], 0, v[132:133]
	global_load_lds_dwordx4 v[236:237], off
	s_waitcnt vmcnt(8)
	s_waitcnt lgkmcnt(0)
	s_setprio 1
	s_barrier
	v_mfma_f32_16x16x32_bf16 v[126:129], v[164:167], v[200:203], v[126:129]
	v_mfma_f32_16x16x32_bf16 v[118:121], v[172:175], v[200:203], v[118:121]
	v_mfma_f32_16x16x32_bf16 v[110:113], v[164:167], v[208:211], v[110:113]
	v_mfma_f32_16x16x32_bf16 v[102:105], v[172:175], v[208:211], v[102:105]
	v_mfma_f32_16x16x32_bf16 v[94:97], v[164:167], v[216:219], v[94:97]
	v_mfma_f32_16x16x32_bf16 v[86:89], v[172:175], v[216:219], v[86:89]
	v_mfma_f32_16x16x32_bf16 v[78:81], v[164:167], v[224:227], v[78:81]
	v_mfma_f32_16x16x32_bf16 v[70:73], v[172:175], v[224:227], v[70:73]
	v_mfma_f32_16x16x32_bf16 v[126:129], v[168:171], v[204:207], v[126:129]
	v_mfma_f32_16x16x32_bf16 v[118:121], v[176:179], v[204:207], v[118:121]
	v_mfma_f32_16x16x32_bf16 v[110:113], v[168:171], v[212:215], v[110:113]
	v_mfma_f32_16x16x32_bf16 v[102:105], v[176:179], v[212:215], v[102:105]
	v_mfma_f32_16x16x32_bf16 v[94:97], v[168:171], v[220:223], v[94:97]
	v_mfma_f32_16x16x32_bf16 v[86:89], v[176:179], v[220:223], v[86:89]
	v_mfma_f32_16x16x32_bf16 v[78:81], v[168:171], v[228:231], v[78:81]
	v_mfma_f32_16x16x32_bf16 v[70:73], v[176:179], v[228:231], v[70:73]
	v_mfma_f32_16x16x32_bf16 v[122:125], v[184:187], v[200:203], v[122:125]
	v_mfma_f32_16x16x32_bf16 v[114:117], v[192:195], v[200:203], v[114:117]
	v_mfma_f32_16x16x32_bf16 v[106:109], v[184:187], v[208:211], v[106:109]
	v_mfma_f32_16x16x32_bf16 v[98:101], v[192:195], v[208:211], v[98:101]
	v_mfma_f32_16x16x32_bf16 v[90:93], v[184:187], v[216:219], v[90:93]
	v_mfma_f32_16x16x32_bf16 v[82:85], v[192:195], v[216:219], v[82:85]
	v_mfma_f32_16x16x32_bf16 v[74:77], v[184:187], v[224:227], v[74:77]
	v_mfma_f32_16x16x32_bf16 v[66:69], v[192:195], v[224:227], v[66:69]
	v_mfma_f32_16x16x32_bf16 v[122:125], v[188:191], v[204:207], v[122:125]
	v_mfma_f32_16x16x32_bf16 v[114:117], v[196:199], v[204:207], v[114:117]
	v_mfma_f32_16x16x32_bf16 v[106:109], v[188:191], v[212:215], v[106:109]
	v_mfma_f32_16x16x32_bf16 v[98:101], v[196:199], v[212:215], v[98:101]
	v_mfma_f32_16x16x32_bf16 v[90:93], v[188:191], v[220:223], v[90:93]
	v_mfma_f32_16x16x32_bf16 v[82:85], v[196:199], v[220:223], v[82:85]
	v_mfma_f32_16x16x32_bf16 v[74:77], v[188:191], v[228:231], v[74:77]
	v_mfma_f32_16x16x32_bf16 v[66:69], v[196:199], v[228:231], v[66:69]
	s_barrier
; #define PG8_STAGE(bufoff, gbase, voff) do { _Pragma("unroll") for (int _i = 0; _i < 2; ++_i) \
;         __builtin_amdgcn_global_load_lds((const unsigned*)((const char*)(gbase) + (voff)[_i]), (LAS unsigned*)(lds + (bufoff) + ldsw + _i * 8192), 16, 0, 0); } while (0)
; #define PG8_LDA(dst, b, h) do { _Pragma("unroll") for (int m = 0; m < 4; ++m) _Pragma("unroll") for (int k = 0; k < 2; ++k) dst[m][k] = *(const LAS bf16x8*)(lds + PG8_SA(b, h) + aoff + m * 2048 + k * 1024); } while (0)
; #define PG8_MMA(ai, bj, At, Bt) do { __builtin_amdgcn_s_setprio(1); _Pragma("unroll") for (int m = 0; m < 4; ++m) _Pragma("unroll") for (int n = 0; n < 2; ++n) _Pragma("unroll") for (int k = 0; k < 2; ++k) \
;         acc[ai][bj][m][n] = __builtin_amdgcn_mfma_f32_16x16x32_bf16(Bt[n][k], At[m][k], acc[ai][bj][m][n], 0, 0, 0); __builtin_amdgcn_s_setprio(0); } while (0)
; #define PG8_WAIT_V(n) asm volatile("s_waitcnt vmcnt(" #n ")" ::: "memory")
; #define PG8_WAIT_L(n) asm volatile("s_waitcnt lgkmcnt(" #n ")" ::: "memory")
; #define PG8_BAR __builtin_amdgcn_s_barrier()
; #define PG8_SCHED __builtin_amdgcn_sched_barrier(0)
; template <class Epi, bool ALIGN_EPI = PG8_ALIGN, bool SP2 = PG8_SP2>
; __device__ __forceinline__ void gemm_phase(LAS uchar* lds, const Gemm g, const StaticOrder& S, const Epi& E) {
;     ...
;             PG8_LDA(At, 1, 1); PG8_STAGE(PG8_SB(1, 0), b3, voffB); PG8_STAGE(PG8_SB(1, 1), b3 + hstepB, voffB); PG8_STAGE(PG8_SA(1, 0), a3, voffA);
;             PG8_WAIT_V(8); PG8_WAIT_L(0); PG8_BAR; PG8_MMA(1, 0, At, B0); PG8_MMA(1, 1, At, B1); PG8_BAR; PG8_SCHED;
;     ...
;         if constexpr (ALIGN_EPI) { if (wr == 0) PG8_BAR; }
	s_setprio 0
	s_add_i32 s12, s39, s21
	v_lshl_add_u64 v[160:161], v[160:161], 0, s[84:85]
	s_mov_b32 m0, s12
	ds_read_b128 v[200:203], v163 offset:49152
	ds_read_b128 v[204:207], v163 offset:50176
	ds_read_b128 v[208:211], v163 offset:51200
	ds_read_b128 v[212:215], v163 offset:52224
	ds_read_b128 v[216:219], v163 offset:53248
	ds_read_b128 v[220:223], v163 offset:54272
	ds_read_b128 v[224:227], v163 offset:55296
	ds_read_b128 v[228:231], v163 offset:56320
	global_load_lds_dwordx4 v[160:161], off
	s_add_i32 m0, s12, 0x2000
	s_add_u32 s12, s16, 0x44080
	v_lshl_add_u64 v[160:161], v[180:181], 0, s[84:85]
	s_addc_u32 s13, s17, 0
	s_add_i32 s16, s40, s21
	global_load_lds_dwordx4 v[160:161], off
	s_mov_b32 m0, s16
	v_lshl_add_u64 v[160:161], s[12:13], 0, v[134:135]
	global_load_lds_dwordx4 v[160:161], off
	s_add_i32 m0, s16, 0x2000
	v_lshl_add_u64 v[160:161], s[12:13], 0, v[130:131]
	global_load_lds_dwordx4 v[160:161], off
	s_mov_b32 m0, s27
	v_lshl_add_u64 v[160:161], v[232:233], 0, s[84:85]
	global_load_lds_dwordx4 v[160:161], off
	s_mov_b32 m0, s28
	v_lshl_add_u64 v[160:161], v[234:235], 0, s[84:85]
	global_load_lds_dwordx4 v[160:161], off
	s_waitcnt vmcnt(8)
	s_waitcnt lgkmcnt(0)
	s_setprio 1
	s_barrier
	v_mfma_f32_16x16x32_bf16 v[62:65], v[164:167], v[200:203], v[62:65]
	v_mfma_f32_16x16x32_bf16 v[54:57], v[172:175], v[200:203], v[54:57]
	v_mfma_f32_16x16x32_bf16 v[46:49], v[164:167], v[208:211], v[46:49]
	v_mfma_f32_16x16x32_bf16 v[38:41], v[172:175], v[208:211], v[38:41]
	v_mfma_f32_16x16x32_bf16 v[30:33], v[164:167], v[216:219], v[30:33]
	v_mfma_f32_16x16x32_bf16 v[22:25], v[172:175], v[216:219], v[22:25]
	v_mfma_f32_16x16x32_bf16 v[14:17], v[164:167], v[224:227], v[14:17]
	v_mfma_f32_16x16x32_bf16 v[6:9], v[172:175], v[224:227], v[6:9]
	v_mfma_f32_16x16x32_bf16 v[62:65], v[168:171], v[204:207], v[62:65]
	v_mfma_f32_16x16x32_bf16 v[54:57], v[176:179], v[204:207], v[54:57]
	v_mfma_f32_16x16x32_bf16 v[46:49], v[168:171], v[212:215], v[46:49]
	v_mfma_f32_16x16x32_bf16 v[38:41], v[176:179], v[212:215], v[38:41]
	v_mfma_f32_16x16x32_bf16 v[30:33], v[168:171], v[220:223], v[30:33]
	v_mfma_f32_16x16x32_bf16 v[22:25], v[176:179], v[220:223], v[22:25]
	v_mfma_f32_16x16x32_bf16 v[14:17], v[168:171], v[228:231], v[14:17]
	v_mfma_f32_16x16x32_bf16 v[6:9], v[176:179], v[228:231], v[6:9]
	v_mfma_f32_16x16x32_bf16 v[58:61], v[184:187], v[200:203], v[58:61]
	v_mfma_f32_16x16x32_bf16 v[50:53], v[192:195], v[200:203], v[50:53]
	v_mfma_f32_16x16x32_bf16 v[42:45], v[184:187], v[208:211], v[42:45]
	v_mfma_f32_16x16x32_bf16 v[34:37], v[192:195], v[208:211], v[34:37]
	v_mfma_f32_16x16x32_bf16 v[26:29], v[184:187], v[216:219], v[26:29]
	v_mfma_f32_16x16x32_bf16 v[18:21], v[192:195], v[216:219], v[18:21]
	v_mfma_f32_16x16x32_bf16 v[10:13], v[184:187], v[224:227], v[10:13]
	v_mfma_f32_16x16x32_bf16 v[2:5], v[192:195], v[224:227], v[2:5]
	v_mfma_f32_16x16x32_bf16 v[58:61], v[188:191], v[204:207], v[58:61]
	v_mfma_f32_16x16x32_bf16 v[50:53], v[196:199], v[204:207], v[50:53]
	v_mfma_f32_16x16x32_bf16 v[42:45], v[188:191], v[212:215], v[42:45]
	v_mfma_f32_16x16x32_bf16 v[34:37], v[196:199], v[212:215], v[34:37]
	v_mfma_f32_16x16x32_bf16 v[26:29], v[188:191], v[220:223], v[26:29]
	v_mfma_f32_16x16x32_bf16 v[18:21], v[196:199], v[220:223], v[18:21]
	v_mfma_f32_16x16x32_bf16 v[10:13], v[188:191], v[228:231], v[10:13]
	v_mfma_f32_16x16x32_bf16 v[2:5], v[196:199], v[228:231], v[2:5]
	s_barrier
	s_setprio 0
	s_add_i32 s38, s38, 2
	s_add_u32 s36, s36, 0x100
	s_addc_u32 s37, s37, 0
	s_cmp_gt_u32 s38, 13
	s_mov_b64 s[12:13], s[14:15]
	s_cbranch_scc0 .LBB0_1050
	s_and_b64 vcc, exec, s[8:9]
	s_cbranch_vccz .LBB0_1053
	s_barrier

; #define PG8_STAGE(bufoff, gbase, voff) do { _Pragma("unroll") for (int _i = 0; _i < 2; ++_i) \
;         __builtin_amdgcn_global_load_lds((const unsigned*)((const char*)(gbase) + (voff)[_i]), (LAS unsigned*)(lds + (bufoff) + ldsw + _i * 8192), 16, 0, 0); } while (0)
; #define PG8_LDA(dst, b, h) do { _Pragma("unroll") for (int m = 0; m < 4; ++m) _Pragma("unroll") for (int k = 0; k < 2; ++k) dst[m][k] = *(const LAS bf16x8*)(lds + PG8_SA(b, h) + aoff + m * 2048 + k * 1024); } while (0)
; #define PG8_LDB(dst, b, h) do { _Pragma("unroll") for (int n = 0; n < 2; ++n) _Pragma("unroll") for (int k = 0; k < 2; ++k) dst[n][k] = *(const LAS bf16x8*)(lds + PG8_SB(b, h) + boff + n * 2048 + k * 1024); } while (0)
; #define PG8_MMA(ai, bj, At, Bt) do { __builtin_amdgcn_s_setprio(1); _Pragma("unroll") for (int m = 0; m < 4; ++m) _Pragma("unroll") for (int n = 0; n < 2; ++n) _Pragma("unroll") for (int k = 0; k < 2; ++k) \
;         acc[ai][bj][m][n] = __builtin_amdgcn_mfma_f32_16x16x32_bf16(Bt[n][k], At[m][k], acc[ai][bj][m][n], 0, 0, 0); __builtin_amdgcn_s_setprio(0); } while (0)
; #define PG8_WAIT_V(n) asm volatile("s_waitcnt vmcnt(" #n ")" ::: "memory")
; #define PG8_WAIT_L(n) asm volatile("s_waitcnt lgkmcnt(" #n ")" ::: "memory")
; #define PG8_BAR __builtin_amdgcn_s_barrier()
; #define PG8_SCHED __builtin_amdgcn_sched_barrier(0)
; template <class Epi, bool ALIGN_EPI = PG8_ALIGN, bool SP2 = PG8_SP2>
; __device__ __forceinline__ void gemm_phase(LAS uchar* lds, const Gemm g, const StaticOrder& S, const Epi& E) {
;     ...
;             const bool last = (t == nt - 2);
;             const char* a1 = cA + (size_t)(t + 1) * kstep;
;             const char* a2 = last ? nA : cA + (size_t)(t + 2) * kstep; const char* b2 = last ? nB : cB + (size_t)(t + 2) * kstep;
;             const char* a3 = a2 + kstep; const char* b3 = b2 + kstep;
;             if constexpr (SP2) {
;             PG8_LDB(B0, 0, 0); PG8_LDB(B1, 0, 1); PG8_SCHED; PG8_LDA(At, 0, 0); PG8_STAGE(PG8_SA(1, 1), a1 + hstepA, voffA);
;             PG8_WAIT_V(8); PG8_WAIT_L(0); PG8_BAR; PG8_MMA(0, 0, At, B0); PG8_MMA(0, 1, At, B1); PG8_BAR; PG8_SCHED;
;             PG8_LDA(At, 0, 1); PG8_STAGE(PG8_SB(0, 0), b2, voffB); PG8_STAGE(PG8_SB(0, 1), b2 + hstepB, voffB); PG8_STAGE(PG8_SA(0, 0), a2, voffA);
;             PG8_WAIT_V(8); PG8_WAIT_L(0); PG8_BAR; PG8_MMA(1, 0, At, B0); PG8_MMA(1, 1, At, B1); PG8_BAR; PG8_SCHED;
.LBB0_1142:
	s_add_u32 s38, s16, 0x100
	s_addc_u32 s39, s17, 0
	s_mov_b32 s40, -2
	s_add_u32 s16, s14, 0x100
	s_addc_u32 s17, s15, 0
	s_add_i32 s41, 0, 0x10000
	s_cmp_eq_u32 s40, 40
	s_cselect_b32 s21, s5, s17
	s_cselect_b32 s20, s4, s16
	v_add_u32_e32 v144, s41, v139
	s_cselect_b32 s19, s13, s39
	s_cselect_b32 s18, s12, s38
	s_add_i32 s42, 0, 0x14000
	ds_read_b128 v[160:163], v144
	ds_read_b128 v[166:169], v144 offset:1024
	ds_read_b128 v[170:173], v144 offset:2048
	ds_read_b128 v[174:177], v144 offset:3072
	v_add_u32_e32 v144, s42, v139
	ds_read_b128 v[178:181], v144
	ds_read_b128 v[184:187], v144 offset:1024
	ds_read_b128 v[188:191], v144 offset:2048
	ds_read_b128 v[192:195], v144 offset:3072
	v_lshl_add_u64 v[228:229], s[14:15], 0, v[156:157]
	s_add_i32 m0, s25, 0xc000
	ds_read_b128 v[196:199], v165
	ds_read_b128 v[200:203], v165 offset:1024
	ds_read_b128 v[204:207], v165 offset:2048
	ds_read_b128 v[208:211], v165 offset:3072
	ds_read_b128 v[212:215], v165 offset:4096
	ds_read_b128 v[216:219], v165 offset:5120
	ds_read_b128 v[220:223], v165 offset:6144
	ds_read_b128 v[224:227], v165 offset:7168
	global_load_lds_dwordx4 v[228:229], off
	s_add_i32 m0, s25, 0xe000
	v_lshl_add_u64 v[228:229], s[14:15], 0, v[158:159]
	global_load_lds_dwordx4 v[228:229], off
	s_waitcnt vmcnt(8)
	s_waitcnt lgkmcnt(0)
	s_setprio 1
	s_barrier
	v_mfma_f32_16x16x32_bf16 v[126:129], v[160:163], v[196:199], 0
	v_mfma_f32_16x16x32_bf16 v[122:125], v[170:173], v[196:199], 0
	v_mfma_f32_16x16x32_bf16 v[118:121], v[160:163], v[204:207], 0
	v_mfma_f32_16x16x32_bf16 v[110:113], v[170:173], v[204:207], 0
	v_mfma_f32_16x16x32_bf16 v[102:105], v[160:163], v[212:215], 0
	v_mfma_f32_16x16x32_bf16 v[94:97], v[170:173], v[212:215], 0
	v_mfma_f32_16x16x32_bf16 v[86:89], v[160:163], v[220:223], 0
	v_mfma_f32_16x16x32_bf16 v[78:81], v[170:173], v[220:223], 0
	v_mfma_f32_16x16x32_bf16 v[126:129], v[166:169], v[200:203], v[126:129]
	v_mfma_f32_16x16x32_bf16 v[122:125], v[174:177], v[200:203], v[122:125]
	v_mfma_f32_16x16x32_bf16 v[118:121], v[166:169], v[208:211], v[118:121]
	v_mfma_f32_16x16x32_bf16 v[110:113], v[174:177], v[208:211], v[110:113]
	v_mfma_f32_16x16x32_bf16 v[102:105], v[166:169], v[216:219], v[102:105]
	v_mfma_f32_16x16x32_bf16 v[94:97], v[174:177], v[216:219], v[94:97]
	v_mfma_f32_16x16x32_bf16 v[86:89], v[166:169], v[224:227], v[86:89]
	v_mfma_f32_16x16x32_bf16 v[78:81], v[174:177], v[224:227], v[78:81]
	v_mfma_f32_16x16x32_bf16 v[114:117], v[178:181], v[196:199], 0
	v_mfma_f32_16x16x32_bf16 v[106:109], v[188:191], v[196:199], 0
	v_mfma_f32_16x16x32_bf16 v[98:101], v[178:181], v[204:207], 0
	v_mfma_f32_16x16x32_bf16 v[90:93], v[188:191], v[204:207], 0
	v_mfma_f32_16x16x32_bf16 v[82:85], v[178:181], v[212:215], 0
	v_mfma_f32_16x16x32_bf16 v[74:77], v[188:191], v[212:215], 0
	v_mfma_f32_16x16x32_bf16 v[70:73], v[178:181], v[220:223], 0
	v_mfma_f32_16x16x32_bf16 v[66:69], v[188:191], v[220:223], 0
	v_mfma_f32_16x16x32_bf16 v[114:117], v[184:187], v[200:203], v[114:117]
	v_mfma_f32_16x16x32_bf16 v[106:109], v[192:195], v[200:203], v[106:109]
	v_mfma_f32_16x16x32_bf16 v[98:101], v[184:187], v[208:211], v[98:101]
	v_mfma_f32_16x16x32_bf16 v[90:93], v[192:195], v[208:211], v[90:93]
	v_mfma_f32_16x16x32_bf16 v[82:85], v[184:187], v[216:219], v[82:85]
	v_mfma_f32_16x16x32_bf16 v[74:77], v[192:195], v[216:219], v[74:77]
	v_mfma_f32_16x16x32_bf16 v[70:73], v[184:187], v[224:227], v[70:73]
	v_mfma_f32_16x16x32_bf16 v[66:69], v[192:195], v[224:227], v[66:69]
	s_barrier
	s_setprio 0
	s_add_i32 s14, s41, s24
	v_lshl_add_u64 v[228:229], s[18:19], 0, v[132:133]
	s_mov_b32 m0, s14
	ds_read_b128 v[196:199], v165 offset:16384
	ds_read_b128 v[200:203], v165 offset:17408
	ds_read_b128 v[204:207], v165 offset:18432
	ds_read_b128 v[208:211], v165 offset:19456
	ds_read_b128 v[212:215], v165 offset:20480
	ds_read_b128 v[216:219], v165 offset:21504
	ds_read_b128 v[220:223], v165 offset:22528
	ds_read_b128 v[224:227], v165 offset:23552
	global_load_lds_dwordx4 v[228:229], off
	s_add_i32 m0, s14, 0x2000
	s_add_u32 s14, s18, 0xb0000
	v_lshl_add_u64 v[230:231], s[18:19], 0, v[154:155]
	s_addc_u32 s15, s19, 0
	s_add_i32 s41, s42, s24
	global_load_lds_dwordx4 v[230:231], off
	s_mov_b32 m0, s41
	v_lshl_add_u64 v[232:233], s[14:15], 0, v[132:133]
	global_load_lds_dwordx4 v[232:233], off
	s_add_i32 m0, s41, 0x2000
	v_lshl_add_u64 v[232:233], s[14:15], 0, v[154:155]
	global_load_lds_dwordx4 v[232:233], off
	s_mov_b32 m0, s25
	v_lshl_add_u64 v[232:233], s[20:21], 0, v[130:131]
	global_load_lds_dwordx4 v[232:233], off
	s_mov_b32 m0, s26
	v_lshl_add_u64 v[234:235], s[20:21], 0, v[134:135]
	global_load_lds_dwordx4 v[234:235], off
	s_waitcnt vmcnt(8)
	s_waitcnt lgkmcnt(0)
	s_setprio 1
	s_barrier
; #define PG8_STAGE(bufoff, gbase, voff) do { _Pragma("unroll") for (int _i = 0; _i < 2; ++_i) \
;         __builtin_amdgcn_global_load_lds((const unsigned*)((const char*)(gbase) + (voff)[_i]), (LAS unsigned*)(lds + (bufoff) + ldsw + _i * 8192), 16, 0, 0); } while (0)
; #define PG8_LDA(dst, b, h) do { _Pragma("unroll") for (int m = 0; m < 4; ++m) _Pragma("unroll") for (int k = 0; k < 2; ++k) dst[m][k] = *(const LAS bf16x8*)(lds + PG8_SA(b, h) + aoff + m * 2048 + k * 1024); } while (0)
; #define PG8_LDB(dst, b, h) do { _Pragma("unroll") for (int n = 0; n < 2; ++n) _Pragma("unroll") for (int k = 0; k < 2; ++k) dst[n][k] = *(const LAS bf16x8*)(lds + PG8_SB(b, h) + boff + n * 2048 + k * 1024); } while (0)
; #define PG8_MMA(ai, bj, At, Bt) do { __builtin_amdgcn_s_setprio(1); _Pragma("unroll") for (int m = 0; m < 4; ++m) _Pragma("unroll") for (int n = 0; n < 2; ++n) _Pragma("unroll") for (int k = 0; k < 2; ++k) \
;         acc[ai][bj][m][n] = __builtin_amdgcn_mfma_f32_16x16x32_bf16(Bt[n][k], At[m][k], acc[ai][bj][m][n], 0, 0, 0); __builtin_amdgcn_s_setprio(0); } while (0)
; #define PG8_WAIT_V(n) asm volatile("s_waitcnt vmcnt(" #n ")" ::: "memory")
; #define PG8_WAIT_L(n) asm volatile("s_waitcnt lgkmcnt(" #n ")" ::: "memory")
; #define PG8_BAR __builtin_amdgcn_s_barrier()
; #define PG8_SCHED __builtin_amdgcn_sched_barrier(0)
; template <class Epi, bool ALIGN_EPI = PG8_ALIGN, bool SP2 = PG8_SP2>
; __device__ __forceinline__ void gemm_phase(LAS uchar* lds, const Gemm g, const StaticOrder& S, const Epi& E) {
;     ...
;             PG8_WAIT_V(8); PG8_WAIT_L(0); PG8_BAR; PG8_MMA(1, 0, At, B0); PG8_MMA(1, 1, At, B1); PG8_BAR; PG8_SCHED;
;             PG8_LDB(B0, 1, 0); PG8_LDB(B1, 1, 1); PG8_SCHED; PG8_LDA(At, 1, 0); PG8_STAGE(PG8_SA(0, 1), a2 + hstepA, voffA);
;             PG8_WAIT_V(8); PG8_WAIT_L(0); PG8_BAR; PG8_MMA(0, 0, At, B0); PG8_MMA(0, 1, At, B1); PG8_BAR; PG8_SCHED;
	v_mfma_f32_16x16x32_bf16 v[62:65], v[160:163], v[196:199], 0
	v_mfma_f32_16x16x32_bf16 v[58:61], v[170:173], v[196:199], 0
	v_mfma_f32_16x16x32_bf16 v[54:57], v[160:163], v[204:207], 0
	v_mfma_f32_16x16x32_bf16 v[46:49], v[170:173], v[204:207], 0
	v_mfma_f32_16x16x32_bf16 v[38:41], v[160:163], v[212:215], 0
	v_mfma_f32_16x16x32_bf16 v[30:33], v[170:173], v[212:215], 0
	v_mfma_f32_16x16x32_bf16 v[22:25], v[160:163], v[220:223], 0
	v_mfma_f32_16x16x32_bf16 v[14:17], v[170:173], v[220:223], 0
	v_mfma_f32_16x16x32_bf16 v[62:65], v[166:169], v[200:203], v[62:65]
	v_mfma_f32_16x16x32_bf16 v[58:61], v[174:177], v[200:203], v[58:61]
	v_mfma_f32_16x16x32_bf16 v[54:57], v[166:169], v[208:211], v[54:57]
	v_mfma_f32_16x16x32_bf16 v[46:49], v[174:177], v[208:211], v[46:49]
	v_mfma_f32_16x16x32_bf16 v[38:41], v[166:169], v[216:219], v[38:41]
	v_mfma_f32_16x16x32_bf16 v[30:33], v[174:177], v[216:219], v[30:33]
	v_mfma_f32_16x16x32_bf16 v[22:25], v[166:169], v[224:227], v[22:25]
	v_mfma_f32_16x16x32_bf16 v[14:17], v[174:177], v[224:227], v[14:17]
	v_mfma_f32_16x16x32_bf16 v[50:53], v[178:181], v[196:199], 0
	v_mfma_f32_16x16x32_bf16 v[42:45], v[188:191], v[196:199], 0
	v_mfma_f32_16x16x32_bf16 v[34:37], v[178:181], v[204:207], 0
	v_mfma_f32_16x16x32_bf16 v[26:29], v[188:191], v[204:207], 0
	v_mfma_f32_16x16x32_bf16 v[18:21], v[178:181], v[212:215], 0
	v_mfma_f32_16x16x32_bf16 v[10:13], v[188:191], v[212:215], 0
	v_mfma_f32_16x16x32_bf16 v[6:9], v[178:181], v[220:223], 0
	v_mfma_f32_16x16x32_bf16 v[2:5], v[188:191], v[220:223], 0
	v_mfma_f32_16x16x32_bf16 v[50:53], v[184:187], v[200:203], v[50:53]
	v_mfma_f32_16x16x32_bf16 v[42:45], v[192:195], v[200:203], v[42:45]
	v_mfma_f32_16x16x32_bf16 v[34:37], v[184:187], v[208:211], v[34:37]
	v_mfma_f32_16x16x32_bf16 v[26:29], v[192:195], v[208:211], v[26:29]
	v_mfma_f32_16x16x32_bf16 v[18:21], v[184:187], v[216:219], v[18:21]
	v_mfma_f32_16x16x32_bf16 v[10:13], v[192:195], v[216:219], v[10:13]
	v_mfma_f32_16x16x32_bf16 v[6:9], v[184:187], v[224:227], v[6:9]
	v_mfma_f32_16x16x32_bf16 v[2:5], v[192:195], v[224:227], v[2:5]
	s_barrier
	s_setprio 0
	s_add_i32 s41, 0, 0x18000
	v_add_u32_e32 v144, s41, v139
	s_add_i32 s42, 0, 0x1c000
	ds_read_b128 v[160:163], v144
	ds_read_b128 v[166:169], v144 offset:1024
	ds_read_b128 v[170:173], v144 offset:2048
	ds_read_b128 v[174:177], v144 offset:3072
	v_add_u32_e32 v144, s42, v139
	ds_read_b128 v[178:181], v144
	ds_read_b128 v[184:187], v144 offset:1024
	ds_read_b128 v[188:191], v144 offset:2048
	ds_read_b128 v[192:195], v144 offset:3072
	s_add_u32 s14, s20, 0xb0000
	s_addc_u32 s15, s21, 0
	s_mov_b32 m0, s27
	v_lshl_add_u64 v[236:237], s[14:15], 0, v[130:131]
	ds_read_b128 v[196:199], v165 offset:32768
	ds_read_b128 v[200:203], v165 offset:33792
	ds_read_b128 v[204:207], v165 offset:34816
	ds_read_b128 v[208:211], v165 offset:35840
	ds_read_b128 v[212:215], v165 offset:36864
	ds_read_b128 v[216:219], v165 offset:37888
	ds_read_b128 v[220:223], v165 offset:38912
	ds_read_b128 v[224:227], v165 offset:39936
	global_load_lds_dwordx4 v[236:237], off
	s_mov_b32 m0, s28
	v_lshl_add_u64 v[236:237], s[14:15], 0, v[134:135]
	global_load_lds_dwordx4 v[236:237], off
	s_waitcnt vmcnt(8)
	s_waitcnt lgkmcnt(0)
	s_setprio 1
	s_barrier
	v_mfma_f32_16x16x32_bf16 v[126:129], v[160:163], v[196:199], v[126:129]
	v_mfma_f32_16x16x32_bf16 v[122:125], v[170:173], v[196:199], v[122:125]
	v_mfma_f32_16x16x32_bf16 v[118:121], v[160:163], v[204:207], v[118:121]
	v_mfma_f32_16x16x32_bf16 v[110:113], v[170:173], v[204:207], v[110:113]
	v_mfma_f32_16x16x32_bf16 v[102:105], v[160:163], v[212:215], v[102:105]
	v_mfma_f32_16x16x32_bf16 v[94:97], v[170:173], v[212:215], v[94:97]
	v_mfma_f32_16x16x32_bf16 v[86:89], v[160:163], v[220:223], v[86:89]
	v_mfma_f32_16x16x32_bf16 v[78:81], v[170:173], v[220:223], v[78:81]
	v_mfma_f32_16x16x32_bf16 v[126:129], v[166:169], v[200:203], v[126:129]
	v_mfma_f32_16x16x32_bf16 v[122:125], v[174:177], v[200:203], v[122:125]
	v_mfma_f32_16x16x32_bf16 v[118:121], v[166:169], v[208:211], v[118:121]
	v_mfma_f32_16x16x32_bf16 v[110:113], v[174:177], v[208:211], v[110:113]
	v_mfma_f32_16x16x32_bf16 v[102:105], v[166:169], v[216:219], v[102:105]
	v_mfma_f32_16x16x32_bf16 v[94:97], v[174:177], v[216:219], v[94:97]
	v_mfma_f32_16x16x32_bf16 v[86:89], v[166:169], v[224:227], v[86:89]
	v_mfma_f32_16x16x32_bf16 v[78:81], v[174:177], v[224:227], v[78:81]
	v_mfma_f32_16x16x32_bf16 v[114:117], v[178:181], v[196:199], v[114:117]
	v_mfma_f32_16x16x32_bf16 v[106:109], v[188:191], v[196:199], v[106:109]
	v_mfma_f32_16x16x32_bf16 v[98:101], v[178:181], v[204:207], v[98:101]
	v_mfma_f32_16x16x32_bf16 v[90:93], v[188:191], v[204:207], v[90:93]
	v_mfma_f32_16x16x32_bf16 v[82:85], v[178:181], v[212:215], v[82:85]
	v_mfma_f32_16x16x32_bf16 v[74:77], v[188:191], v[212:215], v[74:77]
	v_mfma_f32_16x16x32_bf16 v[70:73], v[178:181], v[220:223], v[70:73]
	v_mfma_f32_16x16x32_bf16 v[66:69], v[188:191], v[220:223], v[66:69]
	v_mfma_f32_16x16x32_bf16 v[114:117], v[184:187], v[200:203], v[114:117]
	v_mfma_f32_16x16x32_bf16 v[106:109], v[192:195], v[200:203], v[106:109]
	v_mfma_f32_16x16x32_bf16 v[98:101], v[184:187], v[208:211], v[98:101]
	v_mfma_f32_16x16x32_bf16 v[90:93], v[192:195], v[208:211], v[90:93]
	v_mfma_f32_16x16x32_bf16 v[82:85], v[184:187], v[216:219], v[82:85]
	v_mfma_f32_16x16x32_bf16 v[74:77], v[192:195], v[216:219], v[74:77]
	v_mfma_f32_16x16x32_bf16 v[70:73], v[184:187], v[224:227], v[70:73]
	v_mfma_f32_16x16x32_bf16 v[66:69], v[192:195], v[224:227], v[66:69]
	s_barrier
; #define PG8_STAGE(bufoff, gbase, voff) do { _Pragma("unroll") for (int _i = 0; _i < 2; ++_i) \
;         __builtin_amdgcn_global_load_lds((const unsigned*)((const char*)(gbase) + (voff)[_i]), (LAS unsigned*)(lds + (bufoff) + ldsw + _i * 8192), 16, 0, 0); } while (0)
; #define PG8_LDA(dst, b, h) do { _Pragma("unroll") for (int m = 0; m < 4; ++m) _Pragma("unroll") for (int k = 0; k < 2; ++k) dst[m][k] = *(const LAS bf16x8*)(lds + PG8_SA(b, h) + aoff + m * 2048 + k * 1024); } while (0)
; #define PG8_LDB(dst, b, h) do { _Pragma("unroll") for (int n = 0; n < 2; ++n) _Pragma("unroll") for (int k = 0; k < 2; ++k) dst[n][k] = *(const LAS bf16x8*)(lds + PG8_SB(b, h) + boff + n * 2048 + k * 1024); } while (0)
; #define PG8_MMA(ai, bj, At, Bt) do { __builtin_amdgcn_s_setprio(1); _Pragma("unroll") for (int m = 0; m < 4; ++m) _Pragma("unroll") for (int n = 0; n < 2; ++n) _Pragma("unroll") for (int k = 0; k < 2; ++k) \
;         acc[ai][bj][m][n] = __builtin_amdgcn_mfma_f32_16x16x32_bf16(Bt[n][k], At[m][k], acc[ai][bj][m][n], 0, 0, 0); __builtin_amdgcn_s_setprio(0); } while (0)
; #define PG8_WAIT_V(n) asm volatile("s_waitcnt vmcnt(" #n ")" ::: "memory")
; #define PG8_WAIT_L(n) asm volatile("s_waitcnt lgkmcnt(" #n ")" ::: "memory")
; #define PG8_BAR __builtin_amdgcn_s_barrier()
; #define PG8_SCHED __builtin_amdgcn_sched_barrier(0)
; template <class Epi, bool ALIGN_EPI = PG8_ALIGN, bool SP2 = PG8_SP2>
; __device__ __forceinline__ void gemm_phase(LAS uchar* lds, const Gemm g, const StaticOrder& S, const Epi& E) {
;     ...
;             const bool last = (t == nt - 2);
;             const char* a1 = cA + (size_t)(t + 1) * kstep;
;             const char* a2 = last ? nA : cA + (size_t)(t + 2) * kstep; const char* b2 = last ? nB : cB + (size_t)(t + 2) * kstep;
;             const char* a3 = a2 + kstep; const char* b3 = b2 + kstep;
;             if constexpr (SP2) {
;             PG8_LDB(B0, 0, 0); PG8_LDB(B1, 0, 1); PG8_SCHED; PG8_LDA(At, 0, 0); PG8_STAGE(PG8_SA(1, 1), a1 + hstepA, voffA);
;             PG8_WAIT_V(8); PG8_WAIT_L(0); PG8_BAR; PG8_MMA(0, 0, At, B0); PG8_MMA(0, 1, At, B1); PG8_BAR; PG8_SCHED;
;     ...
;             PG8_LDA(At, 1, 1); PG8_STAGE(PG8_SB(1, 0), b3, voffB); PG8_STAGE(PG8_SB(1, 1), b3 + hstepB, voffB); PG8_STAGE(PG8_SA(1, 0), a3, voffA);
;             PG8_WAIT_V(8); PG8_WAIT_L(0); PG8_BAR; PG8_MMA(1, 0, At, B0); PG8_MMA(1, 1, At, B1); PG8_BAR; PG8_SCHED;
	s_setprio 0
	s_add_i32 s14, s41, s24
	v_lshl_add_u64 v[228:229], v[228:229], 0, s[84:85]
	s_mov_b32 m0, s14
	ds_read_b128 v[196:199], v165 offset:49152
	ds_read_b128 v[200:203], v165 offset:50176
	ds_read_b128 v[204:207], v165 offset:51200
	ds_read_b128 v[208:211], v165 offset:52224
	ds_read_b128 v[212:215], v165 offset:53248
	ds_read_b128 v[216:219], v165 offset:54272
	ds_read_b128 v[220:223], v165 offset:55296
	ds_read_b128 v[224:227], v165 offset:56320
	global_load_lds_dwordx4 v[228:229], off
	s_add_i32 m0, s14, 0x2000
	s_add_u32 s14, s18, 0xb0080
	v_lshl_add_u64 v[228:229], v[230:231], 0, s[84:85]
	s_addc_u32 s15, s19, 0
	s_add_i32 s18, s42, s24
	global_load_lds_dwordx4 v[228:229], off
	s_mov_b32 m0, s18
	v_lshl_add_u64 v[228:229], s[14:15], 0, v[132:133]
	global_load_lds_dwordx4 v[228:229], off
	s_add_i32 m0, s18, 0x2000
	v_lshl_add_u64 v[228:229], s[14:15], 0, v[154:155]
	global_load_lds_dwordx4 v[228:229], off
	s_mov_b32 m0, s29
	v_lshl_add_u64 v[228:229], v[232:233], 0, s[84:85]
	global_load_lds_dwordx4 v[228:229], off
	s_mov_b32 m0, s30
	v_lshl_add_u64 v[228:229], v[234:235], 0, s[84:85]
	global_load_lds_dwordx4 v[228:229], off
	s_waitcnt vmcnt(8)
	s_waitcnt lgkmcnt(0)
	s_setprio 1
	s_barrier
	v_mfma_f32_16x16x32_bf16 v[62:65], v[160:163], v[196:199], v[62:65]
	v_mfma_f32_16x16x32_bf16 v[58:61], v[170:173], v[196:199], v[58:61]
	v_mfma_f32_16x16x32_bf16 v[54:57], v[160:163], v[204:207], v[54:57]
	v_mfma_f32_16x16x32_bf16 v[46:49], v[170:173], v[204:207], v[46:49]
	v_mfma_f32_16x16x32_bf16 v[38:41], v[160:163], v[212:215], v[38:41]
	v_mfma_f32_16x16x32_bf16 v[30:33], v[170:173], v[212:215], v[30:33]
	v_mfma_f32_16x16x32_bf16 v[22:25], v[160:163], v[220:223], v[22:25]
	v_mfma_f32_16x16x32_bf16 v[14:17], v[170:173], v[220:223], v[14:17]
	v_mfma_f32_16x16x32_bf16 v[62:65], v[166:169], v[200:203], v[62:65]
	v_mfma_f32_16x16x32_bf16 v[58:61], v[174:177], v[200:203], v[58:61]
	v_mfma_f32_16x16x32_bf16 v[54:57], v[166:169], v[208:211], v[54:57]
	v_mfma_f32_16x16x32_bf16 v[46:49], v[174:177], v[208:211], v[46:49]
	v_mfma_f32_16x16x32_bf16 v[38:41], v[166:169], v[216:219], v[38:41]
	v_mfma_f32_16x16x32_bf16 v[30:33], v[174:177], v[216:219], v[30:33]
	v_mfma_f32_16x16x32_bf16 v[22:25], v[166:169], v[224:227], v[22:25]
	v_mfma_f32_16x16x32_bf16 v[14:17], v[174:177], v[224:227], v[14:17]
	v_mfma_f32_16x16x32_bf16 v[50:53], v[178:181], v[196:199], v[50:53]
	v_mfma_f32_16x16x32_bf16 v[42:45], v[188:191], v[196:199], v[42:45]
	v_mfma_f32_16x16x32_bf16 v[34:37], v[178:181], v[204:207], v[34:37]
	v_mfma_f32_16x16x32_bf16 v[26:29], v[188:191], v[204:207], v[26:29]
	v_mfma_f32_16x16x32_bf16 v[18:21], v[178:181], v[212:215], v[18:21]
	v_mfma_f32_16x16x32_bf16 v[10:13], v[188:191], v[212:215], v[10:13]
	v_mfma_f32_16x16x32_bf16 v[6:9], v[178:181], v[220:223], v[6:9]
	v_mfma_f32_16x16x32_bf16 v[2:5], v[188:191], v[220:223], v[2:5]
	v_mfma_f32_16x16x32_bf16 v[50:53], v[184:187], v[200:203], v[50:53]
	v_mfma_f32_16x16x32_bf16 v[42:45], v[192:195], v[200:203], v[42:45]
	v_mfma_f32_16x16x32_bf16 v[34:37], v[184:187], v[208:211], v[34:37]
	v_mfma_f32_16x16x32_bf16 v[26:29], v[192:195], v[208:211], v[26:29]
	v_mfma_f32_16x16x32_bf16 v[18:21], v[184:187], v[216:219], v[18:21]
	v_mfma_f32_16x16x32_bf16 v[10:13], v[192:195], v[216:219], v[10:13]
	v_mfma_f32_16x16x32_bf16 v[6:9], v[184:187], v[224:227], v[6:9]
	v_mfma_f32_16x16x32_bf16 v[2:5], v[192:195], v[224:227], v[2:5]
	s_barrier
	s_setprio 0
	s_add_i32 s40, s40, 2
	s_add_u32 s38, s38, 0x100
	s_addc_u32 s39, s39, 0
	s_cmp_gt_u32 s40, 41
	s_mov_b64 s[14:15], s[16:17]
.LBB0_1143:
	s_add_u32 s16, s14, 0x100
	s_addc_u32 s17, s15, 0
	s_add_i32 s41, 0, 0x10000
	s_cmp_eq_u32 s40, 40
	s_cselect_b32 s21, s5, s17
	s_cselect_b32 s20, s4, s16
	v_add_u32_e32 v144, s41, v139
	s_cselect_b32 s19, s13, s39
	s_cselect_b32 s18, s12, s38
	s_add_i32 s42, 0, 0x14000
	ds_read_b128 v[160:163], v144
	ds_read_b128 v[166:169], v144 offset:1024
	ds_read_b128 v[170:173], v144 offset:2048
	ds_read_b128 v[174:177], v144 offset:3072
	v_add_u32_e32 v144, s42, v139
	ds_read_b128 v[178:181], v144
	ds_read_b128 v[184:187], v144 offset:1024
	ds_read_b128 v[188:191], v144 offset:2048
	ds_read_b128 v[192:195], v144 offset:3072
	v_lshl_add_u64 v[228:229], s[14:15], 0, v[156:157]
	s_add_i32 m0, s25, 0xc000
	ds_read_b128 v[196:199], v165
	ds_read_b128 v[200:203], v165 offset:1024
	ds_read_b128 v[204:207], v165 offset:2048
	ds_read_b128 v[208:211], v165 offset:3072
	ds_read_b128 v[212:215], v165 offset:4096
	ds_read_b128 v[216:219], v165 offset:5120
	ds_read_b128 v[220:223], v165 offset:6144
	ds_read_b128 v[224:227], v165 offset:7168
	global_load_lds_dwordx4 v[228:229], off
	s_add_i32 m0, s25, 0xe000
	v_lshl_add_u64 v[228:229], s[14:15], 0, v[158:159]
	global_load_lds_dwordx4 v[228:229], off
	s_waitcnt vmcnt(8)
	s_waitcnt lgkmcnt(0)
	s_setprio 1
	s_barrier
; #define PG8_STAGE(bufoff, gbase, voff) do { _Pragma("unroll") for (int _i = 0; _i < 2; ++_i) \
;         __builtin_amdgcn_global_load_lds((const unsigned*)((const char*)(gbase) + (voff)[_i]), (LAS unsigned*)(lds + (bufoff) + ldsw + _i * 8192), 16, 0, 0); } while (0)
; #define PG8_LDA(dst, b, h) do { _Pragma("unroll") for (int m = 0; m < 4; ++m) _Pragma("unroll") for (int k = 0; k < 2; ++k) dst[m][k] = *(const LAS bf16x8*)(lds + PG8_SA(b, h) + aoff + m * 2048 + k * 1024); } while (0)
; #define PG8_MMA(ai, bj, At, Bt) do { __builtin_amdgcn_s_setprio(1); _Pragma("unroll") for (int m = 0; m < 4; ++m) _Pragma("unroll") for (int n = 0; n < 2; ++n) _Pragma("unroll") for (int k = 0; k < 2; ++k) \
;         acc[ai][bj][m][n] = __builtin_amdgcn_mfma_f32_16x16x32_bf16(Bt[n][k], At[m][k], acc[ai][bj][m][n], 0, 0, 0); __builtin_amdgcn_s_setprio(0); } while (0)
; #define PG8_WAIT_V(n) asm volatile("s_waitcnt vmcnt(" #n ")" ::: "memory")
; #define PG8_WAIT_L(n) asm volatile("s_waitcnt lgkmcnt(" #n ")" ::: "memory")
; #define PG8_BAR __builtin_amdgcn_s_barrier()
; #define PG8_SCHED __builtin_amdgcn_sched_barrier(0)
; template <class Epi, bool ALIGN_EPI = PG8_ALIGN, bool SP2 = PG8_SP2>
; __device__ __forceinline__ void gemm_phase(LAS uchar* lds, const Gemm g, const StaticOrder& S, const Epi& E) {
;     ...
;             PG8_WAIT_V(8); PG8_WAIT_L(0); PG8_BAR; PG8_MMA(0, 0, At, B0); PG8_MMA(0, 1, At, B1); PG8_BAR; PG8_SCHED;
;             PG8_LDA(At, 0, 1); PG8_STAGE(PG8_SB(0, 0), b2, voffB); PG8_STAGE(PG8_SB(0, 1), b2 + hstepB, voffB); PG8_STAGE(PG8_SA(0, 0), a2, voffA);
;             PG8_WAIT_V(8); PG8_WAIT_L(0); PG8_BAR; PG8_MMA(1, 0, At, B0); PG8_MMA(1, 1, At, B1); PG8_BAR; PG8_SCHED;
	v_mfma_f32_16x16x32_bf16 v[126:129], v[160:163], v[196:199], v[126:129]
	v_mfma_f32_16x16x32_bf16 v[122:125], v[170:173], v[196:199], v[122:125]
	v_mfma_f32_16x16x32_bf16 v[118:121], v[160:163], v[204:207], v[118:121]
	v_mfma_f32_16x16x32_bf16 v[110:113], v[170:173], v[204:207], v[110:113]
	v_mfma_f32_16x16x32_bf16 v[102:105], v[160:163], v[212:215], v[102:105]
	v_mfma_f32_16x16x32_bf16 v[94:97], v[170:173], v[212:215], v[94:97]
	v_mfma_f32_16x16x32_bf16 v[86:89], v[160:163], v[220:223], v[86:89]
	v_mfma_f32_16x16x32_bf16 v[78:81], v[170:173], v[220:223], v[78:81]
	v_mfma_f32_16x16x32_bf16 v[126:129], v[166:169], v[200:203], v[126:129]
	v_mfma_f32_16x16x32_bf16 v[122:125], v[174:177], v[200:203], v[122:125]
	v_mfma_f32_16x16x32_bf16 v[118:121], v[166:169], v[208:211], v[118:121]
	v_mfma_f32_16x16x32_bf16 v[110:113], v[174:177], v[208:211], v[110:113]
	v_mfma_f32_16x16x32_bf16 v[102:105], v[166:169], v[216:219], v[102:105]
	v_mfma_f32_16x16x32_bf16 v[94:97], v[174:177], v[216:219], v[94:97]
	v_mfma_f32_16x16x32_bf16 v[86:89], v[166:169], v[224:227], v[86:89]
	v_mfma_f32_16x16x32_bf16 v[78:81], v[174:177], v[224:227], v[78:81]
	v_mfma_f32_16x16x32_bf16 v[114:117], v[178:181], v[196:199], v[114:117]
	v_mfma_f32_16x16x32_bf16 v[106:109], v[188:191], v[196:199], v[106:109]
	v_mfma_f32_16x16x32_bf16 v[98:101], v[178:181], v[204:207], v[98:101]
	v_mfma_f32_16x16x32_bf16 v[90:93], v[188:191], v[204:207], v[90:93]
	v_mfma_f32_16x16x32_bf16 v[82:85], v[178:181], v[212:215], v[82:85]
	v_mfma_f32_16x16x32_bf16 v[74:77], v[188:191], v[212:215], v[74:77]
	v_mfma_f32_16x16x32_bf16 v[70:73], v[178:181], v[220:223], v[70:73]
	v_mfma_f32_16x16x32_bf16 v[66:69], v[188:191], v[220:223], v[66:69]
	v_mfma_f32_16x16x32_bf16 v[114:117], v[184:187], v[200:203], v[114:117]
	v_mfma_f32_16x16x32_bf16 v[106:109], v[192:195], v[200:203], v[106:109]
	v_mfma_f32_16x16x32_bf16 v[98:101], v[184:187], v[208:211], v[98:101]
	v_mfma_f32_16x16x32_bf16 v[90:93], v[192:195], v[208:211], v[90:93]
	v_mfma_f32_16x16x32_bf16 v[82:85], v[184:187], v[216:219], v[82:85]
	v_mfma_f32_16x16x32_bf16 v[74:77], v[192:195], v[216:219], v[74:77]
	v_mfma_f32_16x16x32_bf16 v[70:73], v[184:187], v[224:227], v[70:73]
	v_mfma_f32_16x16x32_bf16 v[66:69], v[192:195], v[224:227], v[66:69]
	s_barrier
	s_setprio 0
	s_add_i32 s14, s41, s24
	v_lshl_add_u64 v[228:229], s[18:19], 0, v[132:133]
	s_mov_b32 m0, s14
	ds_read_b128 v[196:199], v165 offset:16384
	ds_read_b128 v[200:203], v165 offset:17408
	ds_read_b128 v[204:207], v165 offset:18432
	ds_read_b128 v[208:211], v165 offset:19456
	ds_read_b128 v[212:215], v165 offset:20480
	ds_read_b128 v[216:219], v165 offset:21504
	ds_read_b128 v[220:223], v165 offset:22528
	ds_read_b128 v[224:227], v165 offset:23552
	global_load_lds_dwordx4 v[228:229], off
	s_add_i32 m0, s14, 0x2000
	s_add_u32 s14, s18, 0xb0000
	v_lshl_add_u64 v[230:231], s[18:19], 0, v[154:155]
	s_addc_u32 s15, s19, 0
	s_add_i32 s41, s42, s24
	global_load_lds_dwordx4 v[230:231], off
	s_mov_b32 m0, s41
	v_lshl_add_u64 v[232:233], s[14:15], 0, v[132:133]
	global_load_lds_dwordx4 v[232:233], off
	s_add_i32 m0, s41, 0x2000
	v_lshl_add_u64 v[232:233], s[14:15], 0, v[154:155]
	global_load_lds_dwordx4 v[232:233], off
	s_mov_b32 m0, s25
	v_lshl_add_u64 v[232:233], s[20:21], 0, v[130:131]
	global_load_lds_dwordx4 v[232:233], off
	s_mov_b32 m0, s26
	v_lshl_add_u64 v[234:235], s[20:21], 0, v[134:135]
	global_load_lds_dwordx4 v[234:235], off
	s_waitcnt vmcnt(8)
	s_waitcnt lgkmcnt(0)
	s_setprio 1
	s_barrier
	v_mfma_f32_16x16x32_bf16 v[62:65], v[160:163], v[196:199], v[62:65]
	v_mfma_f32_16x16x32_bf16 v[58:61], v[170:173], v[196:199], v[58:61]
	v_mfma_f32_16x16x32_bf16 v[54:57], v[160:163], v[204:207], v[54:57]
	v_mfma_f32_16x16x32_bf16 v[46:49], v[170:173], v[204:207], v[46:49]
	v_mfma_f32_16x16x32_bf16 v[38:41], v[160:163], v[212:215], v[38:41]
	v_mfma_f32_16x16x32_bf16 v[30:33], v[170:173], v[212:215], v[30:33]
	v_mfma_f32_16x16x32_bf16 v[22:25], v[160:163], v[220:223], v[22:25]
	v_mfma_f32_16x16x32_bf16 v[14:17], v[170:173], v[220:223], v[14:17]
	v_mfma_f32_16x16x32_bf16 v[62:65], v[166:169], v[200:203], v[62:65]
	v_mfma_f32_16x16x32_bf16 v[58:61], v[174:177], v[200:203], v[58:61]
	v_mfma_f32_16x16x32_bf16 v[54:57], v[166:169], v[208:211], v[54:57]
	v_mfma_f32_16x16x32_bf16 v[46:49], v[174:177], v[208:211], v[46:49]
	v_mfma_f32_16x16x32_bf16 v[38:41], v[166:169], v[216:219], v[38:41]
	v_mfma_f32_16x16x32_bf16 v[30:33], v[174:177], v[216:219], v[30:33]
	v_mfma_f32_16x16x32_bf16 v[22:25], v[166:169], v[224:227], v[22:25]
	v_mfma_f32_16x16x32_bf16 v[14:17], v[174:177], v[224:227], v[14:17]
	v_mfma_f32_16x16x32_bf16 v[50:53], v[178:181], v[196:199], v[50:53]
	v_mfma_f32_16x16x32_bf16 v[42:45], v[188:191], v[196:199], v[42:45]
	v_mfma_f32_16x16x32_bf16 v[34:37], v[178:181], v[204:207], v[34:37]
	v_mfma_f32_16x16x32_bf16 v[26:29], v[188:191], v[204:207], v[26:29]
	v_mfma_f32_16x16x32_bf16 v[18:21], v[178:181], v[212:215], v[18:21]
	v_mfma_f32_16x16x32_bf16 v[10:13], v[188:191], v[212:215], v[10:13]
	v_mfma_f32_16x16x32_bf16 v[6:9], v[178:181], v[220:223], v[6:9]
	v_mfma_f32_16x16x32_bf16 v[2:5], v[188:191], v[220:223], v[2:5]
	v_mfma_f32_16x16x32_bf16 v[50:53], v[184:187], v[200:203], v[50:53]
	v_mfma_f32_16x16x32_bf16 v[42:45], v[192:195], v[200:203], v[42:45]
	v_mfma_f32_16x16x32_bf16 v[34:37], v[184:187], v[208:211], v[34:37]
	v_mfma_f32_16x16x32_bf16 v[26:29], v[192:195], v[208:211], v[26:29]
	v_mfma_f32_16x16x32_bf16 v[18:21], v[184:187], v[216:219], v[18:21]
	v_mfma_f32_16x16x32_bf16 v[10:13], v[192:195], v[216:219], v[10:13]
	v_mfma_f32_16x16x32_bf16 v[6:9], v[184:187], v[224:227], v[6:9]
	v_mfma_f32_16x16x32_bf16 v[2:5], v[192:195], v[224:227], v[2:5]
	s_barrier
; #define PG8_STAGE(bufoff, gbase, voff) do { _Pragma("unroll") for (int _i = 0; _i < 2; ++_i) \
;         __builtin_amdgcn_global_load_lds((const unsigned*)((const char*)(gbase) + (voff)[_i]), (LAS unsigned*)(lds + (bufoff) + ldsw + _i * 8192), 16, 0, 0); } while (0)
; #define PG8_LDA(dst, b, h) do { _Pragma("unroll") for (int m = 0; m < 4; ++m) _Pragma("unroll") for (int k = 0; k < 2; ++k) dst[m][k] = *(const LAS bf16x8*)(lds + PG8_SA(b, h) + aoff + m * 2048 + k * 1024); } while (0)
; #define PG8_LDB(dst, b, h) do { _Pragma("unroll") for (int n = 0; n < 2; ++n) _Pragma("unroll") for (int k = 0; k < 2; ++k) dst[n][k] = *(const LAS bf16x8*)(lds + PG8_SB(b, h) + boff + n * 2048 + k * 1024); } while (0)
; #define PG8_MMA(ai, bj, At, Bt) do { __builtin_amdgcn_s_setprio(1); _Pragma("unroll") for (int m = 0; m < 4; ++m) _Pragma("unroll") for (int n = 0; n < 2; ++n) _Pragma("unroll") for (int k = 0; k < 2; ++k) \
;         acc[ai][bj][m][n] = __builtin_amdgcn_mfma_f32_16x16x32_bf16(Bt[n][k], At[m][k], acc[ai][bj][m][n], 0, 0, 0); __builtin_amdgcn_s_setprio(0); } while (0)
; #define PG8_WAIT_V(n) asm volatile("s_waitcnt vmcnt(" #n ")" ::: "memory")
; #define PG8_WAIT_L(n) asm volatile("s_waitcnt lgkmcnt(" #n ")" ::: "memory")
; #define PG8_BAR __builtin_amdgcn_s_barrier()
; #define PG8_SCHED __builtin_amdgcn_sched_barrier(0)
; template <class Epi, bool ALIGN_EPI = PG8_ALIGN, bool SP2 = PG8_SP2>
; __device__ __forceinline__ void gemm_phase(LAS uchar* lds, const Gemm g, const StaticOrder& S, const Epi& E) {
;     ...
;             PG8_WAIT_V(8); PG8_WAIT_L(0); PG8_BAR; PG8_MMA(1, 0, At, B0); PG8_MMA(1, 1, At, B1); PG8_BAR; PG8_SCHED;
;             PG8_LDB(B0, 1, 0); PG8_LDB(B1, 1, 1); PG8_SCHED; PG8_LDA(At, 1, 0); PG8_STAGE(PG8_SA(0, 1), a2 + hstepA, voffA);
;             PG8_WAIT_V(8); PG8_WAIT_L(0); PG8_BAR; PG8_MMA(0, 0, At, B0); PG8_MMA(0, 1, At, B1); PG8_BAR; PG8_SCHED;
	s_setprio 0
	s_add_i32 s41, 0, 0x18000
	v_add_u32_e32 v144, s41, v139
	s_add_i32 s42, 0, 0x1c000
	ds_read_b128 v[160:163], v144
	ds_read_b128 v[166:169], v144 offset:1024
	ds_read_b128 v[170:173], v144 offset:2048
	ds_read_b128 v[174:177], v144 offset:3072
	v_add_u32_e32 v144, s42, v139
	ds_read_b128 v[178:181], v144
	ds_read_b128 v[184:187], v144 offset:1024
	ds_read_b128 v[188:191], v144 offset:2048
	ds_read_b128 v[192:195], v144 offset:3072
	s_add_u32 s14, s20, 0xb0000
	s_addc_u32 s15, s21, 0
	s_mov_b32 m0, s27
	v_lshl_add_u64 v[236:237], s[14:15], 0, v[130:131]
	ds_read_b128 v[196:199], v165 offset:32768
	ds_read_b128 v[200:203], v165 offset:33792
	ds_read_b128 v[204:207], v165 offset:34816
	ds_read_b128 v[208:211], v165 offset:35840
	ds_read_b128 v[212:215], v165 offset:36864
	ds_read_b128 v[216:219], v165 offset:37888
	ds_read_b128 v[220:223], v165 offset:38912
	ds_read_b128 v[224:227], v165 offset:39936
	global_load_lds_dwordx4 v[236:237], off
	s_mov_b32 m0, s28
	v_lshl_add_u64 v[236:237], s[14:15], 0, v[134:135]
	global_load_lds_dwordx4 v[236:237], off
	s_waitcnt vmcnt(8)
	s_waitcnt lgkmcnt(0)
	s_setprio 1
	s_barrier
	v_mfma_f32_16x16x32_bf16 v[126:129], v[160:163], v[196:199], v[126:129]
	v_mfma_f32_16x16x32_bf16 v[122:125], v[170:173], v[196:199], v[122:125]
	v_mfma_f32_16x16x32_bf16 v[118:121], v[160:163], v[204:207], v[118:121]
	v_mfma_f32_16x16x32_bf16 v[110:113], v[170:173], v[204:207], v[110:113]
	v_mfma_f32_16x16x32_bf16 v[102:105], v[160:163], v[212:215], v[102:105]
	v_mfma_f32_16x16x32_bf16 v[94:97], v[170:173], v[212:215], v[94:97]
	v_mfma_f32_16x16x32_bf16 v[86:89], v[160:163], v[220:223], v[86:89]
	v_mfma_f32_16x16x32_bf16 v[78:81], v[170:173], v[220:223], v[78:81]
	v_mfma_f32_16x16x32_bf16 v[126:129], v[166:169], v[200:203], v[126:129]
	v_mfma_f32_16x16x32_bf16 v[122:125], v[174:177], v[200:203], v[122:125]
	v_mfma_f32_16x16x32_bf16 v[118:121], v[166:169], v[208:211], v[118:121]
	v_mfma_f32_16x16x32_bf16 v[110:113], v[174:177], v[208:211], v[110:113]
	v_mfma_f32_16x16x32_bf16 v[102:105], v[166:169], v[216:219], v[102:105]
	v_mfma_f32_16x16x32_bf16 v[94:97], v[174:177], v[216:219], v[94:97]
	v_mfma_f32_16x16x32_bf16 v[86:89], v[166:169], v[224:227], v[86:89]
	v_mfma_f32_16x16x32_bf16 v[78:81], v[174:177], v[224:227], v[78:81]
	v_mfma_f32_16x16x32_bf16 v[114:117], v[178:181], v[196:199], v[114:117]
	v_mfma_f32_16x16x32_bf16 v[106:109], v[188:191], v[196:199], v[106:109]
	v_mfma_f32_16x16x32_bf16 v[98:101], v[178:181], v[204:207], v[98:101]
	v_mfma_f32_16x16x32_bf16 v[90:93], v[188:191], v[204:207], v[90:93]
	v_mfma_f32_16x16x32_bf16 v[82:85], v[178:181], v[212:215], v[82:85]
	v_mfma_f32_16x16x32_bf16 v[74:77], v[188:191], v[212:215], v[74:77]
	v_mfma_f32_16x16x32_bf16 v[70:73], v[178:181], v[220:223], v[70:73]
	v_mfma_f32_16x16x32_bf16 v[66:69], v[188:191], v[220:223], v[66:69]
	v_mfma_f32_16x16x32_bf16 v[114:117], v[184:187], v[200:203], v[114:117]
	v_mfma_f32_16x16x32_bf16 v[106:109], v[192:195], v[200:203], v[106:109]
	v_mfma_f32_16x16x32_bf16 v[98:101], v[184:187], v[208:211], v[98:101]
	v_mfma_f32_16x16x32_bf16 v[90:93], v[192:195], v[208:211], v[90:93]
	v_mfma_f32_16x16x32_bf16 v[82:85], v[184:187], v[216:219], v[82:85]
	v_mfma_f32_16x16x32_bf16 v[74:77], v[192:195], v[216:219], v[74:77]
	v_mfma_f32_16x16x32_bf16 v[70:73], v[184:187], v[224:227], v[70:73]
	v_mfma_f32_16x16x32_bf16 v[66:69], v[192:195], v[224:227], v[66:69]
	s_barrier
; #define PG8_STAGE(bufoff, gbase, voff) do { _Pragma("unroll") for (int _i = 0; _i < 2; ++_i) \
;         __builtin_amdgcn_global_load_lds((const unsigned*)((const char*)(gbase) + (voff)[_i]), (LAS unsigned*)(lds + (bufoff) + ldsw + _i * 8192), 16, 0, 0); } while (0)
; #define PG8_LDA(dst, b, h) do { _Pragma("unroll") for (int m = 0; m < 4; ++m) _Pragma("unroll") for (int k = 0; k < 2; ++k) dst[m][k] = *(const LAS bf16x8*)(lds + PG8_SA(b, h) + aoff + m * 2048 + k * 1024); } while (0)
; #define PG8_MMA(ai, bj, At, Bt) do { __builtin_amdgcn_s_setprio(1); _Pragma("unroll") for (int m = 0; m < 4; ++m) _Pragma("unroll") for (int n = 0; n < 2; ++n) _Pragma("unroll") for (int k = 0; k < 2; ++k) \
;         acc[ai][bj][m][n] = __builtin_amdgcn_mfma_f32_16x16x32_bf16(Bt[n][k], At[m][k], acc[ai][bj][m][n], 0, 0, 0); __builtin_amdgcn_s_setprio(0); } while (0)
; #define PG8_WAIT_V(n) asm volatile("s_waitcnt vmcnt(" #n ")" ::: "memory")
; #define PG8_WAIT_L(n) asm volatile("s_waitcnt lgkmcnt(" #n ")" ::: "memory")
; #define PG8_BAR __builtin_amdgcn_s_barrier()
; #define PG8_SCHED __builtin_amdgcn_sched_barrier(0)
; template <class Epi, bool ALIGN_EPI = PG8_ALIGN, bool SP2 = PG8_SP2>
; __device__ __forceinline__ void gemm_phase(LAS uchar* lds, const Gemm g, const StaticOrder& S, const Epi& E) {
;     ...
;             PG8_LDA(At, 1, 1); PG8_STAGE(PG8_SB(1, 0), b3, voffB); PG8_STAGE(PG8_SB(1, 1), b3 + hstepB, voffB); PG8_STAGE(PG8_SA(1, 0), a3, voffA);
;             PG8_WAIT_V(8); PG8_WAIT_L(0); PG8_BAR; PG8_MMA(1, 0, At, B0); PG8_MMA(1, 1, At, B1); PG8_BAR; PG8_SCHED;
;     ...
;         if constexpr (ALIGN_EPI) { if (wr == 0) PG8_BAR; }
	s_setprio 0
	s_add_i32 s14, s41, s24
	v_lshl_add_u64 v[228:229], v[228:229], 0, s[84:85]
	s_mov_b32 m0, s14
	ds_read_b128 v[196:199], v165 offset:49152
	ds_read_b128 v[200:203], v165 offset:50176
	ds_read_b128 v[204:207], v165 offset:51200
	ds_read_b128 v[208:211], v165 offset:52224
	ds_read_b128 v[212:215], v165 offset:53248
	ds_read_b128 v[216:219], v165 offset:54272
	ds_read_b128 v[220:223], v165 offset:55296
	ds_read_b128 v[224:227], v165 offset:56320
	global_load_lds_dwordx4 v[228:229], off
	s_add_i32 m0, s14, 0x2000
	s_add_u32 s14, s18, 0xb0080
	v_lshl_add_u64 v[228:229], v[230:231], 0, s[84:85]
	s_addc_u32 s15, s19, 0
	s_add_i32 s18, s42, s24
	global_load_lds_dwordx4 v[228:229], off
	s_mov_b32 m0, s18
	v_lshl_add_u64 v[228:229], s[14:15], 0, v[132:133]
	global_load_lds_dwordx4 v[228:229], off
	s_add_i32 m0, s18, 0x2000
	v_lshl_add_u64 v[228:229], s[14:15], 0, v[154:155]
	global_load_lds_dwordx4 v[228:229], off
	s_mov_b32 m0, s29
	v_lshl_add_u64 v[228:229], v[232:233], 0, s[84:85]
	global_load_lds_dwordx4 v[228:229], off
	s_mov_b32 m0, s30
	v_lshl_add_u64 v[228:229], v[234:235], 0, s[84:85]
	global_load_lds_dwordx4 v[228:229], off
	s_waitcnt vmcnt(8)
	s_waitcnt lgkmcnt(0)
	s_setprio 1
	s_barrier
	v_mfma_f32_16x16x32_bf16 v[62:65], v[160:163], v[196:199], v[62:65]
	v_mfma_f32_16x16x32_bf16 v[58:61], v[170:173], v[196:199], v[58:61]
	v_mfma_f32_16x16x32_bf16 v[54:57], v[160:163], v[204:207], v[54:57]
	v_mfma_f32_16x16x32_bf16 v[46:49], v[170:173], v[204:207], v[46:49]
	v_mfma_f32_16x16x32_bf16 v[38:41], v[160:163], v[212:215], v[38:41]
	v_mfma_f32_16x16x32_bf16 v[30:33], v[170:173], v[212:215], v[30:33]
	v_mfma_f32_16x16x32_bf16 v[22:25], v[160:163], v[220:223], v[22:25]
	v_mfma_f32_16x16x32_bf16 v[14:17], v[170:173], v[220:223], v[14:17]
	v_mfma_f32_16x16x32_bf16 v[62:65], v[166:169], v[200:203], v[62:65]
	v_mfma_f32_16x16x32_bf16 v[58:61], v[174:177], v[200:203], v[58:61]
	v_mfma_f32_16x16x32_bf16 v[54:57], v[166:169], v[208:211], v[54:57]
	v_mfma_f32_16x16x32_bf16 v[46:49], v[174:177], v[208:211], v[46:49]
	v_mfma_f32_16x16x32_bf16 v[38:41], v[166:169], v[216:219], v[38:41]
	v_mfma_f32_16x16x32_bf16 v[30:33], v[174:177], v[216:219], v[30:33]
	v_mfma_f32_16x16x32_bf16 v[22:25], v[166:169], v[224:227], v[22:25]
	v_mfma_f32_16x16x32_bf16 v[14:17], v[174:177], v[224:227], v[14:17]
	v_mfma_f32_16x16x32_bf16 v[50:53], v[178:181], v[196:199], v[50:53]
	v_mfma_f32_16x16x32_bf16 v[42:45], v[188:191], v[196:199], v[42:45]
	v_mfma_f32_16x16x32_bf16 v[34:37], v[178:181], v[204:207], v[34:37]
	v_mfma_f32_16x16x32_bf16 v[26:29], v[188:191], v[204:207], v[26:29]
	v_mfma_f32_16x16x32_bf16 v[18:21], v[178:181], v[212:215], v[18:21]
	v_mfma_f32_16x16x32_bf16 v[10:13], v[188:191], v[212:215], v[10:13]
	v_mfma_f32_16x16x32_bf16 v[6:9], v[178:181], v[220:223], v[6:9]
	v_mfma_f32_16x16x32_bf16 v[2:5], v[188:191], v[220:223], v[2:5]
	v_mfma_f32_16x16x32_bf16 v[50:53], v[184:187], v[200:203], v[50:53]
	v_mfma_f32_16x16x32_bf16 v[42:45], v[192:195], v[200:203], v[42:45]
	v_mfma_f32_16x16x32_bf16 v[34:37], v[184:187], v[208:211], v[34:37]
	v_mfma_f32_16x16x32_bf16 v[26:29], v[192:195], v[208:211], v[26:29]
	v_mfma_f32_16x16x32_bf16 v[18:21], v[184:187], v[216:219], v[18:21]
	v_mfma_f32_16x16x32_bf16 v[10:13], v[192:195], v[216:219], v[10:13]
	v_mfma_f32_16x16x32_bf16 v[6:9], v[184:187], v[224:227], v[6:9]
	v_mfma_f32_16x16x32_bf16 v[2:5], v[192:195], v[224:227], v[2:5]
	s_barrier
	s_setprio 0
	s_add_i32 s40, s40, 2
	s_add_u32 s38, s38, 0x100
	s_addc_u32 s39, s39, 0
	s_cmp_gt_u32 s40, 41
	s_mov_b64 s[14:15], s[16:17]
	s_cbranch_scc0 .LBB0_1143
	s_and_b64 vcc, exec, s[10:11]
	s_cbranch_vccz .LBB0_1146
	s_barrier
